# v38 + nt (streaming) hint on the P1 x-row loads and the P4 combine/pooling loads
# speedup vs baseline: 1.0070x; 1.0024x over previous
.LBB0_108:
	s_add_i32 s4, s15, 0xfffff000
	s_lshr_b32 s4, s4, 11
	s_add_i32 s12, s4, 1
	s_cmpk_lt_i32 s15, 0x1000
	s_cselect_b64 s[4:5], -1, 0
	s_and_b64 s[6:7], s[4:5], exec
	s_cselect_b32 s12, 0, s12
	s_and_saveexec_b64 s[6:7], s[2:3]
	s_cbranch_execz .LBB0_110
	s_mul_i32 s16, s12, 0xc000
	s_mul_hi_u32 s13, s12, 0xc000
	s_add_u32 s16, s8, s16
	s_addc_u32 s17, s9, s13
	v_lshl_add_u64 v[2:3], s[16:17], 0, v[68:69]
	v_add_co_u32_e32 v2, vcc, 0x2000, v2
	s_nop 1
	v_addc_co_u32_e32 v3, vcc, 0, v3, vcc
	global_load_dwordx4 v[2:5], v[2:3], off nt
	s_nop 0
	global_load_dwordx4 v[6:9], v[70:71], off nt
	global_load_dwordx4 v[10:13], v68, s[16:17]
	s_waitcnt vmcnt(0)
	v_pk_add_f32 v[4:5], v[4:5], 1.0 op_sel_hi:[1,0]
	v_pk_add_f32 v[2:3], v[2:3], 1.0 op_sel_hi:[1,0]
	v_pk_mul_f32 v[4:5], v[8:9], v[4:5]
	v_pk_mul_f32 v[2:3], v[6:7], v[2:3]
	ds_write_b128 v77, v[2:5]
	ds_write_b128 v77, v[10:13] offset:8192

.LBB0_112:
	s_add_i32 s12, s4, 0xfffff000
	s_cmpk_lt_i32 s4, 0x1000
	s_cselect_b32 s13, s5, 0
	s_cselect_b32 s12, s4, s12
	s_cselect_b32 s15, s53, s55
	s_cselect_b32 s16, s52, s54
	s_lshl_b64 s[12:13], s[12:13], 13
	s_add_u32 s12, s16, s12
	s_addc_u32 s13, s15, s13
	v_lshl_add_u64 v[110:111], v[66:67], 4, s[12:13]
	global_load_dwordx4 v[94:97], v[110:111], off nt
	global_load_dwordx4 v[98:101], v[110:111], off offset:1024 nt
	global_load_dwordx4 v[102:105], v[110:111], off offset:2048 nt
	global_load_dwordx4 v[106:109], v[110:111], off offset:3072 nt
	v_add_co_u32_e32 v122, vcc, s10, v110
	s_add_u32 s4, s4, 8
	s_nop 0
	v_addc_co_u32_e32 v123, vcc, 0, v111, vcc
	global_load_dwordx4 v[110:113], v[122:123], off nt
	global_load_dwordx4 v[114:117], v[122:123], off offset:1024 nt
	global_load_dwordx4 v[118:121], v[122:123], off offset:3072 nt
	s_nop 0
	global_load_dwordx4 v[122:125], v[122:123], off offset:2048 nt
	s_addc_u32 s5, s5, 0
	s_cmp_ge_i32 s4, s7
	s_waitcnt vmcnt(7)
	v_mov_b32_e32 v128, v95
	s_waitcnt vmcnt(6)
	v_mov_b32_e32 v129, v99
	v_mov_b32_e32 v132, v97
	v_mov_b32_e32 v133, v101
	v_mov_b32_e32 v126, v94
	v_mov_b32_e32 v127, v98
	v_mov_b32_e32 v130, v96
	v_mov_b32_e32 v131, v100
	s_waitcnt vmcnt(5)
	v_pk_mul_f32 v[134:135], v[104:105], v[104:105]
	v_pk_mul_f32 v[136:137], v[102:103], v[102:103]
	v_pk_mul_f32 v[128:129], v[128:129], v[128:129]
	v_pk_mul_f32 v[132:133], v[132:133], v[132:133]
	v_pk_mov_b32 v[142:143], v[136:137], v[134:135] op_sel:[1,0]
	v_mov_b32_e32 v137, v135
	v_pk_fma_f32 v[126:127], v[126:127], v[126:127], v[128:129]
	v_pk_fma_f32 v[128:129], v[130:131], v[130:131], v[132:133]
	s_waitcnt vmcnt(4)
	v_mul_f32_e32 v138, v107, v107
	v_mul_f32_e32 v140, v109, v109
	v_pk_add_f32 v[130:131], v[142:143], v[136:137]
	v_pk_add_f32 v[126:127], v[126:127], v[128:129]
	s_waitcnt vmcnt(3)
	v_mul_f32_e32 v93, v110, v110
	v_mul_f32_e32 v147, v111, v111
	v_mul_f32_e32 v149, v112, v112
	v_mul_f32_e32 v150, v113, v113
	v_pk_fma_f32 v[134:135], v[106:107], v[106:107], v[138:139] op_sel_hi:[1,1,0]
	v_pk_fma_f32 v[138:139], v[108:109], v[108:109], v[140:141] op_sel_hi:[1,1,0]
	v_pk_add_f32 v[128:129], v[130:131], v[130:131] op_sel:[0,1] op_sel_hi:[1,0]
	v_pk_add_f32 v[126:127], v[126:127], v[126:127] op_sel:[0,1] op_sel_hi:[1,0]
	s_waitcnt vmcnt(2)
	v_pk_mul_f32 v[140:141], v[116:117], v[116:117]
	v_pk_mul_f32 v[144:145], v[114:115], v[114:115]
	v_mov_b32_e32 v135, v149
	v_mov_b32_e32 v139, v150
	v_mov_b32_e32 v129, v147
	v_mov_b32_e32 v127, v93
	v_pk_mov_b32 v[132:133], v[144:145], v[140:141] op_sel:[1,0]
	v_mov_b32_e32 v145, v141
	v_pk_add_f32 v[130:131], v[134:135], v[138:139]
	v_pk_add_f32 v[126:127], v[126:127], v[128:129]
	s_waitcnt vmcnt(0)
	v_mul_f32_e32 v146, v123, v123
	v_mul_f32_e32 v148, v125, v125
	v_pk_add_f32 v[132:133], v[132:133], v[144:145]
	v_pk_add_f32 v[126:127], v[126:127], v[130:131]
	v_mul_f32_e32 v151, v118, v118
	v_mul_f32_e32 v152, v119, v119
	v_mul_f32_e32 v153, v120, v120
	v_mul_f32_e32 v154, v121, v121
	v_pk_fma_f32 v[136:137], v[122:123], v[122:123], v[146:147] op_sel_hi:[1,1,0]
	v_pk_fma_f32 v[140:141], v[124:125], v[124:125], v[148:149] op_sel_hi:[1,1,0]
	v_pk_add_f32 v[132:133], v[132:133], v[132:133] op_sel:[0,1] op_sel_hi:[1,0]
	v_pk_add_f32 v[126:127], v[126:127], v[126:127] op_sel:[0,1] op_sel_hi:[1,0]
	v_mov_b32_e32 v137, v153
	v_mov_b32_e32 v141, v154
	v_mov_b32_e32 v133, v152
	v_mov_b32_e32 v127, v151
	v_pk_add_f32 v[134:135], v[136:137], v[140:141]
	v_pk_add_f32 v[126:127], v[126:127], v[132:133]
	s_nop 0
	v_pk_add_f32 v[126:127], v[126:127], v[134:135]
	s_nop 0
	v_add_f32_e32 v93, v126, v127
	ds_bpermute_b32 v126, v87, v93
	s_waitcnt lgkmcnt(0)
	v_add_f32_e32 v93, v93, v126
	ds_bpermute_b32 v126, v88, v93
	s_waitcnt lgkmcnt(0)
	v_add_f32_e32 v93, v93, v126
	ds_bpermute_b32 v126, v89, v93
	s_waitcnt lgkmcnt(0)
	v_add_f32_e32 v93, v93, v126
	ds_bpermute_b32 v126, v90, v93
	s_waitcnt lgkmcnt(0)
	v_add_f32_e32 v93, v93, v126
	ds_bpermute_b32 v126, v91, v93
	s_waitcnt lgkmcnt(0)
	v_add_f32_e32 v93, v93, v126
	ds_bpermute_b32 v126, v92, v93
	s_waitcnt lgkmcnt(0)
	v_add_f32_e32 v93, v93, v126
	v_fmamk_f32 v93, v93, 0x3a000000, v86
	v_mul_f32_e32 v126, 0x4b800000, v93
	v_cmp_gt_f32_e32 vcc, s11, v93
	s_nop 1
	v_cndmask_b32_e32 v93, v93, v126, vcc
	v_rsq_f32_e32 v93, v93
	s_nop 0
	v_mul_f32_e32 v126, 0x45800000, v93
	v_cndmask_b32_e32 v126, v93, v126, vcc
	v_pk_mul_f32 v[94:95], v[94:95], v[126:127] op_sel_hi:[1,0]
	v_pk_mul_f32 v[96:97], v[96:97], v[126:127] op_sel_hi:[1,0]
	v_pk_mul_f32 v[98:99], v[98:99], v[126:127] op_sel_hi:[1,0]
	v_pk_mul_f32 v[100:101], v[100:101], v[126:127] op_sel_hi:[1,0]
	v_pk_mul_f32 v[102:103], v[102:103], v[126:127] op_sel_hi:[1,0]
	v_pk_mul_f32 v[104:105], v[104:105], v[126:127] op_sel_hi:[1,0]
	v_pk_mul_f32 v[106:107], v[106:107], v[126:127] op_sel_hi:[1,0]
	v_pk_mul_f32 v[108:109], v[108:109], v[126:127] op_sel_hi:[1,0]
	v_pk_mul_f32 v[110:111], v[110:111], v[126:127] op_sel_hi:[1,0]
	v_pk_mul_f32 v[112:113], v[112:113], v[126:127] op_sel_hi:[1,0]
	v_pk_mul_f32 v[114:115], v[114:115], v[126:127] op_sel_hi:[1,0]
	v_pk_mul_f32 v[116:117], v[116:117], v[126:127] op_sel_hi:[1,0]
	v_pk_mul_f32 v[122:123], v[122:123], v[126:127] op_sel_hi:[1,0]
	v_pk_mul_f32 v[124:125], v[124:125], v[126:127] op_sel_hi:[1,0]
	v_pk_mul_f32 v[118:119], v[118:119], v[126:127] op_sel_hi:[1,0]
	v_pk_mul_f32 v[120:121], v[120:121], v[126:127] op_sel_hi:[1,0]
	v_pk_fma_f32 v[96:97], v[4:5], v[96:97], v[12:13]
	v_pk_fma_f32 v[94:95], v[2:3], v[94:95], v[10:11]
	v_pk_fma_f32 v[100:101], v[8:9], v[100:101], v[16:17]
	v_pk_fma_f32 v[98:99], v[6:7], v[98:99], v[14:15]
	v_pk_fma_f32 v[104:105], v[20:21], v[104:105], v[28:29]
	v_pk_fma_f32 v[102:103], v[18:19], v[102:103], v[26:27]
	v_pk_fma_f32 v[108:109], v[24:25], v[108:109], v[32:33]
	v_pk_fma_f32 v[106:107], v[22:23], v[106:107], v[30:31]
	v_pk_fma_f32 v[112:113], v[36:37], v[112:113], v[44:45]
	v_pk_fma_f32 v[110:111], v[34:35], v[110:111], v[42:43]
	v_pk_fma_f32 v[116:117], v[40:41], v[116:117], v[48:49]
	v_pk_fma_f32 v[114:115], v[38:39], v[114:115], v[46:47]
	v_pk_fma_f32 v[124:125], v[52:53], v[124:125], v[60:61]
	v_pk_fma_f32 v[122:123], v[50:51], v[122:123], v[58:59]
	v_pk_fma_f32 v[120:121], v[56:57], v[120:121], v[64:65]
	v_pk_fma_f32 v[118:119], v[54:55], v[118:119], v[62:63]
	v_cvt_pk_bf16_f32 v94, v94, v95
	v_cvt_pk_bf16_f32 v95, v96, v97
	v_cvt_pk_bf16_f32 v96, v98, v99
	v_cvt_pk_bf16_f32 v97, v100, v101
	v_cvt_pk_bf16_f32 v98, v102, v103
	v_cvt_pk_bf16_f32 v99, v104, v105
	v_cvt_pk_bf16_f32 v100, v106, v107
	v_cvt_pk_bf16_f32 v101, v108, v109
	v_cvt_pk_bf16_f32 v102, v110, v111
	v_cvt_pk_bf16_f32 v103, v112, v113
	v_cvt_pk_bf16_f32 v104, v114, v115
	v_cvt_pk_bf16_f32 v105, v116, v117
	v_cvt_pk_bf16_f32 v106, v122, v123
	v_cvt_pk_bf16_f32 v107, v124, v125
	v_cvt_pk_bf16_f32 v108, v118, v119
	v_cvt_pk_bf16_f32 v109, v120, v121
	global_store_dwordx2 v[74:75], v[94:95], off
	global_store_dwordx2 v[74:75], v[96:97], off offset:512
	global_store_dwordx2 v[74:75], v[98:99], off offset:1024
	global_store_dwordx2 v[74:75], v[100:101], off offset:1536
	global_store_dwordx2 v[74:75], v[102:103], off offset:2048
	global_store_dwordx2 v[74:75], v[104:105], off offset:2560
	global_store_dwordx2 v[74:75], v[106:107], off offset:3072
	global_store_dwordx2 v[74:75], v[108:109], off offset:3584
	v_lshl_add_u64 v[74:75], v[74:75], 0, s[0:1]
	s_cbranch_scc0 .LBB0_112
	s_branch .LBB0_107

.LBB0_484:
	s_cmp_lt_i32 s76, 5
	s_cselect_b64 s[0:1], -1, 0
	s_cmp_gt_i32 s77, 4
	s_cselect_b64 s[2:3], -1, 0
	s_and_b64 s[0:1], s[0:1], s[2:3]
	s_andn2_b64 vcc, exec, s[0:1]
	s_cbranch_vccnz .LBB0_564
	s_abs_i32 s0, s33
	v_cvt_f32_u32_e32 v1, s0
	s_sub_i32 s3, 0, s0
	s_add_i32 s1, s33, 0x4fff
	s_xor_b32 s2, s1, s33
	v_rcp_iflag_f32_e32 v1, v1
	s_abs_i32 s1, s1
	s_ashr_i32 s2, s2, 31
	v_mul_f32_e32 v1, 0x4f7ffffe, v1
	v_cvt_u32_f32_e32 v1, v1
	s_nop 0
	v_readfirstlane_b32 s4, v1
	s_mul_i32 s3, s3, s4
	s_mul_hi_u32 s3, s4, s3
	s_add_i32 s4, s4, s3
	s_mul_hi_u32 s3, s1, s4
	s_mul_i32 s4, s3, s0
	s_sub_i32 s1, s1, s4
	s_add_i32 s5, s3, 1
	s_sub_i32 s4, s1, s0
	s_cmp_ge_u32 s1, s0
	s_cselect_b32 s3, s5, s3
	s_cselect_b32 s1, s4, s1
	s_add_i32 s4, s3, 1
	s_cmp_ge_u32 s1, s0
	s_cselect_b32 s0, s4, s3
	s_xor_b32 s0, s0, s2
	s_sub_i32 s0, s0, s2
	s_mul_i32 s1, s0, s30
	s_min_i32 s1, s1, 0x5000
	s_add_i32 s0, s1, s0
	s_min_i32 s10, s0, 0x5000
	s_add_i32 s2, s1, s91
	s_cmp_ge_i32 s2, s10
	v_mbcnt_lo_u32_b32 v1, -1, 0
	v_mbcnt_hi_u32_b32 v1, -1, v1
	s_cbranch_scc1 .LBB0_490
	v_readlane_b32 s12, v254, 0
	v_readlane_b32 s14, v254, 2
	v_readlane_b32 s15, v254, 3
	s_mov_b64 s[6:7], s[14:15]
	s_waitcnt vmcnt(0)
	v_lshlrev_b32_e32 v18, 4, v1
	v_mov_b32_e32 v2, s6
	v_mov_b32_e32 v3, s7
	v_ashrrev_i32_e32 v19, 31, v18
	v_lshl_add_u64 v[20:21], v[18:19], 2, v[2:3]
	global_load_dwordx4 v[2:5], v[20:21], off nt
	global_load_dwordx4 v[6:9], v[20:21], off offset:16 nt
	global_load_dwordx4 v[10:13], v[20:21], off offset:32 nt
	global_load_dwordx4 v[14:17], v[20:21], off offset:48 nt
	v_mbcnt_lo_u32_b32 v20, -1, 0
	v_mbcnt_hi_u32_b32 v20, -1, v20
	v_readlane_b32 s16, v254, 4
	s_add_u32 s11, s74, 0x18400000
	v_and_b32_e32 v22, 64, v20
	v_readlane_b32 s17, v254, 5
	s_addc_u32 s16, s75, 0
	s_ashr_i32 s3, s2, 31
	v_xor_b32_e32 v21, 1, v20
	v_add_u32_e32 v22, 64, v22
	s_add_i32 s17, s10, -1
	v_xor_b32_e32 v23, 2, v20
	s_lshl_b64 s[8:9], s[2:3], 11
	v_cmp_lt_i32_e32 vcc, v21, v22
	v_readlane_b32 s18, v254, 6
	v_xor_b32_e32 v24, 4, v20
	s_add_u32 s8, s74, s8
	v_cndmask_b32_e32 v21, v20, v21, vcc
	v_cmp_lt_i32_e32 vcc, v23, v22
	v_readlane_b32 s19, v254, 7
	s_addc_u32 s9, s75, s9
	v_cndmask_b32_e32 v23, v20, v23, vcc
	v_cmp_lt_i32_e32 vcc, v24, v22
	s_add_i32 s18, s2, 8
	s_ashr_i32 s19, s18, 31
	v_cndmask_b32_e32 v20, v20, v24, vcc
	v_lshlrev_b32_e32 v51, 2, v21
	v_lshlrev_b32_e32 v53, 2, v20
	v_lshl_add_u64 v[20:21], s[8:9], 0, v[18:19]
	s_lshl_b64 s[8:9], s[18:19], 11
	s_add_u32 s8, s74, s8
	s_addc_u32 s9, s75, s9
	v_readlane_b32 s13, v254, 1
	s_mov_b64 s[0:1], 0x6c00000
	v_lshlrev_b64 v[36:37], 1, v[18:19]
	v_lshl_add_u64 v[18:19], s[8:9], 0, v[18:19]
	s_mov_b64 s[4:5], 0x2800000
	s_mov_b32 s12, 0x2800000
	s_mov_b64 s[6:7], 0xbc01800
	s_mov_b32 s13, 0xbc01000
	v_mov_b32_e32 v1, 0x358637bd
	s_mov_b32 s14, 0x800000
	s_mov_b32 s15, 0xc3e00000
	v_mov_b32_e32 v50, 0x43e00000
	v_lshlrev_b32_e32 v52, 2, v23
	v_lshl_add_u64 v[38:39], v[20:21], 0, s[0:1]
	v_lshl_add_u64 v[40:41], v[18:19], 0, s[0:1]
	s_mov_b64 s[8:9], 0x8000
	v_readlane_b32 s20, v254, 8
	v_readlane_b32 s21, v254, 9
	v_readlane_b32 s22, v254, 10
	v_readlane_b32 s23, v254, 11
	v_readlane_b32 s24, v254, 12
	v_readlane_b32 s25, v254, 13
	v_readlane_b32 s26, v254, 14
	v_readlane_b32 s27, v254, 15
	s_waitcnt vmcnt(3)
	v_mul_f32_e32 v54, 0x41800000, v2
	v_mul_f32_e32 v55, 0x41800000, v3
	v_mul_f32_e32 v56, 0x41800000, v4
	v_mul_f32_e32 v57, 0x41800000, v5
	s_waitcnt vmcnt(2)
	v_mul_f32_e32 v58, 0x41800000, v6
	v_mul_f32_e32 v59, 0x41800000, v7
	v_mul_f32_e32 v60, 0x41800000, v8
	v_mul_f32_e32 v61, 0x41800000, v9
	s_waitcnt vmcnt(1)
	v_mul_f32_e32 v62, 0x41800000, v10
	v_mul_f32_e32 v63, 0x41800000, v11
	v_mul_f32_e32 v64, 0x41800000, v12
	v_mul_f32_e32 v65, 0x41800000, v13
	s_waitcnt vmcnt(0)
	v_mul_f32_e32 v66, 0x41800000, v14
	v_mul_f32_e32 v67, 0x41800000, v15
	v_mul_f32_e32 v68, 0x41800000, v16
	v_mul_f32_e32 v69, 0x41800000, v17
	s_branch .LBB0_488

.LBB0_488:
	s_min_i32 s0, s2, s17
	s_ashr_i32 s1, s0, 31
	s_lshl_b64 s[18:19], s[0:1], 11
	s_add_u32 s18, s11, s18
	s_addc_u32 s19, s16, s19
	v_lshl_add_u64 v[14:15], s[18:19], 0, v[36:37]
	v_add_co_u32_e32 v10, vcc, s12, v14
	global_load_dwordx4 v[2:5], v[14:15], off nt
	global_load_dwordx4 v[6:9], v[14:15], off offset:16 nt
	v_addc_co_u32_e32 v11, vcc, 0, v15, vcc
	global_load_dwordx4 v[10:13], v[10:11], off nt
	v_lshl_add_u64 v[14:15], v[14:15], 0, s[4:5]
	s_waitcnt lgkmcnt(0)
	global_load_dwordx4 v[14:17], v[14:15], off offset:16 nt
	s_add_i32 s3, s2, 8
	s_mul_hi_i32 s21, s0, 0x2800
	s_mul_i32 s20, s0, 0x2800
	s_min_i32 s0, s3, s17
	s_ashr_i32 s1, s0, 31
	s_mul_hi_i32 s19, s0, 0x2800
	s_mul_i32 s18, s0, 0x2800
	s_lshl_b64 s[0:1], s[0:1], 11
	s_add_u32 s0, s11, s0
	s_addc_u32 s1, s16, s1
	s_add_u32 s18, s74, s18
	s_addc_u32 s19, s75, s19
	s_add_u32 s20, s74, s20
	s_addc_u32 s21, s75, s21
	v_lshl_add_u64 v[22:23], s[20:21], 0, v[36:37]
	v_add_co_u32_e32 v18, vcc, s13, v22
	s_cmp_ge_i32 s3, s10
	s_nop 0
	v_addc_co_u32_e32 v19, vcc, 0, v23, vcc
	global_load_dwordx4 v[32:35], v[18:19], off offset:2048 nt
	s_waitcnt vmcnt(4)
	v_lshlrev_b32_e32 v18, 16, v2
	v_and_b32_e32 v2, 0xffff0000, v2
	v_lshlrev_b32_e32 v19, 16, v3
	v_and_b32_e32 v3, 0xffff0000, v3
	v_lshlrev_b32_e32 v21, 16, v4
	v_and_b32_e32 v25, 0xffff0000, v4
	v_lshlrev_b32_e32 v20, 16, v5
	v_and_b32_e32 v24, 0xffff0000, v5
	s_waitcnt vmcnt(3)
	v_lshlrev_b32_e32 v5, 16, v6
	v_and_b32_e32 v27, 0xffff0000, v6
	v_lshlrev_b32_e32 v4, 16, v7
	v_and_b32_e32 v26, 0xffff0000, v7
	v_lshlrev_b32_e32 v7, 16, v8
	v_and_b32_e32 v29, 0xffff0000, v8
	v_lshlrev_b32_e32 v6, 16, v9
	v_and_b32_e32 v28, 0xffff0000, v9
	s_waitcnt vmcnt(2)
	v_lshlrev_b32_e32 v8, 16, v10
	v_and_b32_e32 v10, 0xffff0000, v10
	v_lshlrev_b32_e32 v9, 16, v11
	v_and_b32_e32 v11, 0xffff0000, v11
	v_and_b32_e32 v43, 0xffff0000, v12
	v_and_b32_e32 v42, 0xffff0000, v13
	v_pk_add_f32 v[74:75], v[2:3], v[10:11]
	v_lshlrev_b32_e32 v31, 16, v12
	v_lshlrev_b32_e32 v30, 16, v13
	s_waitcnt vmcnt(1)
	v_lshlrev_b32_e32 v13, 16, v14
	v_lshlrev_b32_e32 v12, 16, v15
	v_pk_add_f32 v[72:73], v[18:19], v[8:9]
	v_pk_add_f32 v[78:79], v[24:25], v[42:43]
	v_pk_mul_f32 v[2:3], v[74:75], v[74:75]
	v_and_b32_e32 v45, 0xffff0000, v14
	v_and_b32_e32 v44, 0xffff0000, v15
	v_pk_add_f32 v[76:77], v[20:21], v[30:31]
	v_pk_add_f32 v[48:49], v[4:5], v[12:13]
	v_pk_mul_f32 v[4:5], v[78:79], v[78:79]
	v_pk_fma_f32 v[2:3], v[72:73], v[72:73], v[2:3]
	v_lshlrev_b32_e32 v15, 16, v16
	v_lshlrev_b32_e32 v14, 16, v17
	v_pk_add_f32 v[46:47], v[26:27], v[44:45]
	v_pk_fma_f32 v[4:5], v[76:77], v[76:77], v[4:5]
	v_add_f32_e32 v2, v2, v3
	v_and_b32_e32 v71, 0xffff0000, v16
	v_and_b32_e32 v70, 0xffff0000, v17
	v_pk_add_f32 v[44:45], v[6:7], v[14:15]
	v_pk_mul_f32 v[6:7], v[46:47], v[46:47]
	v_add_f32_e32 v2, v5, v2
	v_pk_add_f32 v[42:43], v[28:29], v[70:71]
	v_pk_fma_f32 v[6:7], v[48:49], v[48:49], v[6:7]
	v_add_f32_e32 v2, v4, v2
	v_pk_mul_f32 v[8:9], v[42:43], v[42:43]
	v_add_f32_e32 v2, v7, v2
	v_pk_fma_f32 v[8:9], v[44:45], v[44:45], v[8:9]
	v_add_f32_e32 v2, v6, v2
	v_add_f32_e32 v2, v9, v2
	v_add_f32_e32 v4, v8, v2
	ds_bpermute_b32 v5, v51, v4
	v_lshl_add_u64 v[2:3], s[0:1], 0, v[36:37]
	global_load_dwordx4 v[10:13], v[2:3], off offset:16 nt
	global_load_dwordx4 v[18:21], v[2:3], off nt
	v_add_co_u32_e32 v70, vcc, s12, v2
	s_waitcnt lgkmcnt(0)
	v_add_f32_e32 v6, v4, v5
	ds_bpermute_b32 v7, v52, v6
	v_lshl_add_u64 v[4:5], v[22:23], 0, s[6:7]
	global_load_dwordx4 v[28:31], v[4:5], off offset:16 nt
	v_addc_co_u32_e32 v71, vcc, 0, v3, vcc
	s_waitcnt lgkmcnt(0)
	v_add_f32_e32 v6, v6, v7
	ds_bpermute_b32 v7, v53, v6
	s_waitcnt vmcnt(3)
	v_lshlrev_b32_e32 v4, 16, v33
	v_mul_f32_e32 v4, 0xbfb8aa3b, v4
	v_lshl_add_u64 v[26:27], v[2:3], 0, s[4:5]
	v_lshl_add_u64 v[2:3], s[18:19], 0, v[36:37]
	s_waitcnt lgkmcnt(0)
	v_add_f32_e32 v5, v6, v7
	v_fmamk_f32 v5, v5, 0x3c000000, v1
	v_mul_f32_e32 v6, 0x4b800000, v5
	v_cmp_gt_f32_e32 vcc, s14, v5
	v_exp_f32_e32 v4, v4
	v_lshl_add_u64 v[80:81], v[2:3], 0, s[6:7]
	v_cndmask_b32_e32 v5, v5, v6, vcc
	v_rsq_f32_e32 v5, v5
	v_add_co_u32_e64 v82, s[0:1], s13, v2
	v_add_f32_e32 v84, 1.0, v4
	v_mul_f32_e32 v2, 0x45800000, v5
	v_cndmask_b32_e32 v85, v5, v2, vcc
	v_mul_f32_e32 v2, v73, v85
	v_mul_f32_e32 v73, v56, v2
	v_addc_co_u32_e64 v83, s[0:1], 0, v3, s[0:1]
	v_div_scale_f32 v86, s[0:1], v84, v84, v73
	v_rcp_f32_e32 v87, v86
	v_and_b32_e32 v33, 0xffff0000, v33
	global_load_dwordx4 v[22:25], v[70:71], off nt
	global_load_dwordx4 v[6:9], v[82:83], off offset:2048 nt
	global_load_dwordx4 v[14:17], v[26:27], off offset:16 nt
	global_load_dwordx4 v[2:5], v[80:81], off offset:16 nt
	v_mul_f32_e32 v33, 0xbfb8aa3b, v33
	v_fma_f32 v26, -v86, v87, 1.0
	v_fmac_f32_e32 v87, v26, v87
	v_div_scale_f32 v26, vcc, v73, v84, v73
	v_exp_f32_e32 v33, v33
	v_mul_f32_e32 v27, v26, v87
	v_fma_f32 v70, -v86, v27, v26
	v_fmac_f32_e32 v27, v70, v87
	v_mul_f32_e32 v70, v75, v85
	v_mul_f32_e32 v70, v57, v70
	v_add_f32_e32 v33, 1.0, v33
	v_div_scale_f32 v71, s[0:1], v33, v33, v70
	v_rcp_f32_e32 v75, v71
	v_fma_f32 v26, -v86, v27, v26
	v_div_fmas_f32 v26, v26, v87, v27
	v_lshlrev_b32_e32 v81, 16, v32
	v_div_fixup_f32 v26, v26, v84, v73
	v_mul_f32_e32 v81, 0xbfb8aa3b, v81
	v_med3_f32 v27, v26, s15, v50
	v_fma_f32 v26, -v71, v75, 1.0
	v_exp_f32_e32 v81, v81
	v_fmac_f32_e32 v75, v26, v75
	v_div_scale_f32 v26, vcc, v70, v33, v70
	v_mul_f32_e32 v73, v26, v75
	v_fma_f32 v80, -v71, v73, v26
	v_mul_f32_e32 v72, v72, v85
	v_fmac_f32_e32 v73, v80, v75
	v_mul_f32_e32 v72, v54, v72
	v_add_f32_e32 v80, 1.0, v81
	v_div_scale_f32 v81, s[0:1], v80, v80, v72
	v_rcp_f32_e32 v82, v81
	v_and_b32_e32 v32, 0xffff0000, v32
	v_mul_f32_e32 v32, 0xbfb8aa3b, v32
	v_fma_f32 v26, -v71, v73, v26
	v_exp_f32_e32 v32, v32
	v_div_fmas_f32 v71, v26, v75, v73
	v_fma_f32 v26, -v81, v82, 1.0
	v_fmac_f32_e32 v82, v26, v82
	v_div_scale_f32 v26, vcc, v72, v80, v72
	v_mul_f32_e32 v73, v26, v82
	v_mul_f32_e32 v74, v74, v85
	v_fma_f32 v75, -v81, v73, v26
	v_mul_f32_e32 v74, v55, v74
	v_add_f32_e32 v32, 1.0, v32
	v_fmac_f32_e32 v73, v75, v82
	v_div_scale_f32 v75, s[0:1], v32, v32, v74
	v_fma_f32 v26, -v81, v73, v26
	v_rcp_f32_e32 v81, v75
	v_div_fmas_f32 v26, v26, v82, v73
	v_div_fixup_f32 v26, v26, v80, v72
	v_med3_f32 v72, v26, s15, v50
	v_fma_f32 v26, -v75, v81, 1.0
	v_fmac_f32_e32 v81, v26, v81
	v_div_scale_f32 v26, vcc, v74, v32, v74
	v_mul_f32_e32 v73, v26, v81
	v_fma_f32 v80, -v75, v73, v26
	v_fmac_f32_e32 v73, v80, v81
	v_fma_f32 v26, -v75, v73, v26
	v_div_fmas_f32 v26, v26, v81, v73
	v_lshlrev_b32_e32 v73, 16, v35
	v_mul_f32_e32 v73, 0xbfb8aa3b, v73
	v_exp_f32_e32 v73, v73
	v_div_fixup_f32 v26, v26, v32, v74
	v_med3_f32 v32, v26, s15, v50
	v_mov_b32_e32 v26, 0
	v_cvt_pk_fp8_f32 v26, v72, v32
	v_mul_f32_e32 v32, v76, v85
	v_mul_f32_e32 v32, v60, v32
	v_add_f32_e32 v72, 1.0, v73
	v_div_scale_f32 v73, s[0:1], v72, v72, v32
	v_rcp_f32_e32 v74, v73
	v_div_fixup_f32 v33, v71, v33, v70
	v_med3_f32 v33, v33, s15, v50
	v_and_b32_e32 v35, 0xffff0000, v35
	v_cvt_pk_fp8_f32 v26, v27, v33 op_sel:[0,0,1]
	v_fma_f32 v27, -v73, v74, 1.0
	v_mul_f32_e32 v35, 0xbfb8aa3b, v35
	v_fmac_f32_e32 v74, v27, v74
	v_div_scale_f32 v27, vcc, v32, v72, v32
	v_exp_f32_e32 v35, v35
	v_mul_f32_e32 v33, v27, v74
	v_fma_f32 v70, -v73, v33, v27
	v_fmac_f32_e32 v33, v70, v74
	v_mul_f32_e32 v70, v78, v85
	v_mul_f32_e32 v70, v61, v70
	v_add_f32_e32 v35, 1.0, v35
	v_div_scale_f32 v71, s[0:1], v35, v35, v70
	v_fma_f32 v27, -v73, v33, v27
	v_rcp_f32_e32 v73, v71
	v_div_fmas_f32 v27, v27, v74, v33
	v_div_fixup_f32 v27, v27, v72, v32
	v_lshlrev_b32_e32 v74, 16, v34
	v_med3_f32 v32, v27, s15, v50
	v_fma_f32 v27, -v71, v73, 1.0
	v_mul_f32_e32 v74, 0xbfb8aa3b, v74
	v_fmac_f32_e32 v73, v27, v73
	v_div_scale_f32 v27, vcc, v70, v35, v70
	v_exp_f32_e32 v74, v74
	v_mul_f32_e32 v33, v27, v73
	v_fma_f32 v72, -v71, v33, v27
	v_fmac_f32_e32 v33, v72, v73
	v_mul_f32_e32 v72, v77, v85
	v_mul_f32_e32 v72, v58, v72
	v_add_f32_e32 v74, 1.0, v74
	v_div_scale_f32 v75, s[0:1], v74, v74, v72
	v_rcp_f32_e32 v76, v75
	v_fma_f32 v27, -v71, v33, v27
	v_and_b32_e32 v34, 0xffff0000, v34
	v_div_fmas_f32 v33, v27, v73, v33
	v_fma_f32 v27, -v75, v76, 1.0
	v_mul_f32_e32 v34, 0xbfb8aa3b, v34
	v_fmac_f32_e32 v76, v27, v76
	v_div_scale_f32 v27, vcc, v72, v74, v72
	v_exp_f32_e32 v34, v34
	v_mul_f32_e32 v71, v27, v76
	v_fma_f32 v73, -v75, v71, v27
	v_fmac_f32_e32 v71, v73, v76
	v_mul_f32_e32 v73, v79, v85
	v_mul_f32_e32 v73, v59, v73
	v_add_f32_e32 v34, 1.0, v34
	v_fma_f32 v27, -v75, v71, v27
	v_div_scale_f32 v75, s[0:1], v34, v34, v73
	v_rcp_f32_e32 v77, v75
	v_div_fmas_f32 v27, v27, v76, v71
	v_div_fixup_f32 v27, v27, v74, v72
	v_med3_f32 v71, v27, s15, v50
	v_fma_f32 v27, -v75, v77, 1.0
	v_fmac_f32_e32 v77, v27, v77
	v_div_scale_f32 v27, vcc, v73, v34, v73
	v_mul_f32_e32 v72, v27, v77
	v_fma_f32 v74, -v75, v72, v27
	v_fmac_f32_e32 v72, v74, v77
	v_fma_f32 v27, -v75, v72, v27
	v_div_fmas_f32 v27, v27, v77, v72
	s_waitcnt vmcnt(4)
	v_lshlrev_b32_e32 v72, 16, v29
	v_mul_f32_e32 v72, 0xbfb8aa3b, v72
	v_exp_f32_e32 v72, v72
	v_div_fixup_f32 v27, v27, v34, v73
	v_med3_f32 v34, v27, s15, v50
	v_mov_b32_e32 v27, 0
	v_cvt_pk_fp8_f32 v27, v71, v34
	v_mul_f32_e32 v34, v48, v85
	v_mul_f32_e32 v34, v64, v34
	v_add_f32_e32 v48, 1.0, v72
	v_div_scale_f32 v71, s[0:1], v48, v48, v34
	v_rcp_f32_e32 v72, v71
	v_div_fixup_f32 v33, v33, v35, v70
	v_med3_f32 v33, v33, s15, v50
	v_and_b32_e32 v29, 0xffff0000, v29
	v_cvt_pk_fp8_f32 v27, v32, v33 op_sel:[0,0,1]
	v_fma_f32 v32, -v71, v72, 1.0
	v_mul_f32_e32 v29, 0xbfb8aa3b, v29
	v_fmac_f32_e32 v72, v32, v72
	v_div_scale_f32 v32, vcc, v34, v48, v34
	v_exp_f32_e32 v29, v29
	v_mul_f32_e32 v33, v32, v72
	v_fma_f32 v35, -v71, v33, v32
	v_fmac_f32_e32 v33, v35, v72
	v_mul_f32_e32 v35, v46, v85
	v_mul_f32_e32 v35, v65, v35
	v_add_f32_e32 v29, 1.0, v29
	v_div_scale_f32 v46, s[0:1], v29, v29, v35
	v_rcp_f32_e32 v70, v46
	v_fma_f32 v32, -v71, v33, v32
	v_lshlrev_b32_e32 v71, 16, v28
	v_div_fmas_f32 v32, v32, v72, v33
	v_fma_f32 v33, -v46, v70, 1.0
	v_mul_f32_e32 v71, 0xbfb8aa3b, v71
	v_fmac_f32_e32 v70, v33, v70
	v_div_scale_f32 v33, vcc, v35, v29, v35
	v_exp_f32_e32 v71, v71
	v_div_fixup_f32 v32, v32, v48, v34
	v_mul_f32_e32 v34, v33, v70
	v_fma_f32 v48, -v46, v34, v33
	v_fmac_f32_e32 v34, v48, v70
	v_mul_f32_e32 v48, v49, v85
	v_mul_f32_e32 v48, v62, v48
	v_add_f32_e32 v49, 1.0, v71
	v_div_scale_f32 v71, s[0:1], v49, v49, v48
	v_rcp_f32_e32 v72, v71
	v_and_b32_e32 v28, 0xffff0000, v28
	v_mul_f32_e32 v28, 0xbfb8aa3b, v28
	v_fma_f32 v33, -v46, v34, v33
	v_exp_f32_e32 v28, v28
	v_div_fmas_f32 v33, v33, v70, v34
	v_fma_f32 v34, -v71, v72, 1.0
	v_fmac_f32_e32 v72, v34, v72
	v_div_scale_f32 v34, vcc, v48, v49, v48
	v_mul_f32_e32 v46, v34, v72
	v_mul_f32_e32 v47, v47, v85
	v_fma_f32 v70, -v71, v46, v34
	v_mul_f32_e32 v47, v63, v47
	v_add_f32_e32 v28, 1.0, v28
	v_fmac_f32_e32 v46, v70, v72
	v_div_scale_f32 v70, s[0:1], v28, v28, v47
	v_fma_f32 v34, -v71, v46, v34
	v_rcp_f32_e32 v71, v70
	v_div_fmas_f32 v34, v34, v72, v46
	v_div_fixup_f32 v34, v34, v49, v48
	v_med3_f32 v34, v34, s15, v50
	v_fma_f32 v46, -v70, v71, 1.0
	v_fmac_f32_e32 v71, v46, v71
	v_div_scale_f32 v46, vcc, v47, v28, v47
	v_mul_f32_e32 v48, v46, v71
	v_fma_f32 v49, -v70, v48, v46
	v_fmac_f32_e32 v48, v49, v71
	v_fma_f32 v46, -v70, v48, v46
	v_div_fmas_f32 v46, v46, v71, v48
	v_div_fixup_f32 v28, v46, v28, v47
	v_lshlrev_b32_e32 v47, 16, v31
	v_mul_f32_e32 v47, 0xbfb8aa3b, v47
	v_exp_f32_e32 v47, v47
	v_med3_f32 v46, v28, s15, v50
	v_mov_b32_e32 v28, 0
	v_cvt_pk_fp8_f32 v28, v34, v46
	v_mul_f32_e32 v34, v44, v85
	v_mul_f32_e32 v34, v68, v34
	v_add_f32_e32 v44, 1.0, v47
	v_div_scale_f32 v46, s[0:1], v44, v44, v34
	v_rcp_f32_e32 v47, v46
	v_div_fixup_f32 v29, v33, v29, v35
	v_med3_f32 v32, v32, s15, v50
	v_med3_f32 v29, v29, s15, v50
	v_and_b32_e32 v31, 0xffff0000, v31
	v_cvt_pk_fp8_f32 v28, v32, v29 op_sel:[0,0,1]
	v_fma_f32 v29, -v46, v47, 1.0
	v_mul_f32_e32 v31, 0xbfb8aa3b, v31
	v_fmac_f32_e32 v47, v29, v47
	v_div_scale_f32 v29, vcc, v34, v44, v34
	v_exp_f32_e32 v31, v31
	v_mul_f32_e32 v32, v29, v47
	v_fma_f32 v33, -v46, v32, v29
	v_fmac_f32_e32 v32, v33, v47
	v_mul_f32_e32 v33, v42, v85
	v_mul_f32_e32 v35, v69, v33
	v_add_f32_e32 v42, 1.0, v31
	v_div_scale_f32 v31, s[0:1], v42, v42, v35
	v_rcp_f32_e32 v33, v31
	v_fma_f32 v29, -v46, v32, v29
	v_div_fmas_f32 v29, v29, v47, v32
	v_lshlrev_b32_e32 v46, 16, v30
	v_div_fixup_f32 v34, v29, v44, v34
	v_fma_f32 v29, -v31, v33, 1.0
	v_mul_f32_e32 v46, 0xbfb8aa3b, v46
	v_fmac_f32_e32 v33, v29, v33
	v_div_scale_f32 v29, vcc, v35, v42, v35
	v_exp_f32_e32 v46, v46
	v_mul_f32_e32 v32, v29, v33
	v_fma_f32 v44, -v31, v32, v29
	v_fmac_f32_e32 v32, v44, v33
	v_mul_f32_e32 v44, v45, v85
	v_mul_f32_e32 v44, v66, v44
	v_add_f32_e32 v45, 1.0, v46
	v_div_scale_f32 v46, s[0:1], v45, v45, v44
	v_rcp_f32_e32 v47, v46
	v_fma_f32 v29, -v31, v32, v29
	v_and_b32_e32 v30, 0xffff0000, v30
	v_div_fmas_f32 v48, v29, v33, v32
	v_fma_f32 v29, -v46, v47, 1.0
	v_mul_f32_e32 v30, 0xbfb8aa3b, v30
	v_fmac_f32_e32 v47, v29, v47
	v_div_scale_f32 v29, vcc, v44, v45, v44
	v_exp_f32_e32 v30, v30
	v_mul_f32_e32 v31, v29, v47
	v_fma_f32 v32, -v46, v31, v29
	v_fmac_f32_e32 v31, v32, v47
	v_mul_f32_e32 v32, v43, v85
	v_fma_f32 v29, -v46, v31, v29
	v_mul_f32_e32 v43, v67, v32
	v_add_f32_e32 v46, 1.0, v30
	v_div_scale_f32 v30, s[0:1], v46, v46, v43
	v_rcp_f32_e32 v32, v30
	v_div_fmas_f32 v29, v29, v47, v31
	v_div_fixup_f32 v29, v29, v45, v44
	v_med3_f32 v44, v29, s15, v50
	v_fma_f32 v29, -v30, v32, 1.0
	v_fmac_f32_e32 v32, v29, v32
	v_div_scale_f32 v29, vcc, v43, v46, v43
	v_mul_f32_e32 v31, v29, v32
	v_fma_f32 v33, -v30, v31, v29
	v_fmac_f32_e32 v31, v33, v32
	v_fma_f32 v29, -v30, v31, v29
	v_div_fmas_f32 v29, v29, v32, v31
	v_lshlrev_b32_e32 v30, 16, v18
	s_waitcnt vmcnt(3)
	v_lshlrev_b32_e32 v31, 16, v22
	v_and_b32_e32 v18, 0xffff0000, v18
	v_and_b32_e32 v22, 0xffff0000, v22
	v_add_f32_e32 v31, v30, v31
	v_add_f32_e32 v30, v18, v22
	v_lshlrev_b32_e32 v22, 16, v19
	v_lshlrev_b32_e32 v32, 16, v23
	v_add_f32_e32 v33, v22, v32
	v_and_b32_e32 v19, 0xffff0000, v19
	v_and_b32_e32 v22, 0xffff0000, v23
	v_add_f32_e32 v32, v19, v22
	v_mul_f32_e32 v18, v30, v30
	v_mul_f32_e32 v19, v32, v32
	v_fmac_f32_e32 v18, v31, v31
	v_fmac_f32_e32 v19, v33, v33
	v_add_f32_e32 v18, v18, v19
	v_lshlrev_b32_e32 v19, 16, v20
	v_lshlrev_b32_e32 v22, 16, v24
	v_add_f32_e32 v23, v19, v22
	v_and_b32_e32 v19, 0xffff0000, v20
	v_and_b32_e32 v20, 0xffff0000, v24
	v_add_f32_e32 v22, v19, v20
	v_mul_f32_e32 v19, v22, v22
	v_fmac_f32_e32 v19, v23, v23
	v_add_f32_e32 v18, v19, v18
	v_lshlrev_b32_e32 v19, 16, v21
	v_lshlrev_b32_e32 v20, 16, v25
	v_add_f32_e32 v24, v19, v20
	v_and_b32_e32 v19, 0xffff0000, v21
	v_and_b32_e32 v20, 0xffff0000, v25
	v_add_f32_e32 v21, v19, v20
	v_mul_f32_e32 v19, v21, v21
	v_fmac_f32_e32 v19, v24, v24
	v_add_f32_e32 v20, v19, v18
	v_lshlrev_b32_e32 v18, 16, v10
	s_waitcnt vmcnt(1)
	v_lshlrev_b32_e32 v19, 16, v14
	v_and_b32_e32 v10, 0xffff0000, v10
	v_and_b32_e32 v14, 0xffff0000, v14
	v_add_f32_e32 v19, v18, v19
	v_add_f32_e32 v18, v10, v14
	v_mul_f32_e32 v10, v18, v18
	v_fmac_f32_e32 v10, v19, v19
	v_add_f32_e32 v10, v20, v10
	v_lshlrev_b32_e32 v14, 16, v11
	v_lshlrev_b32_e32 v20, 16, v15
	v_add_f32_e32 v20, v14, v20
	v_and_b32_e32 v11, 0xffff0000, v11
	v_and_b32_e32 v14, 0xffff0000, v15
	v_add_f32_e32 v15, v11, v14
	v_mul_f32_e32 v11, v15, v15
	v_fmac_f32_e32 v11, v20, v20
	v_add_f32_e32 v14, v11, v10
	v_lshlrev_b32_e32 v10, 16, v12
	v_lshlrev_b32_e32 v11, 16, v16
	v_add_f32_e32 v11, v10, v11
	v_and_b32_e32 v10, 0xffff0000, v12
	v_and_b32_e32 v12, 0xffff0000, v16
	v_add_f32_e32 v10, v10, v12
	v_mul_f32_e32 v12, v10, v10
	v_fmac_f32_e32 v12, v11, v11
	v_add_f32_e32 v16, v12, v14
	v_lshlrev_b32_e32 v12, 16, v13
	v_lshlrev_b32_e32 v14, 16, v17
	v_add_f32_e32 v14, v12, v14
	v_and_b32_e32 v12, 0xffff0000, v13
	v_and_b32_e32 v13, 0xffff0000, v17
	v_add_f32_e32 v12, v12, v13
	v_mul_f32_e32 v13, v12, v12
	v_fmac_f32_e32 v13, v14, v14
	v_add_f32_e32 v13, v13, v16
	ds_bpermute_b32 v16, v51, v13
	v_div_fixup_f32 v17, v29, v46, v43
	v_med3_f32 v17, v17, s15, v50
	v_mov_b32_e32 v29, 0
	v_cvt_pk_fp8_f32 v29, v44, v17
	s_waitcnt lgkmcnt(0)
	v_add_f32_e32 v13, v13, v16
	ds_bpermute_b32 v16, v52, v13
	v_div_fixup_f32 v25, v48, v42, v35
	v_med3_f32 v17, v34, s15, v50
	v_med3_f32 v25, v25, s15, v50
	v_cvt_pk_fp8_f32 v29, v17, v25 op_sel:[0,0,1]
	s_waitcnt lgkmcnt(0)
	v_add_f32_e32 v13, v13, v16
	ds_bpermute_b32 v16, v53, v13
	global_store_dwordx4 v[38:39], v[26:29], off
	s_cbranch_scc1 .LBB0_487
	s_waitcnt lgkmcnt(0)
	v_add_f32_e32 v13, v13, v16
	v_fmamk_f32 v13, v13, 0x3c000000, v1
	v_mul_f32_e32 v16, 0x4b800000, v13
	v_cmp_gt_f32_e32 vcc, s14, v13
	s_nop 1
	v_cndmask_b32_e32 v13, v13, v16, vcc
	v_rsq_f32_e32 v13, v13
	v_lshlrev_b32_e32 v16, 16, v7
	v_mul_f32_e32 v16, 0xbfb8aa3b, v16
	v_exp_f32_e32 v16, v16
	v_mul_f32_e32 v17, 0x45800000, v13
	v_cndmask_b32_e32 v13, v13, v17, vcc
	v_mul_f32_e32 v17, v33, v13
	v_mul_f32_e32 v17, v56, v17
	v_add_f32_e32 v16, 1.0, v16
	v_div_scale_f32 v25, s[0:1], v16, v16, v17
	v_rcp_f32_e32 v26, v25
	v_and_b32_e32 v7, 0xffff0000, v7
	v_mul_f32_e32 v7, 0xbfb8aa3b, v7
	v_exp_f32_e32 v7, v7
	v_fma_f32 v27, -v25, v26, 1.0
	v_fmac_f32_e32 v26, v27, v26
	v_div_scale_f32 v27, vcc, v17, v16, v17
	v_mul_f32_e32 v28, v27, v26
	v_fma_f32 v29, -v25, v28, v27
	v_fmac_f32_e32 v28, v29, v26
	v_fma_f32 v25, -v25, v28, v27
	v_mul_f32_e32 v27, v32, v13
	v_mul_f32_e32 v27, v57, v27
	v_add_f32_e32 v7, 1.0, v7
	v_div_scale_f32 v29, s[0:1], v7, v7, v27
	v_rcp_f32_e32 v32, v29
	v_div_fmas_f32 v25, v25, v26, v28
	v_lshlrev_b32_e32 v28, 16, v6
	v_div_fixup_f32 v16, v25, v16, v17
	v_fma_f32 v17, -v29, v32, 1.0
	v_mul_f32_e32 v28, 0xbfb8aa3b, v28
	v_fmac_f32_e32 v32, v17, v32
	v_div_scale_f32 v17, vcc, v27, v7, v27
	v_exp_f32_e32 v28, v28
	v_mul_f32_e32 v25, v17, v32
	v_fma_f32 v26, -v29, v25, v17
	v_fmac_f32_e32 v25, v26, v32
	v_mul_f32_e32 v26, v31, v13
	v_mul_f32_e32 v26, v54, v26
	v_add_f32_e32 v28, 1.0, v28
	v_div_scale_f32 v31, s[0:1], v28, v28, v26
	v_rcp_f32_e32 v33, v31
	v_and_b32_e32 v6, 0xffff0000, v6
	v_fma_f32 v17, -v29, v25, v17
	v_mul_f32_e32 v6, 0xbfb8aa3b, v6
	v_div_fmas_f32 v17, v17, v32, v25
	v_fma_f32 v25, -v31, v33, 1.0
	v_exp_f32_e32 v6, v6
	v_fmac_f32_e32 v33, v25, v33
	v_div_scale_f32 v25, vcc, v26, v28, v26
	v_mul_f32_e32 v29, v25, v33
	v_fma_f32 v32, -v31, v29, v25
	v_mul_f32_e32 v30, v30, v13
	v_fmac_f32_e32 v29, v32, v33
	v_mul_f32_e32 v30, v55, v30
	v_add_f32_e32 v6, 1.0, v6
	v_fma_f32 v25, -v31, v29, v25
	v_div_scale_f32 v31, s[0:1], v6, v6, v30
	v_rcp_f32_e32 v32, v31
	v_div_fmas_f32 v25, v25, v33, v29
	v_div_fixup_f32 v25, v25, v28, v26
	v_med3_f32 v25, v25, s15, v50
	v_fma_f32 v26, -v31, v32, 1.0
	v_fmac_f32_e32 v32, v26, v32
	v_div_scale_f32 v26, vcc, v30, v6, v30
	v_mul_f32_e32 v28, v26, v32
	v_fma_f32 v29, -v31, v28, v26
	v_fmac_f32_e32 v28, v29, v32
	v_fma_f32 v26, -v31, v28, v26
	v_div_fmas_f32 v26, v26, v32, v28
	v_lshlrev_b32_e32 v28, 16, v9
	v_mul_f32_e32 v28, 0xbfb8aa3b, v28
	v_exp_f32_e32 v28, v28
	v_div_fixup_f32 v6, v26, v6, v30
	v_med3_f32 v26, v6, s15, v50
	v_mov_b32_e32 v6, 0
	v_mul_f32_e32 v24, v24, v13
	v_cvt_pk_fp8_f32 v6, v25, v26
	v_mul_f32_e32 v24, v60, v24
	v_add_f32_e32 v25, 1.0, v28
	v_div_scale_f32 v26, s[0:1], v25, v25, v24
	v_rcp_f32_e32 v28, v26
	v_div_fixup_f32 v7, v17, v7, v27
	v_med3_f32 v16, v16, s15, v50
	v_med3_f32 v7, v7, s15, v50
	v_and_b32_e32 v9, 0xffff0000, v9
	v_cvt_pk_fp8_f32 v6, v16, v7 op_sel:[0,0,1]
	v_fma_f32 v7, -v26, v28, 1.0
	v_mul_f32_e32 v9, 0xbfb8aa3b, v9
	v_fmac_f32_e32 v28, v7, v28
	v_div_scale_f32 v7, vcc, v24, v25, v24
	v_exp_f32_e32 v9, v9
	v_mul_f32_e32 v16, v7, v28
	v_fma_f32 v17, -v26, v16, v7
	v_fmac_f32_e32 v16, v17, v28
	v_mul_f32_e32 v17, v21, v13
	v_mul_f32_e32 v17, v61, v17
	v_add_f32_e32 v9, 1.0, v9
	v_div_scale_f32 v21, s[0:1], v9, v9, v17
	v_fma_f32 v7, -v26, v16, v7
	v_rcp_f32_e32 v26, v21
	v_div_fmas_f32 v7, v7, v28, v16
	v_lshlrev_b32_e32 v27, 16, v8
	v_div_fixup_f32 v7, v7, v25, v24
	v_mul_f32_e32 v27, 0xbfb8aa3b, v27
	v_med3_f32 v16, v7, s15, v50
	v_fma_f32 v7, -v21, v26, 1.0
	v_exp_f32_e32 v27, v27
	v_fmac_f32_e32 v26, v7, v26
	v_div_scale_f32 v7, vcc, v17, v9, v17
	v_mul_f32_e32 v24, v7, v26
	v_fma_f32 v25, -v21, v24, v7
	v_mul_f32_e32 v23, v23, v13
	v_fmac_f32_e32 v24, v25, v26
	v_mul_f32_e32 v23, v58, v23
	v_add_f32_e32 v25, 1.0, v27
	v_div_scale_f32 v27, s[0:1], v25, v25, v23
	v_rcp_f32_e32 v28, v27
	v_and_b32_e32 v8, 0xffff0000, v8
	v_mul_f32_e32 v8, 0xbfb8aa3b, v8
	v_fma_f32 v7, -v21, v24, v7
	v_exp_f32_e32 v8, v8
	v_div_fmas_f32 v21, v7, v26, v24
	v_fma_f32 v7, -v27, v28, 1.0
	v_fmac_f32_e32 v28, v7, v28
	v_div_scale_f32 v7, vcc, v23, v25, v23
	v_mul_f32_e32 v24, v7, v28
	v_mul_f32_e32 v22, v22, v13
	v_fma_f32 v26, -v27, v24, v7
	v_mul_f32_e32 v22, v59, v22
	v_add_f32_e32 v8, 1.0, v8
	v_fmac_f32_e32 v24, v26, v28
	v_div_scale_f32 v26, s[0:1], v8, v8, v22
	v_fma_f32 v7, -v27, v24, v7
	v_rcp_f32_e32 v27, v26
	v_div_fmas_f32 v7, v7, v28, v24
	v_div_fixup_f32 v7, v7, v25, v23
	v_med3_f32 v23, v7, s15, v50
	v_fma_f32 v7, -v26, v27, 1.0
	v_fmac_f32_e32 v27, v7, v27
	v_div_scale_f32 v7, vcc, v22, v8, v22
	v_mul_f32_e32 v24, v7, v27
	v_fma_f32 v25, -v26, v24, v7
	v_fmac_f32_e32 v24, v25, v27
	v_fma_f32 v7, -v26, v24, v7
	v_div_fmas_f32 v7, v7, v27, v24
	v_div_fixup_f32 v7, v7, v8, v22
	s_waitcnt vmcnt(1)
	v_lshlrev_b32_e32 v22, 16, v3
	v_mul_f32_e32 v22, 0xbfb8aa3b, v22
	v_exp_f32_e32 v22, v22
	v_med3_f32 v8, v7, s15, v50
	v_mov_b32_e32 v7, 0
	v_cvt_pk_fp8_f32 v7, v23, v8
	v_mul_f32_e32 v8, v20, v13
	v_mul_f32_e32 v8, v64, v8
	v_add_f32_e32 v20, 1.0, v22
	v_div_scale_f32 v22, s[0:1], v20, v20, v8
	v_rcp_f32_e32 v23, v22
	v_and_b32_e32 v3, 0xffff0000, v3
	v_div_fixup_f32 v9, v21, v9, v17
	v_mul_f32_e32 v3, 0xbfb8aa3b, v3
	v_med3_f32 v9, v9, s15, v50
	v_exp_f32_e32 v3, v3
	v_cvt_pk_fp8_f32 v7, v16, v9 op_sel:[0,0,1]
	v_fma_f32 v9, -v22, v23, 1.0
	v_fmac_f32_e32 v23, v9, v23
	v_div_scale_f32 v9, vcc, v8, v20, v8
	v_mul_f32_e32 v16, v9, v23
	v_mul_f32_e32 v15, v15, v13
	v_fma_f32 v17, -v22, v16, v9
	v_mul_f32_e32 v15, v65, v15
	v_add_f32_e32 v3, 1.0, v3
	v_fmac_f32_e32 v16, v17, v23
	v_div_scale_f32 v17, s[0:1], v3, v3, v15
	v_rcp_f32_e32 v21, v17
	v_fma_f32 v9, -v22, v16, v9
	v_div_fmas_f32 v9, v9, v23, v16
	v_lshlrev_b32_e32 v22, 16, v2
	v_div_fixup_f32 v8, v9, v20, v8
	v_mul_f32_e32 v22, 0xbfb8aa3b, v22
	v_med3_f32 v9, v8, s15, v50
	v_fma_f32 v8, -v17, v21, 1.0
	v_exp_f32_e32 v22, v22
	v_fmac_f32_e32 v21, v8, v21
	v_div_scale_f32 v8, vcc, v15, v3, v15
	v_mul_f32_e32 v16, v8, v21
	v_fma_f32 v20, -v17, v16, v8
	v_mul_f32_e32 v19, v19, v13
	v_fmac_f32_e32 v16, v20, v21
	v_mul_f32_e32 v19, v62, v19
	v_add_f32_e32 v20, 1.0, v22
	v_div_scale_f32 v22, s[0:1], v20, v20, v19
	v_rcp_f32_e32 v23, v22
	v_and_b32_e32 v2, 0xffff0000, v2
	v_mul_f32_e32 v2, 0xbfb8aa3b, v2
	v_fma_f32 v8, -v17, v16, v8
	v_exp_f32_e32 v2, v2
	v_div_fmas_f32 v16, v8, v21, v16
	v_fma_f32 v8, -v22, v23, 1.0
	v_fmac_f32_e32 v23, v8, v23
	v_div_scale_f32 v8, vcc, v19, v20, v19
	v_mul_f32_e32 v17, v8, v23
	v_mul_f32_e32 v18, v18, v13
	v_fma_f32 v21, -v22, v17, v8
	v_mul_f32_e32 v18, v63, v18
	v_add_f32_e32 v2, 1.0, v2
	v_fmac_f32_e32 v17, v21, v23
	v_div_scale_f32 v21, s[0:1], v2, v2, v18
	v_fma_f32 v8, -v22, v17, v8
	v_rcp_f32_e32 v22, v21
	v_div_fmas_f32 v8, v8, v23, v17
	v_div_fixup_f32 v8, v8, v20, v19
	v_med3_f32 v17, v8, s15, v50
	v_fma_f32 v8, -v21, v22, 1.0
	v_fmac_f32_e32 v22, v8, v22
	v_div_scale_f32 v8, vcc, v18, v2, v18
	v_mul_f32_e32 v19, v8, v22
	v_fma_f32 v20, -v21, v19, v8
	v_fmac_f32_e32 v19, v20, v22
	v_fma_f32 v8, -v21, v19, v8
	v_div_fmas_f32 v8, v8, v22, v19
	v_div_fixup_f32 v2, v8, v2, v18
	v_lshlrev_b32_e32 v18, 16, v5
	v_mul_f32_e32 v18, 0xbfb8aa3b, v18
	v_exp_f32_e32 v18, v18
	v_med3_f32 v2, v2, s15, v50
	v_mov_b32_e32 v8, 0
	v_cvt_pk_fp8_f32 v8, v17, v2
	v_mul_f32_e32 v2, v14, v13
	v_mul_f32_e32 v2, v68, v2
	v_add_f32_e32 v14, 1.0, v18
	v_div_scale_f32 v17, s[0:1], v14, v14, v2
	v_rcp_f32_e32 v18, v17
	v_and_b32_e32 v5, 0xffff0000, v5
	v_div_fixup_f32 v3, v16, v3, v15
	v_mul_f32_e32 v5, 0xbfb8aa3b, v5
	v_med3_f32 v3, v3, s15, v50
	v_exp_f32_e32 v5, v5
	v_cvt_pk_fp8_f32 v8, v9, v3 op_sel:[0,0,1]
	v_fma_f32 v3, -v17, v18, 1.0
	v_fmac_f32_e32 v18, v3, v18
	v_div_scale_f32 v3, vcc, v2, v14, v2
	v_mul_f32_e32 v9, v3, v18
	v_mul_f32_e32 v12, v12, v13
	v_fma_f32 v15, -v17, v9, v3
	v_mul_f32_e32 v12, v69, v12
	v_add_f32_e32 v5, 1.0, v5
	v_fmac_f32_e32 v9, v15, v18
	v_div_scale_f32 v15, s[0:1], v5, v5, v12
	v_rcp_f32_e32 v16, v15
	v_fma_f32 v3, -v17, v9, v3
	v_lshlrev_b32_e32 v17, 16, v4
	v_div_fmas_f32 v3, v3, v18, v9
	v_mul_f32_e32 v17, 0xbfb8aa3b, v17
	v_div_fixup_f32 v2, v3, v14, v2
	v_fma_f32 v3, -v15, v16, 1.0
	v_exp_f32_e32 v17, v17
	v_fmac_f32_e32 v16, v3, v16
	v_div_scale_f32 v3, vcc, v12, v5, v12
	v_mul_f32_e32 v9, v3, v16
	v_fma_f32 v14, -v15, v9, v3
	v_mul_f32_e32 v11, v11, v13
	v_fmac_f32_e32 v9, v14, v16
	v_mul_f32_e32 v11, v66, v11
	v_add_f32_e32 v14, 1.0, v17
	v_div_scale_f32 v17, s[0:1], v14, v14, v11
	v_rcp_f32_e32 v18, v17
	v_and_b32_e32 v4, 0xffff0000, v4
	v_mul_f32_e32 v4, 0xbfb8aa3b, v4
	v_exp_f32_e32 v4, v4
	v_fma_f32 v3, -v15, v9, v3
	v_div_fmas_f32 v3, v3, v16, v9
	v_fma_f32 v9, -v17, v18, 1.0
	v_fmac_f32_e32 v18, v9, v18
	v_div_scale_f32 v9, vcc, v11, v14, v11
	v_mul_f32_e32 v10, v10, v13
	v_mul_f32_e32 v15, v9, v18
	v_mul_f32_e32 v10, v67, v10
	v_add_f32_e32 v4, 1.0, v4
	v_fma_f32 v16, -v17, v15, v9
	v_div_scale_f32 v13, s[0:1], v4, v4, v10
	v_fmac_f32_e32 v15, v16, v18
	v_rcp_f32_e32 v16, v13
	v_fma_f32 v9, -v17, v15, v9
	v_div_fmas_f32 v9, v9, v18, v15
	v_div_fixup_f32 v9, v9, v14, v11
	v_med3_f32 v11, v9, s15, v50
	v_fma_f32 v9, -v13, v16, 1.0
	v_fmac_f32_e32 v16, v9, v16
	v_div_scale_f32 v9, vcc, v10, v4, v10
	v_mul_f32_e32 v14, v9, v16
	v_fma_f32 v15, -v13, v14, v9
	v_fmac_f32_e32 v14, v15, v16
	v_fma_f32 v9, -v13, v14, v9
	v_div_fmas_f32 v9, v9, v16, v14
	v_div_fixup_f32 v4, v9, v4, v10
	v_med3_f32 v4, v4, s15, v50
	v_mov_b32_e32 v9, 0
	v_cvt_pk_fp8_f32 v9, v11, v4
	v_div_fixup_f32 v3, v3, v5, v12
	v_med3_f32 v2, v2, s15, v50
	v_med3_f32 v3, v3, s15, v50
	v_cvt_pk_fp8_f32 v9, v2, v3 op_sel:[0,0,1]
	global_store_dwordx4 v[40:41], v[6:9], off
	s_branch .LBB0_487

.LBB0_496:
	s_add_i32 s82, s38, s3
	s_and_b32 s4, s82, s40
	s_add_i32 s81, s4, -8
	s_max_i32 s0, s81, 0
	s_min_u32 s0, s0, s40
	s_sub_i32 s0, s0, s4
	s_add_i32 s0, s82, s0
	v_mad_i64_i32 v[10:11], s[0:1], s0, v1, v[2:3]
	s_add_i32 s80, s4, -7
	s_max_i32 s0, s80, 0
	s_min_u32 s0, s0, s40
	s_sub_i32 s0, s0, s4
	s_add_i32 s0, s82, s0
	global_load_dwordx2 v[54:55], v[10:11], off nt
	v_mad_i64_i32 v[10:11], s[0:1], s0, v1, v[2:3]
	s_add_i32 s79, s4, -6
	s_max_i32 s0, s79, 0
	s_min_u32 s0, s0, s40
	s_sub_i32 s0, s0, s4
	s_add_i32 s0, s82, s0
	global_load_dwordx2 v[52:53], v[10:11], off nt
	v_mad_i64_i32 v[10:11], s[0:1], s0, v1, v[2:3]
	s_add_i32 s78, s4, -5
	s_max_i32 s0, s78, 0
	s_min_u32 s0, s0, s40
	s_sub_i32 s0, s0, s4
	s_add_i32 s0, s82, s0
	global_load_dwordx2 v[50:51], v[10:11], off nt
	v_mad_i64_i32 v[10:11], s[0:1], s0, v1, v[2:3]
	s_add_i32 s71, s4, -4
	s_max_i32 s0, s71, 0
	s_min_u32 s0, s0, s40
	s_sub_i32 s0, s0, s4
	s_add_i32 s0, s82, s0
	global_load_dwordx2 v[48:49], v[10:11], off nt
	v_mad_i64_i32 v[10:11], s[0:1], s0, v1, v[2:3]
	s_add_i32 s70, s4, -3
	s_max_i32 s0, s70, 0
	s_min_u32 s0, s0, s40
	s_sub_i32 s0, s0, s4
	s_add_i32 s0, s82, s0
	global_load_dwordx2 v[46:47], v[10:11], off nt
	v_mad_i64_i32 v[10:11], s[0:1], s0, v1, v[2:3]
	s_add_i32 s69, s4, -2
	s_max_i32 s0, s69, 0
	s_min_u32 s0, s0, s40
	s_sub_i32 s0, s0, s4
	s_add_i32 s0, s82, s0
	global_load_dwordx2 v[44:45], v[10:11], off nt
	v_mad_i64_i32 v[10:11], s[0:1], s0, v1, v[2:3]
	v_sub_co_u32_e64 v63, s[0:1], s4, 1
	s_nop 0
	v_readfirstlane_b32 s5, v63
	s_max_i32 s5, s5, 0
	s_min_u32 s5, s5, s40
	s_sub_i32 s5, s5, s4
	s_add_i32 s5, s82, s5
	s_or_b32 s68, s4, 1
	global_load_dwordx2 v[42:43], v[10:11], off nt
	v_mad_i64_i32 v[10:11], s[28:29], s5, v1, v[2:3]
	s_min_u32 s5, s68, s40
	s_sub_i32 s5, s5, s4
	global_load_dwordx2 v[24:25], v[10:11], off nt
	v_lshl_add_u64 v[10:11], s[74:75], 0, v[8:9]
	s_add_i32 s5, s82, s5
	s_or_b32 s67, s4, 2
	global_load_dwordx2 v[60:61], v[10:11], off nt
	v_mad_i64_i32 v[10:11], s[28:29], s5, v1, v[2:3]
	s_min_u32 s5, s67, s40
	s_sub_i32 s5, s5, s4
	s_add_i32 s5, s82, s5
	s_or_b32 s66, s4, 3
	global_load_dwordx2 v[64:65], v[10:11], off nt
	v_mad_i64_i32 v[10:11], s[28:29], s5, v1, v[2:3]
	s_min_u32 s5, s66, s40
	s_sub_i32 s5, s5, s4
	s_add_i32 s5, s82, s5
	s_or_b32 s65, s4, 4
	global_load_dwordx2 v[114:115], v[10:11], off nt
	v_mad_i64_i32 v[10:11], s[28:29], s5, v1, v[2:3]
	s_min_u32 s5, s65, s40
	s_sub_i32 s5, s5, s4
	s_add_i32 s5, s82, s5
	s_or_b32 s64, s4, 5
	global_load_dwordx2 v[116:117], v[10:11], off nt
	v_mad_i64_i32 v[10:11], s[28:29], s5, v1, v[2:3]
	s_min_u32 s5, s64, s40
	s_sub_i32 s5, s5, s4
	s_add_i32 s5, s82, s5
	s_or_b32 s63, s4, 6
	global_load_dwordx2 v[118:119], v[10:11], off nt
	v_mad_i64_i32 v[10:11], s[28:29], s5, v1, v[2:3]
	s_min_u32 s5, s63, s40
	s_sub_i32 s5, s5, s4
	s_add_i32 s5, s82, s5
	s_or_b32 s62, s4, 7
	global_load_dwordx2 v[120:121], v[10:11], off nt
	v_mad_i64_i32 v[10:11], s[28:29], s5, v1, v[2:3]
	s_min_u32 s5, s62, s40
	s_sub_i32 s5, s5, s4
	s_add_i32 s5, s82, s5
	global_load_dwordx2 v[58:59], v[10:11], off nt
	v_mad_i64_i32 v[10:11], s[28:29], s5, v1, v[2:3]
	global_load_dwordx2 v[56:57], v[10:11], off nt
	s_or_b32 s60, s4, 8
	s_min_u32 s5, s60, s40
	s_sub_i32 s5, s5, s4
	s_add_i32 s5, s82, s5
	s_or_b32 s58, s4, 9
	v_mad_i64_i32 v[10:11], s[28:29], s5, v1, v[2:3]
	s_min_u32 s5, s58, s40
	s_sub_i32 s5, s5, s4
	s_add_i32 s5, s82, s5
	s_or_b32 s56, s4, 10
	global_load_dwordx2 v[40:41], v[10:11], off nt
	v_mad_i64_i32 v[10:11], s[28:29], s5, v1, v[2:3]
	s_min_u32 s5, s56, s40
	s_sub_i32 s5, s5, s4
	s_add_i32 s5, s82, s5
	s_or_b32 s48, s4, 11
	global_load_dwordx2 v[38:39], v[10:11], off nt
	v_mad_i64_i32 v[10:11], s[28:29], s5, v1, v[2:3]
	s_min_u32 s5, s48, s40
	s_sub_i32 s5, s5, s4
	s_add_i32 s5, s82, s5
	s_or_b32 s46, s4, 12
	global_load_dwordx2 v[36:37], v[10:11], off nt
	v_mad_i64_i32 v[10:11], s[28:29], s5, v1, v[2:3]
	s_min_u32 s5, s46, s40
	s_sub_i32 s5, s5, s4
	s_add_i32 s5, s82, s5
	s_or_b32 s31, s4, 13
	global_load_dwordx2 v[34:35], v[10:11], off nt
	v_mad_i64_i32 v[10:11], s[28:29], s5, v1, v[2:3]
	s_min_u32 s5, s31, s40
	s_sub_i32 s5, s5, s4
	s_add_i32 s5, s82, s5
	global_load_dwordx2 v[32:33], v[10:11], off nt
	v_mad_i64_i32 v[10:11], s[28:29], s5, v1, v[2:3]
	s_or_b32 s28, s4, 14
	s_min_u32 s5, s28, s40
	s_sub_i32 s5, s5, s4
	s_add_i32 s5, s82, s5
	global_load_dwordx2 v[30:31], v[10:11], off nt
	v_mad_i64_i32 v[10:11], s[84:85], s5, v1, v[2:3]
	s_or_b32 s5, s4, 15
	s_min_u32 s29, s5, s40
	s_sub_i32 s29, s29, s4
	s_add_i32 s29, s82, s29
	s_add_i32 s61, s4, 16
	global_load_dwordx2 v[28:29], v[10:11], off nt
	v_mad_i64_i32 v[10:11], s[84:85], s29, v1, v[2:3]
	s_min_u32 s29, s61, s40
	s_sub_i32 s29, s29, s4
	s_add_i32 s29, s82, s29
	s_add_i32 s59, s4, 17
	global_load_dwordx2 v[26:27], v[10:11], off nt
	v_mad_i64_i32 v[10:11], s[84:85], s29, v1, v[2:3]
	s_min_u32 s29, s59, s40
	s_sub_i32 s29, s29, s4
	s_add_i32 s29, s82, s29
	s_add_i32 s57, s4, 18
	global_load_dwordx2 v[22:23], v[10:11], off nt
	v_mad_i64_i32 v[10:11], s[84:85], s29, v1, v[2:3]
	s_min_u32 s29, s57, s40
	s_sub_i32 s29, s29, s4
	s_add_i32 s29, s82, s29
	s_add_i32 s49, s4, 19
	global_load_dwordx2 v[20:21], v[10:11], off nt
	v_mad_i64_i32 v[10:11], s[84:85], s29, v1, v[2:3]
	s_min_u32 s29, s49, s40
	s_sub_i32 s29, s29, s4
	s_add_i32 s29, s82, s29
	s_add_i32 s47, s4, 20
	global_load_dwordx2 v[18:19], v[10:11], off nt
	v_mad_i64_i32 v[10:11], s[84:85], s29, v1, v[2:3]
	s_min_u32 s29, s47, s40
	s_sub_i32 s29, s29, s4
	s_add_i32 s29, s82, s29
	s_add_i32 s45, s4, 21
	s_waitcnt lgkmcnt(0)
	global_load_dwordx2 v[16:17], v[10:11], off nt
	v_mad_i64_i32 v[10:11], s[84:85], s29, v1, v[2:3]
	s_min_u32 s29, s45, s40
	s_sub_i32 s29, s29, s4
	s_add_i32 s29, s82, s29
	global_load_dwordx2 v[14:15], v[10:11], off nt
	v_mad_i64_i32 v[10:11], s[84:85], s29, v1, v[2:3]
	s_add_i32 s29, s4, 22
	s_min_u32 s50, s29, s40
	s_sub_i32 s50, s50, s4
	s_add_i32 s82, s82, s50
	global_load_dwordx2 v[12:13], v[10:11], off nt
	v_mad_i64_i32 v[10:11], s[82:83], s82, v1, v[2:3]
	s_cmp_lt_u32 s81, s39
	s_cselect_b64 s[82:83], -1, 0
	s_cmp_lt_u32 s80, s39
	v_cndmask_b32_e64 v66, 0, 1.0, s[82:83]
	s_waitcnt vmcnt(29)
	v_lshlrev_b32_e32 v100, 16, v54
	v_and_b32_e32 v101, 0xffff0000, v54
	v_lshlrev_b32_e32 v102, 16, v55
	v_and_b32_e32 v108, 0xffff0000, v55
	s_cselect_b64 s[80:81], -1, 0
	s_cmp_lt_u32 s79, s39
	v_fma_f32 v67, v66, v100, 0
	v_fma_f32 v54, v66, v101, 0
	v_fma_f32 v68, v66, v102, 0
	v_fma_f32 v55, v66, v108, 0
	v_cndmask_b32_e64 v66, 0, 1.0, s[80:81]
	s_waitcnt vmcnt(28)
	v_lshlrev_b32_e32 v107, 16, v52
	v_and_b32_e32 v106, 0xffff0000, v52
	v_lshlrev_b32_e32 v105, 16, v53
	v_and_b32_e32 v103, 0xffff0000, v53
	s_cselect_b64 s[80:81], -1, 0
	s_cmp_lt_u32 s78, s39
	v_fmac_f32_e32 v67, v66, v107
	v_fmac_f32_e32 v54, v66, v106
	v_fmac_f32_e32 v68, v66, v105
	v_fmac_f32_e32 v55, v66, v103
	v_cndmask_b32_e64 v52, 0, 1.0, s[80:81]
	s_waitcnt vmcnt(27)
	v_lshlrev_b32_e32 v98, 16, v50
	v_and_b32_e32 v97, 0xffff0000, v50
	v_lshlrev_b32_e32 v96, 16, v51
	v_and_b32_e32 v95, 0xffff0000, v51
	s_cselect_b64 s[78:79], -1, 0
	s_cmp_lt_u32 s71, s39
	v_fmac_f32_e32 v67, v52, v98
	v_fmac_f32_e32 v54, v52, v97
	v_fmac_f32_e32 v68, v52, v96
	v_fmac_f32_e32 v55, v52, v95
	v_cndmask_b32_e64 v50, 0, 1.0, s[78:79]
	s_waitcnt vmcnt(26)
	v_lshlrev_b32_e32 v94, 16, v48
	v_and_b32_e32 v93, 0xffff0000, v48
	v_lshlrev_b32_e32 v92, 16, v49
	v_and_b32_e32 v91, 0xffff0000, v49
	s_cselect_b64 s[78:79], -1, 0
	s_cmp_lt_u32 s70, s39
	v_fmac_f32_e32 v67, v50, v94
	v_fmac_f32_e32 v54, v50, v93
	v_fmac_f32_e32 v68, v50, v92
	v_fmac_f32_e32 v55, v50, v91
	v_cndmask_b32_e64 v48, 0, 1.0, s[78:79]
	s_waitcnt vmcnt(25)
	v_lshlrev_b32_e32 v90, 16, v46
	v_and_b32_e32 v89, 0xffff0000, v46
	v_lshlrev_b32_e32 v88, 16, v47
	v_and_b32_e32 v87, 0xffff0000, v47
	s_cselect_b64 s[70:71], -1, 0
	s_cmp_lt_u32 s69, s39
	v_fmac_f32_e32 v67, v48, v90
	v_fmac_f32_e32 v54, v48, v89
	v_fmac_f32_e32 v68, v48, v88
	v_fmac_f32_e32 v55, v48, v87
	v_cndmask_b32_e64 v46, 0, 1.0, s[70:71]
	s_waitcnt vmcnt(24)
	v_lshlrev_b32_e32 v86, 16, v44
	v_and_b32_e32 v85, 0xffff0000, v44
	v_lshlrev_b32_e32 v84, 16, v45
	v_and_b32_e32 v83, 0xffff0000, v45
	s_cselect_b64 s[70:71], -1, 0
	v_fmac_f32_e32 v67, v46, v86
	v_fmac_f32_e32 v54, v46, v85
	v_fmac_f32_e32 v68, v46, v84
	v_fmac_f32_e32 v55, v46, v83
	v_cndmask_b32_e64 v44, 0, 1.0, s[70:71]
	s_waitcnt vmcnt(23)
	v_lshlrev_b32_e32 v82, 16, v42
	v_and_b32_e32 v81, 0xffff0000, v42
	v_lshlrev_b32_e32 v80, 16, v43
	v_and_b32_e32 v79, 0xffff0000, v43
	v_cmp_gt_u32_e32 vcc, s39, v63
	v_fmac_f32_e32 v67, v44, v82
	v_fmac_f32_e32 v54, v44, v81
	v_fmac_f32_e32 v68, v44, v80
	v_fmac_f32_e32 v55, v44, v79
	v_cndmask_b32_e64 v42, 0, 1.0, vcc
	s_waitcnt vmcnt(22)
	v_lshlrev_b32_e32 v78, 16, v24
	v_and_b32_e32 v77, 0xffff0000, v24
	v_lshlrev_b32_e32 v76, 16, v25
	v_and_b32_e32 v75, 0xffff0000, v25
	s_cmp_lt_u32 s68, s39
	v_fmac_f32_e32 v67, v42, v78
	v_fmac_f32_e32 v54, v42, v77
	v_fmac_f32_e32 v68, v42, v76
	v_fmac_f32_e32 v55, v42, v75
	s_waitcnt vmcnt(21)
	v_lshlrev_b32_e32 v74, 16, v60
	v_and_b32_e32 v73, 0xffff0000, v60
	v_lshlrev_b32_e32 v72, 16, v61
	v_and_b32_e32 v71, 0xffff0000, v61
	s_cselect_b64 s[70:71], -1, 0
	s_cmp_lt_u32 s67, s39
	v_add_f32_e32 v112, v67, v74
	v_add_f32_e32 v111, v54, v73
	v_add_f32_e32 v110, v68, v72
	v_add_f32_e32 v109, v55, v71
	v_cndmask_b32_e64 v24, 0, 1.0, s[70:71]
	s_waitcnt vmcnt(20)
	v_lshlrev_b32_e32 v70, 16, v64
	v_and_b32_e32 v69, 0xffff0000, v64
	v_lshlrev_b32_e32 v68, 16, v65
	v_and_b32_e32 v67, 0xffff0000, v65
	s_cselect_b64 s[70:71], -1, 0
	s_cmp_lt_u32 s66, s39
	v_fmac_f32_e32 v112, v24, v70
	v_fmac_f32_e32 v111, v24, v69
	v_fmac_f32_e32 v110, v24, v68
	v_fmac_f32_e32 v109, v24, v67
	v_cndmask_b32_e64 v24, 0, 1.0, s[70:71]
	s_waitcnt vmcnt(19)
	v_lshlrev_b32_e32 v66, 16, v114
	v_and_b32_e32 v65, 0xffff0000, v114
	v_lshlrev_b32_e32 v64, 16, v115
	v_and_b32_e32 v63, 0xffff0000, v115
	s_cselect_b64 s[70:71], -1, 0
	s_cmp_lt_u32 s65, s39
	v_fmac_f32_e32 v112, v24, v66
	v_fmac_f32_e32 v111, v24, v65
	v_fmac_f32_e32 v110, v24, v64
	v_fmac_f32_e32 v109, v24, v63
	v_cndmask_b32_e64 v24, 0, 1.0, s[70:71]
	s_waitcnt vmcnt(18)
	v_lshlrev_b32_e32 v61, 16, v116
	v_and_b32_e32 v60, 0xffff0000, v116
	v_lshlrev_b32_e32 v55, 16, v117
	v_and_b32_e32 v54, 0xffff0000, v117
	s_cselect_b64 s[70:71], -1, 0
	s_cmp_lt_u32 s64, s39
	v_fmac_f32_e32 v112, v24, v61
	v_fmac_f32_e32 v111, v24, v60
	v_fmac_f32_e32 v110, v24, v55
	v_fmac_f32_e32 v109, v24, v54
	v_cndmask_b32_e64 v24, 0, 1.0, s[70:71]
	s_waitcnt vmcnt(17)
	v_lshlrev_b32_e32 v53, 16, v118
	v_and_b32_e32 v52, 0xffff0000, v118
	v_lshlrev_b32_e32 v51, 16, v119
	v_and_b32_e32 v50, 0xffff0000, v119
	s_cselect_b64 s[70:71], -1, 0
	s_cmp_lt_u32 s63, s39
	v_fmac_f32_e32 v112, v24, v53
	v_fmac_f32_e32 v111, v24, v52
	v_fmac_f32_e32 v110, v24, v51
	v_fmac_f32_e32 v109, v24, v50
	v_cndmask_b32_e64 v24, 0, 1.0, s[70:71]
	s_waitcnt vmcnt(16)
	v_lshlrev_b32_e32 v49, 16, v120
	v_and_b32_e32 v48, 0xffff0000, v120
	v_lshlrev_b32_e32 v47, 16, v121
	v_and_b32_e32 v46, 0xffff0000, v121
	s_cselect_b64 s[70:71], -1, 0
	s_cmp_lt_u32 s62, s39
	v_fmac_f32_e32 v112, v24, v49
	v_fmac_f32_e32 v111, v24, v48
	v_fmac_f32_e32 v110, v24, v47
	v_fmac_f32_e32 v109, v24, v46
	v_cndmask_b32_e64 v24, 0, 1.0, s[70:71]
	s_waitcnt vmcnt(15)
	v_lshlrev_b32_e32 v42, 16, v58
	v_and_b32_e32 v43, 0xffff0000, v58
	v_lshlrev_b32_e32 v44, 16, v59
	v_and_b32_e32 v45, 0xffff0000, v59
	s_cselect_b64 s[70:71], -1, 0
	v_fmac_f32_e32 v112, v24, v42
	v_fmac_f32_e32 v111, v24, v43
	v_fmac_f32_e32 v110, v24, v44
	v_fmac_f32_e32 v109, v24, v45
	v_cndmask_b32_e64 v24, 0, 1.0, s[70:71]
	s_waitcnt vmcnt(14)
	v_lshlrev_b32_e32 v58, 16, v56
	v_and_b32_e32 v56, 0xffff0000, v56
	v_lshlrev_b32_e32 v59, 16, v57
	v_and_b32_e32 v57, 0xffff0000, v57
	v_fmac_f32_e32 v112, v24, v58
	v_fmac_f32_e32 v111, v24, v56
	v_fmac_f32_e32 v110, v24, v59
	v_fmac_f32_e32 v109, v24, v57
	s_min_u32 s50, s60, s39
	v_sub_u32_e64 v24, s4, 8 clamp
	v_sub_u32_e32 v24, s50, v24
	v_cvt_f32_i32_e32 v24, v24
	s_cmp_lt_u32 s68, s2
	global_load_dwordx2 v[10:11], v[10:11], off nt
	v_lshl_add_u64 v[8:9], v[8:9], 0, s[12:13]
	v_div_scale_f32 v25, s[70:71], v24, v24, 1.0
	v_rcp_f32_e32 v99, v25
	s_cselect_b64 s[70:71], -1, 0
	v_fma_f32 v104, -v25, v99, 1.0
	v_fmac_f32_e32 v99, v104, v99
	v_div_scale_f32 v104, vcc, 1.0, v24, 1.0
	v_mul_f32_e32 v113, v104, v99
	v_fma_f32 v114, -v25, v113, v104
	v_fmac_f32_e32 v113, v114, v99
	v_fma_f32 v25, -v25, v113, v104
	v_div_fmas_f32 v25, v25, v99, v113
	v_div_fixup_f32 v25, v25, v24, 1.0
	v_fma_f32 v24, v25, v112, -v74
	v_mul_f32_e32 v99, 0x41800000, v24
	v_fma_f32 v24, v25, v111, -v73
	v_mul_f32_e32 v104, 0x41800000, v24
	v_med3_f32 v99, v99, s21, v62
	v_med3_f32 v104, v104, s21, v62
	v_mov_b32_e32 v113, 0
	v_cvt_pk_fp8_f32 v113, v99, v104
	v_fma_f32 v24, v25, v110, -v72
	v_fma_f32 v25, v25, v109, -v71
	v_mul_f32_e32 v24, 0x41800000, v24
	v_mul_f32_e32 v25, 0x41800000, v25
	v_med3_f32 v24, v24, s21, v62
	v_med3_f32 v25, v25, s21, v62
	v_cvt_pk_fp8_f32 v113, v24, v25 op_sel:[0,0,1]
	v_lshl_add_u64 v[24:25], s[74:75], 0, v[6:7]
	v_add_co_u32_e32 v114, vcc, s22, v24
	v_cndmask_b32_e64 v104, 1.0, 0, s[0:1]
	s_nop 0
	v_addc_co_u32_e32 v115, vcc, 0, v25, vcc
	global_store_dword v[114:115], v113, off offset:1024
	v_cndmask_b32_e64 v113, 0, 1.0, s[70:71]
	s_waitcnt vmcnt(15)
	v_lshlrev_b32_e32 v99, 16, v40
	v_mul_f32_e32 v100, v104, v100
	v_fma_f32 v100, v113, v99, -v100
	v_add_f32_e32 v112, v100, v112
	v_and_b32_e32 v100, 0xffff0000, v40
	v_mul_f32_e32 v40, v104, v101
	v_fma_f32 v40, v113, v100, -v40
	v_add_f32_e32 v111, v40, v111
	v_lshlrev_b32_e32 v101, 16, v41
	v_mul_f32_e32 v40, v104, v102
	v_fma_f32 v40, v113, v101, -v40
	v_add_f32_e32 v110, v40, v110
	v_and_b32_e32 v102, 0xffff0000, v41
	v_mul_f32_e32 v40, v104, v108
	v_fma_f32 v40, v113, v102, -v40
	v_add_f32_e32 v108, v40, v109
	s_min_u32 s0, s58, s39
	v_sub_u32_e64 v40, s68, 8 clamp
	v_sub_u32_e32 v40, s0, v40
	v_cvt_f32_i32_e32 v40, v40
	s_cmp_lt_u32 s67, s2
	v_mul_f32_e32 v103, v104, v103
	v_mul_f32_e32 v105, v104, v105
	v_div_scale_f32 v41, s[0:1], v40, v40, 1.0
	v_rcp_f32_e32 v109, v41
	s_cselect_b64 s[0:1], -1, 0
	v_mul_f32_e32 v97, v104, v97
	v_mul_f32_e32 v96, v104, v96
	v_fma_f32 v113, -v41, v109, 1.0
	v_fmac_f32_e32 v109, v113, v109
	v_div_scale_f32 v113, vcc, 1.0, v40, 1.0
	v_mul_f32_e32 v116, v113, v109
	v_fma_f32 v117, -v41, v116, v113
	v_fmac_f32_e32 v116, v117, v109
	v_fma_f32 v41, -v41, v116, v113
	v_div_fmas_f32 v41, v41, v109, v116
	v_div_fixup_f32 v40, v41, v40, 1.0
	v_fma_f32 v41, v40, v112, -v70
	v_fma_f32 v109, v40, v111, -v69
	v_mul_f32_e32 v41, 0x41800000, v41
	v_mul_f32_e32 v109, 0x41800000, v109
	v_med3_f32 v41, v41, s21, v62
	v_med3_f32 v109, v109, s21, v62
	v_mov_b32_e32 v116, 0
	v_cvt_pk_fp8_f32 v116, v41, v109
	v_fma_f32 v113, v40, v110, -v68
	v_fma_f32 v40, v40, v108, -v67
	v_mul_f32_e32 v113, 0x41800000, v113
	v_mul_f32_e32 v40, 0x41800000, v40
	v_med3_f32 v41, v113, s21, v62
	v_med3_f32 v40, v40, s21, v62
	v_cvt_pk_fp8_f32 v116, v41, v40 op_sel:[0,0,1]
	v_cndmask_b32_e64 v109, 0, 1.0, s[0:1]
	s_waitcnt vmcnt(14)
	v_lshlrev_b32_e32 v40, 16, v38
	v_mul_f32_e32 v41, v104, v107
	v_fma_f32 v41, v109, v40, -v41
	v_add_f32_e32 v112, v41, v112
	v_and_b32_e32 v38, 0xffff0000, v38
	v_mul_f32_e32 v41, v104, v106
	v_fma_f32 v41, v109, v38, -v41
	v_add_f32_e32 v111, v41, v111
	v_lshlrev_b32_e32 v41, 16, v39
	v_and_b32_e32 v39, 0xffff0000, v39
	v_fma_f32 v103, v109, v39, -v103
	v_add_f32_e32 v108, v103, v108
	s_min_u32 s0, s56, s39
	v_sub_u32_e64 v103, s67, 8 clamp
	v_sub_u32_e32 v103, s0, v103
	v_cvt_f32_i32_e32 v103, v103
	v_fma_f32 v105, v109, v41, -v105
	v_add_f32_e32 v105, v105, v110
	s_cmp_lt_u32 s66, s2
	v_div_scale_f32 v106, s[0:1], v103, v103, 1.0
	v_rcp_f32_e32 v107, v106
	s_cselect_b64 s[0:1], -1, 0
	v_mul_f32_e32 v95, v104, v95
	v_mul_f32_e32 v98, v104, v98
	v_fma_f32 v109, -v106, v107, 1.0
	v_fmac_f32_e32 v107, v109, v107
	v_div_scale_f32 v109, vcc, 1.0, v103, 1.0
	v_mul_f32_e32 v110, v109, v107
	v_fma_f32 v113, -v106, v110, v109
	v_fmac_f32_e32 v110, v113, v107
	v_fma_f32 v106, -v106, v110, v109
	v_div_fmas_f32 v106, v106, v107, v110
	v_div_fixup_f32 v103, v106, v103, 1.0
	v_fma_f32 v106, v103, v112, -v66
	v_fma_f32 v107, v103, v111, -v65
	v_mul_f32_e32 v106, 0x41800000, v106
	v_mul_f32_e32 v107, 0x41800000, v107
	v_med3_f32 v106, v106, s21, v62
	v_med3_f32 v107, v107, s21, v62
	v_mov_b32_e32 v110, 0
	v_cvt_pk_fp8_f32 v110, v106, v107
	v_fma_f32 v109, v103, v105, -v64
	v_fma_f32 v103, v103, v108, -v63
	v_mul_f32_e32 v109, 0x41800000, v109
	v_mul_f32_e32 v103, 0x41800000, v103
	v_med3_f32 v106, v109, s21, v62
	v_med3_f32 v103, v103, s21, v62
	v_cvt_pk_fp8_f32 v110, v106, v103 op_sel:[0,0,1]
	v_add_co_u32_e32 v106, vcc, s23, v24
	v_cndmask_b32_e64 v109, 0, 1.0, s[0:1]
	s_waitcnt vmcnt(13)
	v_lshlrev_b32_e32 v103, 16, v36
	v_and_b32_e32 v36, 0xffff0000, v36
	v_addc_co_u32_e32 v107, vcc, 0, v25, vcc
	v_fma_f32 v97, v109, v36, -v97
	global_store_dword v[106:107], v110, off offset:1024
	v_add_f32_e32 v110, v97, v111
	v_lshlrev_b32_e32 v97, 16, v37
	v_and_b32_e32 v37, 0xffff0000, v37
	v_fma_f32 v96, v109, v97, -v96
	v_fma_f32 v95, v109, v37, -v95
	v_add_f32_e32 v96, v96, v105
	v_add_f32_e32 v105, v95, v108
	s_min_u32 s0, s48, s39
	v_sub_u32_e64 v95, s66, 8 clamp
	v_sub_u32_e32 v95, s0, v95
	v_cvt_f32_i32_e32 v95, v95
	v_fma_f32 v98, v109, v103, -v98
	v_add_f32_e32 v98, v98, v112
	s_cmp_lt_u32 s65, s2
	v_div_scale_f32 v108, s[0:1], v95, v95, 1.0
	v_rcp_f32_e32 v109, v108
	s_cselect_b64 s[0:1], -1, 0
	v_mul_f32_e32 v94, v104, v94
	v_mul_f32_e32 v93, v104, v93
	v_fma_f32 v111, -v108, v109, 1.0
	v_fmac_f32_e32 v109, v111, v109
	v_div_scale_f32 v111, vcc, 1.0, v95, 1.0
	v_mul_f32_e32 v112, v111, v109
	v_fma_f32 v113, -v108, v112, v111
	v_fmac_f32_e32 v112, v113, v109
	v_fma_f32 v108, -v108, v112, v111
	v_div_fmas_f32 v108, v108, v109, v112
	v_div_fixup_f32 v95, v108, v95, 1.0
	v_fma_f32 v108, v95, v98, -v61
	v_fma_f32 v109, v95, v110, -v60
	v_mul_f32_e32 v108, 0x41800000, v108
	v_mul_f32_e32 v109, 0x41800000, v109
	v_med3_f32 v108, v108, s21, v62
	v_med3_f32 v109, v109, s21, v62
	v_mov_b32_e32 v112, 0
	v_cvt_pk_fp8_f32 v112, v108, v109
	v_fma_f32 v111, v95, v96, -v55
	v_fma_f32 v95, v95, v105, -v54
	v_mul_f32_e32 v111, 0x41800000, v111
	v_mul_f32_e32 v95, 0x41800000, v95
	v_med3_f32 v108, v111, s21, v62
	v_med3_f32 v95, v95, s21, v62
	v_cvt_pk_fp8_f32 v112, v108, v95 op_sel:[0,0,1]
	s_waitcnt vmcnt(13)
	v_lshlrev_b32_e32 v95, 16, v34
	v_and_b32_e32 v34, 0xffff0000, v34
	v_mul_f32_e32 v92, v104, v92
	global_store_dword v[106:107], v112, off offset:3072
	v_cndmask_b32_e64 v106, 0, 1.0, s[0:1]
	v_fma_f32 v94, v106, v95, -v94
	v_fma_f32 v93, v106, v34, -v93
	v_add_f32_e32 v94, v94, v98
	v_add_f32_e32 v98, v93, v110
	v_lshlrev_b32_e32 v93, 16, v35
	v_and_b32_e32 v35, 0xffff0000, v35
	v_mul_f32_e32 v91, v104, v91
	v_fma_f32 v92, v106, v93, -v92
	v_fma_f32 v91, v106, v35, -v91
	v_add_f32_e32 v92, v92, v96
	v_add_f32_e32 v96, v91, v105
	s_min_u32 s0, s46, s39
	v_sub_u32_e64 v91, s65, 8 clamp
	v_sub_u32_e32 v91, s0, v91
	v_cvt_f32_i32_e32 v91, v91
	s_cmp_lt_u32 s64, s2
	v_mul_f32_e32 v90, v104, v90
	v_mul_f32_e32 v89, v104, v89
	v_div_scale_f32 v105, s[0:1], v91, v91, 1.0
	v_rcp_f32_e32 v106, v105
	s_cselect_b64 s[0:1], -1, 0
	v_mul_f32_e32 v88, v104, v88
	v_mul_f32_e32 v87, v104, v87
	v_fma_f32 v107, -v105, v106, 1.0
	v_fmac_f32_e32 v106, v107, v106
	v_div_scale_f32 v107, vcc, 1.0, v91, 1.0
	v_mul_f32_e32 v108, v107, v106
	v_fma_f32 v109, -v105, v108, v107
	v_fmac_f32_e32 v108, v109, v106
	v_fma_f32 v105, -v105, v108, v107
	v_div_fmas_f32 v105, v105, v106, v108
	v_div_fixup_f32 v91, v105, v91, 1.0
	v_fma_f32 v105, v91, v94, -v53
	v_fma_f32 v106, v91, v98, -v52
	v_mul_f32_e32 v105, 0x41800000, v105
	v_mul_f32_e32 v106, 0x41800000, v106
	v_med3_f32 v105, v105, s21, v62
	v_med3_f32 v106, v106, s21, v62
	v_mov_b32_e32 v108, 0
	v_cvt_pk_fp8_f32 v108, v105, v106
	v_fma_f32 v107, v91, v92, -v51
	v_fma_f32 v91, v91, v96, -v50
	v_mul_f32_e32 v107, 0x41800000, v107
	v_mul_f32_e32 v91, 0x41800000, v91
	v_med3_f32 v105, v107, s21, v62
	v_med3_f32 v91, v91, s21, v62
	v_cvt_pk_fp8_f32 v108, v105, v91 op_sel:[0,0,1]
	v_cndmask_b32_e64 v105, 0, 1.0, s[0:1]
	s_waitcnt vmcnt(13)
	v_lshlrev_b32_e32 v91, 16, v32
	v_and_b32_e32 v32, 0xffff0000, v32
	v_fma_f32 v90, v105, v91, -v90
	v_fma_f32 v89, v105, v32, -v89
	v_add_f32_e32 v90, v90, v94
	v_add_f32_e32 v94, v89, v98
	v_lshlrev_b32_e32 v89, 16, v33
	v_and_b32_e32 v33, 0xffff0000, v33
	v_fma_f32 v88, v105, v89, -v88
	v_fma_f32 v87, v105, v33, -v87
	v_add_f32_e32 v88, v88, v92
	v_add_f32_e32 v92, v87, v96
	s_min_u32 s0, s31, s39
	v_sub_u32_e64 v87, s64, 8 clamp
	v_sub_u32_e32 v87, s0, v87
	v_cvt_f32_i32_e32 v87, v87
	v_add_co_u32_e32 v106, vcc, s24, v24
	s_cmp_lt_u32 s63, s2
	v_div_scale_f32 v96, s[0:1], v87, v87, 1.0
	v_rcp_f32_e32 v98, v96
	v_addc_co_u32_e32 v107, vcc, 0, v25, vcc
	global_store_dword v[106:107], v108, off offset:1024
	v_fma_f32 v105, -v96, v98, 1.0
	v_fmac_f32_e32 v98, v105, v98
	v_div_scale_f32 v105, vcc, 1.0, v87, 1.0
	v_mul_f32_e32 v108, v105, v98
	v_fma_f32 v109, -v96, v108, v105
	v_fmac_f32_e32 v108, v109, v98
	v_fma_f32 v96, -v96, v108, v105
	v_div_fmas_f32 v96, v96, v98, v108
	v_div_fixup_f32 v87, v96, v87, 1.0
	v_fma_f32 v96, v87, v90, -v49
	v_fma_f32 v98, v87, v94, -v48
	v_mul_f32_e32 v96, 0x41800000, v96
	v_mul_f32_e32 v98, 0x41800000, v98
	v_med3_f32 v96, v96, s21, v62
	v_med3_f32 v98, v98, s21, v62
	v_mov_b32_e32 v108, 0
	v_cvt_pk_fp8_f32 v108, v96, v98
	v_fma_f32 v105, v87, v88, -v47
	v_fma_f32 v87, v87, v92, -v46
	v_mul_f32_e32 v105, 0x41800000, v105
	v_mul_f32_e32 v87, 0x41800000, v87
	v_med3_f32 v96, v105, s21, v62
	v_med3_f32 v87, v87, s21, v62
	s_cselect_b64 s[0:1], -1, 0
	v_cvt_pk_fp8_f32 v108, v96, v87 op_sel:[0,0,1]
	v_cndmask_b32_e64 v96, 0, 1.0, s[0:1]
	s_waitcnt vmcnt(13)
	v_lshlrev_b32_e32 v87, 16, v30
	v_mul_f32_e32 v86, v104, v86
	v_and_b32_e32 v30, 0xffff0000, v30
	v_mul_f32_e32 v85, v104, v85
	v_fma_f32 v86, v96, v87, -v86
	v_fma_f32 v85, v96, v30, -v85
	v_add_f32_e32 v86, v86, v90
	v_add_f32_e32 v90, v85, v94
	v_lshlrev_b32_e32 v85, 16, v31
	v_mul_f32_e32 v84, v104, v84
	v_and_b32_e32 v31, 0xffff0000, v31
	v_mul_f32_e32 v83, v104, v83
	v_fma_f32 v84, v96, v85, -v84
	v_fma_f32 v83, v96, v31, -v83
	v_add_f32_e32 v84, v84, v88
	v_add_f32_e32 v88, v83, v92
	s_min_u32 s0, s28, s39
	v_sub_u32_e64 v83, s63, 8 clamp
	v_sub_u32_e32 v83, s0, v83
	v_cvt_f32_i32_e32 v83, v83
	s_cmp_lt_u32 s62, s2
	v_mul_f32_e32 v82, v104, v82
	v_mul_f32_e32 v81, v104, v81
	v_div_scale_f32 v92, s[0:1], v83, v83, 1.0
	v_rcp_f32_e32 v94, v92
	s_cselect_b64 s[0:1], -1, 0
	v_mul_f32_e32 v80, v104, v80
	v_mul_f32_e32 v79, v104, v79
	v_fma_f32 v96, -v92, v94, 1.0
	v_fmac_f32_e32 v94, v96, v94
	v_div_scale_f32 v96, vcc, 1.0, v83, 1.0
	v_mul_f32_e32 v98, v96, v94
	v_fma_f32 v105, -v92, v98, v96
	v_fmac_f32_e32 v98, v105, v94
	v_fma_f32 v92, -v92, v98, v96
	v_div_fmas_f32 v92, v92, v94, v98
	v_div_fixup_f32 v83, v92, v83, 1.0
	v_fma_f32 v92, v83, v86, -v42
	v_fma_f32 v94, v83, v90, -v43
	v_mul_f32_e32 v92, 0x41800000, v92
	v_mul_f32_e32 v94, 0x41800000, v94
	v_med3_f32 v92, v92, s21, v62
	v_med3_f32 v94, v94, s21, v62
	v_mov_b32_e32 v98, 0
	v_cvt_pk_fp8_f32 v98, v92, v94
	v_fma_f32 v96, v83, v84, -v44
	v_fma_f32 v83, v83, v88, -v45
	v_mul_f32_e32 v96, 0x41800000, v96
	v_mul_f32_e32 v83, 0x41800000, v83
	v_med3_f32 v92, v96, s21, v62
	v_med3_f32 v83, v83, s21, v62
	v_cvt_pk_fp8_f32 v98, v92, v83 op_sel:[0,0,1]
	v_cndmask_b32_e64 v92, 0, 1.0, s[0:1]
	s_waitcnt vmcnt(12)
	v_lshlrev_b32_e32 v83, 16, v28
	v_and_b32_e32 v28, 0xffff0000, v28
	v_fma_f32 v82, v92, v83, -v82
	v_fma_f32 v81, v92, v28, -v81
	v_add_f32_e32 v82, v82, v86
	v_add_f32_e32 v86, v81, v90
	v_lshlrev_b32_e32 v81, 16, v29
	v_fma_f32 v80, v92, v81, -v80
	v_add_f32_e32 v80, v80, v84
	s_min_u32 s0, s5, s39
	v_sub_u32_e64 v84, s62, 8 clamp
	v_sub_u32_e32 v84, s0, v84
	v_cvt_f32_i32_e32 v84, v84
	v_and_b32_e32 v29, 0xffff0000, v29
	v_fma_f32 v79, v92, v29, -v79
	v_add_f32_e32 v79, v79, v88
	v_div_scale_f32 v88, s[0:1], v84, v84, 1.0
	v_rcp_f32_e32 v90, v88
	global_store_dword v[106:107], v108, off offset:3072
	v_add_co_u32_e32 v106, vcc, s25, v24
	v_fma_f32 v92, -v88, v90, 1.0
	s_nop 0
	v_addc_co_u32_e32 v107, vcc, 0, v25, vcc
	v_fmac_f32_e32 v90, v92, v90
	v_div_scale_f32 v92, vcc, 1.0, v84, 1.0
	v_mul_f32_e32 v94, v92, v90
	v_fma_f32 v96, -v88, v94, v92
	v_fmac_f32_e32 v94, v96, v90
	v_fma_f32 v88, -v88, v94, v92
	v_div_fmas_f32 v88, v88, v90, v94
	v_div_fixup_f32 v84, v88, v84, 1.0
	v_fma_f32 v58, v84, v82, -v58
	v_fma_f32 v56, v84, v86, -v56
	v_mul_f32_e32 v58, 0x41800000, v58
	v_mul_f32_e32 v56, 0x41800000, v56
	v_fma_f32 v59, v84, v80, -v59
	v_fma_f32 v57, v84, v79, -v57
	v_med3_f32 v58, v58, s21, v62
	v_med3_f32 v56, v56, s21, v62
	v_mov_b32_e32 v84, 0
	v_cvt_pk_fp8_f32 v84, v58, v56
	v_mul_f32_e32 v59, 0x41800000, v59
	v_mul_f32_e32 v57, 0x41800000, v57
	s_cmp_lt_u32 s60, s2
	v_med3_f32 v56, v59, s21, v62
	v_med3_f32 v57, v57, s21, v62
	s_cselect_b64 s[0:1], -1, 0
	v_cvt_pk_fp8_f32 v84, v56, v57 op_sel:[0,0,1]
	v_cndmask_b32_e64 v58, 0, 1.0, s[0:1]
	s_waitcnt vmcnt(12)
	v_lshlrev_b32_e32 v56, 16, v26
	v_mul_f32_e32 v57, v104, v78
	v_fma_f32 v57, v58, v56, -v57
	v_add_f32_e32 v78, v57, v82
	v_and_b32_e32 v26, 0xffff0000, v26
	v_mul_f32_e32 v57, v104, v77
	v_fma_f32 v57, v58, v26, -v57
	v_add_f32_e32 v77, v57, v86
	v_lshlrev_b32_e32 v57, 16, v27
	v_mul_f32_e32 v59, v104, v76
	v_fma_f32 v59, v58, v57, -v59
	s_min_u32 s0, s61, s39
	v_add_f32_e32 v76, v59, v80
	v_and_b32_e32 v27, 0xffff0000, v27
	v_mul_f32_e32 v59, v104, v75
	s_sub_i32 s0, s0, s60
	v_fma_f32 v58, v58, v27, -v59
	s_add_i32 s0, s0, 8
	v_add_f32_e32 v75, v58, v79
	v_cvt_f32_i32_e32 v58, s0
	global_store_dword v[106:107], v84, off offset:3072
	s_cmp_lt_u32 s58, s2
	v_lshl_add_u64 v[6:7], v[6:7], 0, s[10:11]
	v_div_scale_f32 v59, s[0:1], v58, v58, 1.0
	v_rcp_f32_e32 v79, v59
	s_cselect_b64 s[0:1], -1, 0
	global_store_dword v[114:115], v116, off offset:3072
	global_store_dword v[106:107], v98, off offset:1024
	v_fma_f32 v80, -v59, v79, 1.0
	v_fmac_f32_e32 v79, v80, v79
	v_div_scale_f32 v80, vcc, 1.0, v58, 1.0
	v_mul_f32_e32 v82, v80, v79
	v_fma_f32 v84, -v59, v82, v80
	v_fmac_f32_e32 v82, v84, v79
	v_fma_f32 v59, -v59, v82, v80
	v_div_fmas_f32 v59, v59, v79, v82
	v_div_fixup_f32 v58, v59, v58, 1.0
	v_fma_f32 v59, v58, v78, -v99
	v_fma_f32 v79, v58, v77, -v100
	v_mul_f32_e32 v59, 0x41800000, v59
	v_mul_f32_e32 v79, 0x41800000, v79
	v_fma_f32 v80, v58, v76, -v101
	v_med3_f32 v59, v59, s21, v62
	v_med3_f32 v79, v79, s21, v62
	v_mov_b32_e32 v82, 0
	v_mul_f32_e32 v80, 0x41800000, v80
	v_cvt_pk_fp8_f32 v82, v59, v79
	v_cndmask_b32_e64 v79, 0, 1.0, s[0:1]
	s_min_u32 s0, s59, s39
	v_med3_f32 v59, v80, s21, v62
	s_waitcnt vmcnt(14)
	v_lshlrev_b32_e32 v80, 16, v22
	v_and_b32_e32 v22, 0xffff0000, v22
	s_sub_i32 s0, s0, s58
	v_fma_f32 v22, v79, v22, -v73
	v_lshlrev_b32_e32 v73, 16, v23
	v_and_b32_e32 v23, 0xffff0000, v23
	s_add_i32 s0, s0, 8
	v_fma_f32 v23, v79, v23, -v71
	v_cvt_f32_i32_e32 v71, s0
	v_fma_f32 v72, v79, v73, -v72
	v_fma_f32 v58, v58, v75, -v102
	v_add_f32_e32 v23, v23, v75
	v_div_scale_f32 v73, s[0:1], v71, v71, 1.0
	v_rcp_f32_e32 v75, v73
	v_mul_f32_e32 v58, 0x41800000, v58
	v_med3_f32 v58, v58, s21, v62
	v_cvt_pk_fp8_f32 v82, v59, v58 op_sel:[0,0,1]
	v_add_co_u32_e32 v58, vcc, s26, v24
	v_add_f32_e32 v72, v72, v76
	s_nop 0
	v_addc_co_u32_e32 v59, vcc, 0, v25, vcc
	v_fma_f32 v76, -v73, v75, 1.0
	v_fmac_f32_e32 v75, v76, v75
	v_div_scale_f32 v76, vcc, 1.0, v71, 1.0
	v_fma_f32 v74, v79, v80, -v74
	v_add_f32_e32 v22, v22, v77
	v_mul_f32_e32 v77, v76, v75
	v_add_f32_e32 v74, v74, v78
	v_fma_f32 v78, -v73, v77, v76
	v_fmac_f32_e32 v77, v78, v75
	v_fma_f32 v73, -v73, v77, v76
	v_div_fmas_f32 v73, v73, v75, v77
	v_div_fixup_f32 v71, v73, v71, 1.0
	v_fma_f32 v40, v71, v74, -v40
	v_fma_f32 v38, v71, v22, -v38
	v_mul_f32_e32 v40, 0x41800000, v40
	v_mul_f32_e32 v38, 0x41800000, v38
	v_fma_f32 v41, v71, v72, -v41
	v_fma_f32 v39, v71, v23, -v39
	v_med3_f32 v40, v40, s21, v62
	v_med3_f32 v38, v38, s21, v62
	v_mov_b32_e32 v71, 0
	v_cvt_pk_fp8_f32 v71, v40, v38
	v_mul_f32_e32 v41, 0x41800000, v41
	v_mul_f32_e32 v39, 0x41800000, v39
	s_cmp_lt_u32 s56, s2
	v_med3_f32 v38, v41, s21, v62
	v_med3_f32 v39, v39, s21, v62
	s_cselect_b64 s[0:1], -1, 0
	v_cvt_pk_fp8_f32 v71, v38, v39 op_sel:[0,0,1]
	v_cndmask_b32_e64 v38, 0, 1.0, s[0:1]
	s_waitcnt vmcnt(13)
	v_lshlrev_b32_e32 v39, 16, v20
	v_and_b32_e32 v20, 0xffff0000, v20
	v_fma_f32 v20, v38, v20, -v69
	v_add_f32_e32 v22, v20, v22
	v_lshlrev_b32_e32 v20, 16, v21
	v_fma_f32 v20, v38, v20, -v68
	s_min_u32 s0, s57, s39
	v_add_f32_e32 v40, v20, v72
	v_and_b32_e32 v20, 0xffff0000, v21
	s_sub_i32 s0, s0, s56
	v_fma_f32 v20, v38, v20, -v67
	s_add_i32 s0, s0, 8
	v_add_f32_e32 v23, v20, v23
	v_cvt_f32_i32_e32 v20, s0
	v_fma_f32 v39, v38, v39, -v70
	global_store_dword v[58:59], v82, off offset:1024
	global_store_dword v[58:59], v71, off offset:3072
	v_div_scale_f32 v21, s[0:1], v20, v20, 1.0
	v_rcp_f32_e32 v38, v21
	v_add_f32_e32 v39, v39, v74
	s_cmp_lt_u32 s48, s2
	s_cselect_b64 s[0:1], -1, 0
	v_fma_f32 v41, -v21, v38, 1.0
	v_fmac_f32_e32 v38, v41, v38
	v_div_scale_f32 v41, vcc, 1.0, v20, 1.0
	v_mul_f32_e32 v58, v41, v38
	v_fma_f32 v59, -v21, v58, v41
	v_fmac_f32_e32 v58, v59, v38
	v_fma_f32 v21, -v21, v58, v41
	v_div_fmas_f32 v21, v21, v38, v58
	v_div_fixup_f32 v20, v21, v20, 1.0
	v_fma_f32 v21, v20, v39, -v103
	v_fma_f32 v36, v20, v22, -v36
	v_mul_f32_e32 v21, 0x41800000, v21
	v_mul_f32_e32 v36, 0x41800000, v36
	v_fma_f32 v38, v20, v40, -v97
	v_fma_f32 v20, v20, v23, -v37
	v_med3_f32 v21, v21, s21, v62
	v_med3_f32 v36, v36, s21, v62
	v_mov_b32_e32 v37, 0
	v_cvt_pk_fp8_f32 v37, v21, v36
	v_mul_f32_e32 v38, 0x41800000, v38
	v_mul_f32_e32 v20, 0x41800000, v20
	v_med3_f32 v21, v38, s21, v62
	v_med3_f32 v20, v20, s21, v62
	v_cvt_pk_fp8_f32 v37, v21, v20 op_sel:[0,0,1]
	v_add_co_u32_e32 v20, vcc, s27, v24
	v_cndmask_b32_e64 v36, 0, 1.0, s[0:1]
	s_nop 0
	v_addc_co_u32_e32 v21, vcc, 0, v25, vcc
	global_store_dword v[20:21], v37, off offset:1024
	s_waitcnt vmcnt(15)
	v_lshlrev_b32_e32 v37, 16, v18
	v_and_b32_e32 v18, 0xffff0000, v18
	v_fma_f32 v18, v36, v18, -v65
	s_min_u32 s0, s49, s39
	v_add_f32_e32 v18, v18, v22
	v_lshlrev_b32_e32 v22, 16, v19
	v_and_b32_e32 v19, 0xffff0000, v19
	s_sub_i32 s0, s0, s48
	v_fma_f32 v19, v36, v19, -v63
	s_add_i32 s0, s0, 8
	v_add_f32_e32 v19, v19, v23
	v_cvt_f32_i32_e32 v23, s0
	v_fma_f32 v37, v36, v37, -v66
	v_fma_f32 v22, v36, v22, -v64
	v_add_f32_e32 v37, v37, v39
	v_div_scale_f32 v36, s[0:1], v23, v23, 1.0
	v_rcp_f32_e32 v38, v36
	v_add_f32_e32 v22, v22, v40
	s_cmp_lt_u32 s46, s2
	s_cselect_b64 s[0:1], -1, 0
	v_fma_f32 v39, -v36, v38, 1.0
	v_fmac_f32_e32 v38, v39, v38
	v_div_scale_f32 v39, vcc, 1.0, v23, 1.0
	v_mul_f32_e32 v40, v39, v38
	v_fma_f32 v41, -v36, v40, v39
	v_fmac_f32_e32 v40, v41, v38
	v_fma_f32 v36, -v36, v40, v39
	v_div_fmas_f32 v36, v36, v38, v40
	v_div_fixup_f32 v23, v36, v23, 1.0
	v_fma_f32 v36, v23, v37, -v95
	v_fma_f32 v34, v23, v18, -v34
	v_mul_f32_e32 v36, 0x41800000, v36
	v_mul_f32_e32 v34, 0x41800000, v34
	v_fma_f32 v38, v23, v22, -v93
	v_fma_f32 v23, v23, v19, -v35
	v_med3_f32 v35, v36, s21, v62
	v_med3_f32 v34, v34, s21, v62
	v_mov_b32_e32 v36, 0
	v_cvt_pk_fp8_f32 v36, v35, v34
	v_mul_f32_e32 v38, 0x41800000, v38
	v_mul_f32_e32 v23, 0x41800000, v23
	v_med3_f32 v34, v38, s21, v62
	v_med3_f32 v23, v23, s21, v62
	v_cvt_pk_fp8_f32 v36, v34, v23 op_sel:[0,0,1]
	global_store_dword v[20:21], v36, off offset:3072
	v_cndmask_b32_e64 v20, 0, 1.0, s[0:1]
	s_waitcnt vmcnt(15)
	v_lshlrev_b32_e32 v21, 16, v16
	v_and_b32_e32 v16, 0xffff0000, v16
	v_fma_f32 v16, v20, v16, -v60
	v_add_f32_e32 v18, v16, v18
	v_lshlrev_b32_e32 v16, 16, v17
	v_fma_f32 v16, v20, v16, -v55
	s_min_u32 s0, s47, s39
	v_add_f32_e32 v22, v16, v22
	v_and_b32_e32 v16, 0xffff0000, v17
	s_sub_i32 s0, s0, s46
	v_fma_f32 v16, v20, v16, -v54
	s_add_i32 s0, s0, 8
	v_add_f32_e32 v19, v16, v19
	v_cvt_f32_i32_e32 v16, s0
	v_fma_f32 v21, v20, v21, -v61
	v_add_f32_e32 v21, v21, v37
	s_cmp_lt_u32 s31, s2
	v_div_scale_f32 v17, s[0:1], v16, v16, 1.0
	v_rcp_f32_e32 v20, v17
	s_cselect_b64 s[0:1], -1, 0
	v_fma_f32 v23, -v17, v20, 1.0
	v_fmac_f32_e32 v20, v23, v20
	v_div_scale_f32 v23, vcc, 1.0, v16, 1.0
	v_mul_f32_e32 v34, v23, v20
	v_fma_f32 v35, -v17, v34, v23
	v_fmac_f32_e32 v34, v35, v20
	v_fma_f32 v17, -v17, v34, v23
	v_div_fmas_f32 v17, v17, v20, v34
	v_div_fixup_f32 v16, v17, v16, 1.0
	v_fma_f32 v17, v16, v21, -v91
	v_fma_f32 v20, v16, v18, -v32
	v_mul_f32_e32 v17, 0x41800000, v17
	v_mul_f32_e32 v20, 0x41800000, v20
	v_fma_f32 v23, v16, v22, -v89
	v_mul_f32_e32 v23, 0x41800000, v23
	v_med3_f32 v17, v17, s21, v62
	v_med3_f32 v20, v20, s21, v62
	v_mov_b32_e32 v32, 0
	v_cvt_pk_fp8_f32 v32, v17, v20
	v_med3_f32 v17, v23, s21, v62
	v_cndmask_b32_e64 v20, 0, 1.0, s[0:1]
	s_waitcnt vmcnt(14)
	v_lshlrev_b32_e32 v23, 16, v14
	v_and_b32_e32 v14, 0xffff0000, v14
	v_fma_f32 v14, v20, v14, -v52
	s_min_u32 s0, s45, s39
	v_add_f32_e32 v14, v14, v18
	v_lshlrev_b32_e32 v18, 16, v15
	v_and_b32_e32 v15, 0xffff0000, v15
	s_sub_i32 s0, s0, s31
	v_fma_f32 v15, v20, v15, -v50
	s_add_i32 s0, s0, 8
	v_fma_f32 v16, v16, v19, -v33
	v_add_f32_e32 v15, v15, v19
	v_cvt_f32_i32_e32 v19, s0
	v_fma_f32 v23, v20, v23, -v53
	v_fma_f32 v18, v20, v18, -v51
	v_mul_f32_e32 v16, 0x41800000, v16
	v_div_scale_f32 v20, s[0:1], v19, v19, 1.0
	v_add_f32_e32 v18, v18, v22
	v_rcp_f32_e32 v22, v20
	v_med3_f32 v16, v16, s21, v62
	v_cvt_pk_fp8_f32 v32, v17, v16 op_sel:[0,0,1]
	v_add_co_u32_e32 v16, vcc, s36, v24
	v_add_f32_e32 v21, v23, v21
	s_nop 0
	v_addc_co_u32_e32 v17, vcc, 0, v25, vcc
	v_fma_f32 v23, -v20, v22, 1.0
	v_fmac_f32_e32 v22, v23, v22
	v_div_scale_f32 v23, vcc, 1.0, v19, 1.0
	global_store_dword v[16:17], v32, off offset:1024
	v_mul_f32_e32 v32, v23, v22
	v_fma_f32 v33, -v20, v32, v23
	v_fmac_f32_e32 v32, v33, v22
	v_fma_f32 v20, -v20, v32, v23
	v_div_fmas_f32 v20, v20, v22, v32
	v_div_fixup_f32 v19, v20, v19, 1.0
	v_fma_f32 v20, v19, v21, -v87
	v_fma_f32 v22, v19, v14, -v30
	v_mul_f32_e32 v20, 0x41800000, v20
	v_mul_f32_e32 v22, 0x41800000, v22
	v_med3_f32 v20, v20, s21, v62
	v_med3_f32 v22, v22, s21, v62
	v_mov_b32_e32 v30, 0
	v_cvt_pk_fp8_f32 v30, v20, v22
	v_fma_f32 v23, v19, v18, -v85
	v_fma_f32 v19, v19, v15, -v31
	v_mul_f32_e32 v23, 0x41800000, v23
	v_mul_f32_e32 v19, 0x41800000, v19
	v_med3_f32 v20, v23, s21, v62
	v_med3_f32 v19, v19, s21, v62
	v_cvt_pk_fp8_f32 v30, v20, v19 op_sel:[0,0,1]
	s_cmp_lt_u32 s28, s2
	s_cselect_b64 s[0:1], -1, 0
	global_store_dword v[16:17], v30, off offset:3072
	v_cndmask_b32_e64 v16, 0, 1.0, s[0:1]
	s_waitcnt vmcnt(15)
	v_lshlrev_b32_e32 v17, 16, v12
	v_and_b32_e32 v12, 0xffff0000, v12
	v_fma_f32 v12, v16, v12, -v48
	v_add_f32_e32 v14, v12, v14
	v_lshlrev_b32_e32 v12, 16, v13
	v_fma_f32 v12, v16, v12, -v47
	s_min_u32 s0, s29, s39
	v_add_f32_e32 v18, v12, v18
	v_and_b32_e32 v12, 0xffff0000, v13
	s_sub_i32 s0, s0, s28
	v_fma_f32 v12, v16, v12, -v46
	s_add_i32 s0, s0, 8
	v_add_f32_e32 v15, v12, v15
	v_cvt_f32_i32_e32 v12, s0
	v_fma_f32 v17, v16, v17, -v49
	v_add_f32_e32 v17, v17, v21
	s_cmp_lt_u32 s5, s2
	v_div_scale_f32 v13, s[0:1], v12, v12, 1.0
	v_rcp_f32_e32 v16, v13
	s_cselect_b64 s[0:1], -1, 0
	s_add_i32 s4, s4, 23
	s_add_i32 s3, s3, 16
	v_fma_f32 v19, -v13, v16, 1.0
	v_fmac_f32_e32 v16, v19, v16
	v_div_scale_f32 v19, vcc, 1.0, v12, 1.0
	v_mul_f32_e32 v20, v19, v16
	v_fma_f32 v21, -v13, v20, v19
	v_fmac_f32_e32 v20, v21, v16
	v_fma_f32 v13, -v13, v20, v19
	v_div_fmas_f32 v13, v13, v16, v20
	v_div_fixup_f32 v12, v13, v12, 1.0
	v_fma_f32 v13, v12, v17, -v83
	v_fma_f32 v16, v12, v14, -v28
	v_mul_f32_e32 v13, 0x41800000, v13
	v_mul_f32_e32 v16, 0x41800000, v16
	v_fma_f32 v19, v12, v18, -v81
	v_mul_f32_e32 v19, 0x41800000, v19
	v_med3_f32 v13, v13, s21, v62
	v_med3_f32 v16, v16, s21, v62
	v_mov_b32_e32 v20, 0
	v_cvt_pk_fp8_f32 v20, v13, v16
	v_med3_f32 v13, v19, s21, v62
	v_cndmask_b32_e64 v16, 0, 1.0, s[0:1]
	s_waitcnt vmcnt(14)
	v_and_b32_e32 v19, 0xffff0000, v11
	v_lshlrev_b32_e32 v11, 16, v11
	s_min_u32 s0, s4, s39
	v_fma_f32 v11, v16, v11, -v44
	s_sub_i32 s0, s0, s5
	v_add_f32_e32 v11, v11, v18
	v_and_b32_e32 v18, 0xffff0000, v10
	v_lshlrev_b32_e32 v10, 16, v10
	s_add_i32 s0, s0, 8
	v_fma_f32 v19, v16, v19, -v45
	v_fma_f32 v18, v16, v18, -v43
	v_fma_f32 v10, v16, v10, -v42
	v_cvt_f32_i32_e32 v16, s0
	v_fma_f32 v12, v12, v15, -v29
	v_add_f32_e32 v10, v10, v17
	v_mul_f32_e32 v12, 0x41800000, v12
	v_div_scale_f32 v17, s[0:1], v16, v16, 1.0
	v_add_f32_e32 v14, v18, v14
	v_rcp_f32_e32 v18, v17
	v_med3_f32 v12, v12, s21, v62
	v_cvt_pk_fp8_f32 v20, v13, v12 op_sel:[0,0,1]
	v_add_co_u32_e32 v12, vcc, s37, v24
	v_add_f32_e32 v15, v19, v15
	s_nop 0
	v_addc_co_u32_e32 v13, vcc, 0, v25, vcc
	v_fma_f32 v19, -v17, v18, 1.0
	v_fmac_f32_e32 v18, v19, v18
	v_div_scale_f32 v19, vcc, 1.0, v16, 1.0
	global_store_dword v[12:13], v20, off offset:1024
	v_mul_f32_e32 v20, v19, v18
	v_fma_f32 v21, -v17, v20, v19
	v_fmac_f32_e32 v20, v21, v18
	v_fma_f32 v17, -v17, v20, v19
	v_div_fmas_f32 v17, v17, v18, v20
	v_div_fixup_f32 v16, v17, v16, 1.0
	v_fma_f32 v10, v16, v10, -v56
	v_fma_f32 v14, v16, v14, -v26
	v_mul_f32_e32 v10, 0x41800000, v10
	v_mul_f32_e32 v14, 0x41800000, v14
	v_fma_f32 v11, v16, v11, -v57
	v_fma_f32 v15, v16, v15, -v27
	v_med3_f32 v10, v10, s21, v62
	v_med3_f32 v14, v14, s21, v62
	v_mov_b32_e32 v16, 0
	v_cvt_pk_fp8_f32 v16, v10, v14
	v_mul_f32_e32 v11, 0x41800000, v11
	v_mul_f32_e32 v15, 0x41800000, v15
	v_med3_f32 v10, v11, s21, v62
	v_med3_f32 v11, v15, s21, v62
	v_cvt_pk_fp8_f32 v16, v10, v11 op_sel:[0,0,1]
	s_cmp_lg_u32 s3, 64
	global_store_dword v[12:13], v16, off offset:3072
	s_cbranch_scc1 .LBB0_496
	s_mov_b64 s[0:1], 0

.LBB0_500:
	s_add_i32 s68, s38, s3
	s_and_b32 s4, s68, s40
	s_add_i32 s67, s4, -4
	s_max_i32 s0, s67, 0
	s_min_u32 s0, s0, s40
	s_sub_i32 s0, s0, s4
	s_add_i32 s0, s68, s0
	v_mad_i64_i32 v[10:11], s[0:1], s0, v1, v[2:3]
	s_add_i32 s66, s4, -3
	s_max_i32 s0, s66, 0
	s_min_u32 s0, s0, s40
	s_sub_i32 s0, s0, s4
	s_add_i32 s0, s68, s0
	global_load_dwordx2 v[20:21], v[10:11], off nt
	v_mad_i64_i32 v[10:11], s[0:1], s0, v1, v[2:3]
	s_add_i32 s65, s4, -2
	s_max_i32 s0, s65, 0
	s_min_u32 s0, s0, s40
	s_sub_i32 s0, s0, s4
	s_add_i32 s0, s68, s0
	global_load_dwordx2 v[42:43], v[10:11], off nt
	v_mad_i64_i32 v[10:11], s[0:1], s0, v1, v[2:3]
	v_sub_co_u32_e64 v50, s[0:1], s4, 1
	s_nop 0
	v_readfirstlane_b32 s5, v50
	s_max_i32 s5, s5, 0
	s_min_u32 s5, s5, s40
	s_sub_i32 s5, s5, s4
	s_add_i32 s5, s68, s5
	s_or_b32 s64, s4, 1
	global_load_dwordx2 v[44:45], v[10:11], off nt
	v_mad_i64_i32 v[10:11], s[28:29], s5, v1, v[2:3]
	s_min_u32 s5, s64, s40
	s_sub_i32 s5, s5, s4
	global_load_dwordx2 v[46:47], v[10:11], off nt
	v_lshl_add_u64 v[10:11], s[74:75], 0, v[8:9]
	s_add_i32 s5, s68, s5
	s_or_b32 s63, s4, 2
	global_load_dwordx2 v[48:49], v[10:11], off nt
	v_mad_i64_i32 v[10:11], s[28:29], s5, v1, v[2:3]
	s_min_u32 s5, s63, s40
	s_sub_i32 s5, s5, s4
	s_add_i32 s5, s68, s5
	s_or_b32 s62, s4, 3
	global_load_dwordx2 v[80:81], v[10:11], off nt
	v_mad_i64_i32 v[10:11], s[28:29], s5, v1, v[2:3]
	s_min_u32 s5, s62, s40
	s_sub_i32 s5, s5, s4
	s_add_i32 s5, s68, s5
	global_load_dwordx2 v[82:83], v[10:11], off nt
	v_mad_i64_i32 v[10:11], s[28:29], s5, v1, v[2:3]
	global_load_dwordx2 v[84:85], v[10:11], off nt
	s_or_b32 s61, s4, 4
	s_min_u32 s5, s61, s40
	s_sub_i32 s5, s5, s4
	s_add_i32 s5, s68, s5
	s_or_b32 s60, s4, 5
	v_mad_i64_i32 v[10:11], s[28:29], s5, v1, v[2:3]
	s_min_u32 s5, s60, s40
	s_sub_i32 s5, s5, s4
	s_add_i32 s5, s68, s5
	s_or_b32 s59, s4, 6
	global_load_dwordx2 v[40:41], v[10:11], off nt
	v_mad_i64_i32 v[10:11], s[28:29], s5, v1, v[2:3]
	s_min_u32 s5, s59, s40
	s_sub_i32 s5, s5, s4
	s_add_i32 s5, s68, s5
	s_or_b32 s58, s4, 7
	global_load_dwordx2 v[38:39], v[10:11], off nt
	v_mad_i64_i32 v[10:11], s[28:29], s5, v1, v[2:3]
	s_min_u32 s5, s58, s40
	s_sub_i32 s5, s5, s4
	s_add_i32 s5, s68, s5
	s_or_b32 s57, s4, 8
	global_load_dwordx2 v[36:37], v[10:11], off nt
	v_mad_i64_i32 v[10:11], s[28:29], s5, v1, v[2:3]
	s_min_u32 s5, s57, s40
	s_sub_i32 s5, s5, s4
	s_add_i32 s5, s68, s5
	s_or_b32 s56, s4, 9
	global_load_dwordx2 v[34:35], v[10:11], off nt
	v_mad_i64_i32 v[10:11], s[28:29], s5, v1, v[2:3]
	s_min_u32 s5, s56, s40
	s_sub_i32 s5, s5, s4
	s_add_i32 s5, s68, s5
	s_or_b32 s49, s4, 10
	global_load_dwordx2 v[32:33], v[10:11], off nt
	v_mad_i64_i32 v[10:11], s[28:29], s5, v1, v[2:3]
	s_min_u32 s5, s49, s40
	s_sub_i32 s5, s5, s4
	s_add_i32 s5, s68, s5
	s_or_b32 s48, s4, 11
	global_load_dwordx2 v[30:31], v[10:11], off nt
	v_mad_i64_i32 v[10:11], s[28:29], s5, v1, v[2:3]
	s_min_u32 s5, s48, s40
	s_sub_i32 s5, s5, s4
	s_add_i32 s5, s68, s5
	s_or_b32 s46, s4, 12
	global_load_dwordx2 v[28:29], v[10:11], off nt
	v_mad_i64_i32 v[10:11], s[28:29], s5, v1, v[2:3]
	s_min_u32 s5, s46, s40
	s_sub_i32 s5, s5, s4
	s_add_i32 s5, s68, s5
	s_or_b32 s31, s4, 13
	global_load_dwordx2 v[26:27], v[10:11], off nt
	v_mad_i64_i32 v[10:11], s[28:29], s5, v1, v[2:3]
	s_min_u32 s5, s31, s40
	s_sub_i32 s5, s5, s4
	s_add_i32 s5, s68, s5
	global_load_dwordx2 v[24:25], v[10:11], off nt
	v_mad_i64_i32 v[10:11], s[28:29], s5, v1, v[2:3]
	s_or_b32 s28, s4, 14
	s_min_u32 s5, s28, s40
	s_sub_i32 s5, s5, s4
	s_add_i32 s5, s68, s5
	global_load_dwordx2 v[22:23], v[10:11], off nt
	v_mad_i64_i32 v[10:11], s[70:71], s5, v1, v[2:3]
	s_or_b32 s5, s4, 15
	s_min_u32 s29, s5, s40
	s_sub_i32 s29, s29, s4
	s_add_i32 s29, s68, s29
	s_add_i32 s47, s4, 16
	global_load_dwordx2 v[18:19], v[10:11], off nt
	v_mad_i64_i32 v[10:11], s[70:71], s29, v1, v[2:3]
	s_min_u32 s29, s47, s40
	s_sub_i32 s29, s29, s4
	s_add_i32 s29, s68, s29
	s_add_i32 s45, s4, 17
	s_waitcnt lgkmcnt(0)
	global_load_dwordx2 v[16:17], v[10:11], off nt
	v_mad_i64_i32 v[10:11], s[70:71], s29, v1, v[2:3]
	s_min_u32 s29, s45, s40
	s_sub_i32 s29, s29, s4
	s_add_i32 s29, s68, s29
	global_load_dwordx2 v[14:15], v[10:11], off nt
	v_mad_i64_i32 v[10:11], s[70:71], s29, v1, v[2:3]
	s_add_i32 s29, s4, 18
	s_min_u32 s50, s29, s40
	s_sub_i32 s50, s50, s4
	s_add_i32 s68, s68, s50
	global_load_dwordx2 v[12:13], v[10:11], off nt
	v_mad_i64_i32 v[10:11], s[68:69], s68, v1, v[2:3]
	s_cmp_lt_u32 s67, s39
	s_cselect_b64 s[68:69], -1, 0
	s_cmp_lt_u32 s66, s39
	v_cndmask_b32_e64 v51, 0, 1.0, s[68:69]
	s_waitcnt vmcnt(21)
	v_lshlrev_b32_e32 v75, 16, v20
	v_and_b32_e32 v59, 0xffff0000, v20
	v_lshlrev_b32_e32 v74, 16, v21
	v_and_b32_e32 v60, 0xffff0000, v21
	s_cselect_b64 s[66:67], -1, 0
	s_cmp_lt_u32 s65, s39
	v_fma_f32 v52, v51, v75, 0
	v_fma_f32 v20, v51, v59, 0
	v_fma_f32 v53, v51, v74, 0
	v_fma_f32 v21, v51, v60, 0
	v_cndmask_b32_e64 v51, 0, 1.0, s[66:67]
	s_waitcnt vmcnt(20)
	v_lshlrev_b32_e32 v73, 16, v42
	v_and_b32_e32 v61, 0xffff0000, v42
	v_lshlrev_b32_e32 v72, 16, v43
	v_and_b32_e32 v63, 0xffff0000, v43
	s_cselect_b64 s[66:67], -1, 0
	v_fmac_f32_e32 v52, v51, v73
	v_fmac_f32_e32 v20, v51, v61
	v_fmac_f32_e32 v53, v51, v72
	v_fmac_f32_e32 v21, v51, v63
	v_cndmask_b32_e64 v42, 0, 1.0, s[66:67]
	s_waitcnt vmcnt(19)
	v_lshlrev_b32_e32 v71, 16, v44
	v_and_b32_e32 v64, 0xffff0000, v44
	v_lshlrev_b32_e32 v70, 16, v45
	v_and_b32_e32 v65, 0xffff0000, v45
	v_cmp_gt_u32_e32 vcc, s39, v50
	v_fmac_f32_e32 v52, v42, v71
	v_fmac_f32_e32 v20, v42, v64
	v_fmac_f32_e32 v53, v42, v70
	v_fmac_f32_e32 v21, v42, v65
	v_cndmask_b32_e64 v42, 0, 1.0, vcc
	s_waitcnt vmcnt(18)
	v_lshlrev_b32_e32 v69, 16, v46
	v_and_b32_e32 v66, 0xffff0000, v46
	v_lshlrev_b32_e32 v68, 16, v47
	v_and_b32_e32 v67, 0xffff0000, v47
	s_cmp_lt_u32 s64, s39
	v_fmac_f32_e32 v52, v42, v69
	v_fmac_f32_e32 v20, v42, v66
	v_fmac_f32_e32 v53, v42, v68
	v_fmac_f32_e32 v21, v42, v67
	s_waitcnt vmcnt(17)
	v_lshlrev_b32_e32 v57, 16, v48
	v_and_b32_e32 v56, 0xffff0000, v48
	v_lshlrev_b32_e32 v55, 16, v49
	v_and_b32_e32 v54, 0xffff0000, v49
	s_cselect_b64 s[66:67], -1, 0
	s_cmp_lt_u32 s63, s39
	v_add_f32_e32 v79, v52, v57
	v_add_f32_e32 v78, v20, v56
	v_add_f32_e32 v77, v53, v55
	v_add_f32_e32 v76, v21, v54
	v_cndmask_b32_e64 v20, 0, 1.0, s[66:67]
	s_waitcnt vmcnt(16)
	v_lshlrev_b32_e32 v53, 16, v80
	v_and_b32_e32 v52, 0xffff0000, v80
	v_lshlrev_b32_e32 v51, 16, v81
	v_and_b32_e32 v50, 0xffff0000, v81
	s_cselect_b64 s[66:67], -1, 0
	s_cmp_lt_u32 s62, s39
	v_fmac_f32_e32 v79, v20, v53
	v_fmac_f32_e32 v78, v20, v52
	v_fmac_f32_e32 v77, v20, v51
	v_fmac_f32_e32 v76, v20, v50
	v_cndmask_b32_e64 v20, 0, 1.0, s[66:67]
	s_waitcnt vmcnt(15)
	v_lshlrev_b32_e32 v49, 16, v82
	v_and_b32_e32 v48, 0xffff0000, v82
	v_lshlrev_b32_e32 v47, 16, v83
	v_and_b32_e32 v46, 0xffff0000, v83
	s_cselect_b64 s[66:67], -1, 0
	v_fmac_f32_e32 v79, v20, v49
	v_fmac_f32_e32 v78, v20, v48
	v_fmac_f32_e32 v77, v20, v47
	v_fmac_f32_e32 v76, v20, v46
	v_cndmask_b32_e64 v20, 0, 1.0, s[66:67]
	s_waitcnt vmcnt(14)
	v_lshlrev_b32_e32 v45, 16, v84
	v_and_b32_e32 v44, 0xffff0000, v84
	v_lshlrev_b32_e32 v43, 16, v85
	v_and_b32_e32 v42, 0xffff0000, v85
	v_fmac_f32_e32 v79, v20, v45
	v_fmac_f32_e32 v78, v20, v44
	v_fmac_f32_e32 v77, v20, v43
	v_fmac_f32_e32 v76, v20, v42
	s_min_u32 s50, s61, s39
	v_sub_u32_e64 v20, s4, 4 clamp
	v_sub_u32_e32 v20, s50, v20
	v_cvt_f32_i32_e32 v20, v20
	s_cmp_lt_u32 s64, s2
	global_load_dwordx2 v[10:11], v[10:11], off nt
	v_lshl_add_u64 v[8:9], v[8:9], 0, s[12:13]
	v_div_scale_f32 v21, s[66:67], v20, v20, 1.0
	v_rcp_f32_e32 v58, v21
	s_cselect_b64 s[66:67], -1, 0
	v_fma_f32 v80, -v21, v58, 1.0
	v_fmac_f32_e32 v58, v80, v58
	v_div_scale_f32 v80, vcc, 1.0, v20, 1.0
	v_mul_f32_e32 v81, v80, v58
	v_fma_f32 v82, -v21, v81, v80
	v_fmac_f32_e32 v81, v82, v58
	v_fma_f32 v21, -v21, v81, v80
	v_div_fmas_f32 v21, v21, v58, v81
	v_div_fixup_f32 v21, v21, v20, 1.0
	v_fma_f32 v20, v21, v79, -v57
	v_mul_f32_e32 v58, 0x41800000, v20
	v_fma_f32 v20, v21, v78, -v56
	v_mul_f32_e32 v80, 0x41800000, v20
	v_med3_f32 v58, v58, s21, v62
	v_med3_f32 v80, v80, s21, v62
	v_mov_b32_e32 v81, 0
	v_cvt_pk_fp8_f32 v81, v58, v80
	v_fma_f32 v20, v21, v77, -v55
	v_fma_f32 v21, v21, v76, -v54
	v_mul_f32_e32 v20, 0x41800000, v20
	v_mul_f32_e32 v21, 0x41800000, v21
	v_med3_f32 v20, v20, s21, v62
	v_med3_f32 v21, v21, s21, v62
	v_cvt_pk_fp8_f32 v81, v20, v21 op_sel:[0,0,1]
	v_lshl_add_u64 v[20:21], s[74:75], 0, v[6:7]
	v_add_co_u32_e32 v82, vcc, s22, v20
	v_cndmask_b32_e64 v80, 1.0, 0, s[0:1]
	s_nop 0
	v_addc_co_u32_e32 v83, vcc, 0, v21, vcc
	global_store_dword v[82:83], v81, off offset:1024
	v_cndmask_b32_e64 v81, 0, 1.0, s[66:67]
	s_waitcnt vmcnt(15)
	v_lshlrev_b32_e32 v58, 16, v40
	v_and_b32_e32 v40, 0xffff0000, v40
	v_mul_f32_e32 v59, v80, v59
	v_fma_f32 v59, v81, v40, -v59
	v_add_f32_e32 v78, v59, v78
	v_lshlrev_b32_e32 v59, 16, v41
	v_and_b32_e32 v41, 0xffff0000, v41
	v_mul_f32_e32 v60, v80, v60
	v_fma_f32 v60, v81, v41, -v60
	v_add_f32_e32 v76, v60, v76
	s_min_u32 s0, s60, s39
	v_sub_u32_e64 v60, s64, 4 clamp
	v_sub_u32_e32 v60, s0, v60
	v_cvt_f32_i32_e32 v60, v60
	v_mul_f32_e32 v74, v80, v74
	v_mul_f32_e32 v75, v80, v75
	v_fma_f32 v74, v81, v59, -v74
	v_fma_f32 v75, v81, v58, -v75
	v_add_f32_e32 v74, v74, v77
	v_div_scale_f32 v77, s[0:1], v60, v60, 1.0
	v_add_f32_e32 v75, v75, v79
	v_rcp_f32_e32 v79, v77
	s_cmp_lt_u32 s63, s2
	s_cselect_b64 s[0:1], -1, 0
	v_mul_f32_e32 v61, v80, v61
	v_fma_f32 v81, -v77, v79, 1.0
	v_fmac_f32_e32 v79, v81, v79
	v_div_scale_f32 v81, vcc, 1.0, v60, 1.0
	v_mul_f32_e32 v84, v81, v79
	v_fma_f32 v85, -v77, v84, v81
	v_fmac_f32_e32 v84, v85, v79
	v_fma_f32 v77, -v77, v84, v81
	v_div_fmas_f32 v77, v77, v79, v84
	v_div_fixup_f32 v60, v77, v60, 1.0
	v_fma_f32 v77, v60, v75, -v53
	v_fma_f32 v79, v60, v78, -v52
	v_mul_f32_e32 v77, 0x41800000, v77
	v_mul_f32_e32 v79, 0x41800000, v79
	v_med3_f32 v77, v77, s21, v62
	v_med3_f32 v79, v79, s21, v62
	v_mov_b32_e32 v84, 0
	v_cvt_pk_fp8_f32 v84, v77, v79
	v_fma_f32 v81, v60, v74, -v51
	v_fma_f32 v60, v60, v76, -v50
	v_mul_f32_e32 v81, 0x41800000, v81
	v_mul_f32_e32 v60, 0x41800000, v60
	v_med3_f32 v77, v81, s21, v62
	v_med3_f32 v60, v60, s21, v62
	v_cvt_pk_fp8_f32 v84, v77, v60 op_sel:[0,0,1]
	v_cndmask_b32_e64 v77, 0, 1.0, s[0:1]
	s_waitcnt vmcnt(14)
	v_lshlrev_b32_e32 v60, 16, v38
	v_and_b32_e32 v38, 0xffff0000, v38
	v_fma_f32 v61, v77, v38, -v61
	v_add_f32_e32 v78, v61, v78
	v_lshlrev_b32_e32 v61, 16, v39
	v_and_b32_e32 v39, 0xffff0000, v39
	v_mul_f32_e32 v63, v80, v63
	v_fma_f32 v63, v77, v39, -v63
	v_add_f32_e32 v76, v63, v76
	s_min_u32 s0, s59, s39
	v_sub_u32_e64 v63, s63, 4 clamp
	v_sub_u32_e32 v63, s0, v63
	v_cvt_f32_i32_e32 v63, v63
	v_mul_f32_e32 v72, v80, v72
	v_mul_f32_e32 v73, v80, v73
	v_fma_f32 v72, v77, v61, -v72
	v_fma_f32 v73, v77, v60, -v73
	v_add_f32_e32 v74, v72, v74
	v_div_scale_f32 v72, s[0:1], v63, v63, 1.0
	v_add_f32_e32 v75, v73, v75
	v_rcp_f32_e32 v73, v72
	s_cmp_lt_u32 s62, s2
	s_cselect_b64 s[0:1], -1, 0
	v_mul_f32_e32 v71, v80, v71
	v_fma_f32 v77, -v72, v73, 1.0
	v_fmac_f32_e32 v73, v77, v73
	v_div_scale_f32 v77, vcc, 1.0, v63, 1.0
	v_mul_f32_e32 v79, v77, v73
	v_fma_f32 v81, -v72, v79, v77
	v_fmac_f32_e32 v79, v81, v73
	v_fma_f32 v72, -v72, v79, v77
	v_div_fmas_f32 v72, v72, v73, v79
	v_div_fixup_f32 v63, v72, v63, 1.0
	v_fma_f32 v72, v63, v75, -v49
	v_fma_f32 v73, v63, v78, -v48
	v_mul_f32_e32 v72, 0x41800000, v72
	v_mul_f32_e32 v73, 0x41800000, v73
	v_med3_f32 v72, v72, s21, v62
	v_med3_f32 v73, v73, s21, v62
	v_mov_b32_e32 v79, 0
	v_cvt_pk_fp8_f32 v79, v72, v73
	v_fma_f32 v77, v63, v74, -v47
	v_fma_f32 v63, v63, v76, -v46
	v_mul_f32_e32 v77, 0x41800000, v77
	v_mul_f32_e32 v63, 0x41800000, v63
	v_med3_f32 v72, v77, s21, v62
	v_med3_f32 v63, v63, s21, v62
	v_cvt_pk_fp8_f32 v79, v72, v63 op_sel:[0,0,1]
	v_cndmask_b32_e64 v77, 0, 1.0, s[0:1]
	s_waitcnt vmcnt(13)
	v_lshlrev_b32_e32 v63, 16, v36
	v_and_b32_e32 v36, 0xffff0000, v36
	v_mul_f32_e32 v64, v80, v64
	v_fma_f32 v71, v77, v63, -v71
	v_fma_f32 v64, v77, v36, -v64
	v_add_f32_e32 v71, v71, v75
	v_add_f32_e32 v75, v64, v78
	v_lshlrev_b32_e32 v64, 16, v37
	v_mul_f32_e32 v70, v80, v70
	v_and_b32_e32 v37, 0xffff0000, v37
	v_mul_f32_e32 v65, v80, v65
	v_fma_f32 v70, v77, v64, -v70
	v_fma_f32 v65, v77, v37, -v65
	v_add_f32_e32 v70, v70, v74
	v_add_f32_e32 v74, v65, v76
	s_min_u32 s0, s58, s39
	v_sub_u32_e64 v65, s62, 4 clamp
	v_sub_u32_e32 v65, s0, v65
	v_cvt_f32_i32_e32 v65, v65
	v_add_co_u32_e32 v72, vcc, s23, v20
	s_cmp_lt_u32 s61, s2
	v_div_scale_f32 v76, s[0:1], v65, v65, 1.0
	v_rcp_f32_e32 v77, v76
	v_addc_co_u32_e32 v73, vcc, 0, v21, vcc
	global_store_dword v[72:73], v79, off offset:1024
	v_fma_f32 v78, -v76, v77, 1.0
	v_fmac_f32_e32 v77, v78, v77
	v_div_scale_f32 v78, vcc, 1.0, v65, 1.0
	v_mul_f32_e32 v79, v78, v77
	v_fma_f32 v81, -v76, v79, v78
	v_fmac_f32_e32 v79, v81, v77
	v_fma_f32 v76, -v76, v79, v78
	v_div_fmas_f32 v76, v76, v77, v79
	v_div_fixup_f32 v65, v76, v65, 1.0
	v_fma_f32 v76, v65, v71, -v45
	v_fma_f32 v77, v65, v75, -v44
	v_mul_f32_e32 v76, 0x41800000, v76
	v_mul_f32_e32 v77, 0x41800000, v77
	v_med3_f32 v76, v76, s21, v62
	v_med3_f32 v77, v77, s21, v62
	v_mov_b32_e32 v79, 0
	v_cvt_pk_fp8_f32 v79, v76, v77
	v_fma_f32 v78, v65, v70, -v43
	v_fma_f32 v65, v65, v74, -v42
	v_mul_f32_e32 v78, 0x41800000, v78
	v_mul_f32_e32 v65, 0x41800000, v65
	v_med3_f32 v76, v78, s21, v62
	v_med3_f32 v65, v65, s21, v62
	v_cvt_pk_fp8_f32 v79, v76, v65 op_sel:[0,0,1]
	s_cselect_b64 s[0:1], -1, 0
	s_waitcnt vmcnt(13)
	v_lshlrev_b32_e32 v65, 16, v34
	v_and_b32_e32 v34, 0xffff0000, v34
	global_store_dword v[72:73], v79, off offset:3072
	v_cndmask_b32_e64 v72, 0, 1.0, s[0:1]
	v_mul_f32_e32 v66, v80, v66
	v_fma_f32 v66, v72, v34, -v66
	s_min_u32 s0, s57, s39
	v_add_f32_e32 v73, v66, v75
	v_lshlrev_b32_e32 v66, 16, v35
	v_and_b32_e32 v35, 0xffff0000, v35
	v_mul_f32_e32 v67, v80, v67
	s_sub_i32 s0, s0, s61
	v_mul_f32_e32 v69, v80, v69
	v_mul_f32_e32 v68, v80, v68
	v_fma_f32 v67, v72, v35, -v67
	s_add_i32 s0, s0, 4
	v_fma_f32 v69, v72, v65, -v69
	v_fma_f32 v68, v72, v66, -v68
	v_add_f32_e32 v72, v67, v74
	v_cvt_f32_i32_e32 v67, s0
	v_add_f32_e32 v70, v68, v70
	v_add_f32_e32 v71, v69, v71
	s_cmp_lt_u32 s60, s2
	v_div_scale_f32 v68, s[0:1], v67, v67, 1.0
	v_rcp_f32_e32 v69, v68
	s_cselect_b64 s[0:1], -1, 0
	v_lshl_add_u64 v[6:7], v[6:7], 0, s[10:11]
	global_store_dword v[82:83], v84, off offset:3072
	v_fma_f32 v74, -v68, v69, 1.0
	v_fmac_f32_e32 v69, v74, v69
	v_div_scale_f32 v74, vcc, 1.0, v67, 1.0
	v_mul_f32_e32 v75, v74, v69
	v_fma_f32 v76, -v68, v75, v74
	v_fmac_f32_e32 v75, v76, v69
	v_fma_f32 v68, -v68, v75, v74
	v_div_fmas_f32 v68, v68, v69, v75
	v_div_fixup_f32 v67, v68, v67, 1.0
	v_fma_f32 v68, v67, v71, -v58
	v_fma_f32 v69, v67, v73, -v40
	v_mul_f32_e32 v68, 0x41800000, v68
	v_mul_f32_e32 v69, 0x41800000, v69
	v_med3_f32 v68, v68, s21, v62
	v_med3_f32 v69, v69, s21, v62
	v_mov_b32_e32 v75, 0
	v_cvt_pk_fp8_f32 v75, v68, v69
	v_fma_f32 v74, v67, v70, -v59
	v_fma_f32 v67, v67, v72, -v41
	v_mul_f32_e32 v74, 0x41800000, v74
	v_mul_f32_e32 v67, 0x41800000, v67
	v_med3_f32 v68, v74, s21, v62
	v_med3_f32 v67, v67, s21, v62
	v_cvt_pk_fp8_f32 v75, v68, v67 op_sel:[0,0,1]
	v_cndmask_b32_e64 v74, 0, 1.0, s[0:1]
	s_waitcnt vmcnt(14)
	v_lshlrev_b32_e32 v67, 16, v32
	v_and_b32_e32 v32, 0xffff0000, v32
	v_fma_f32 v57, v74, v67, -v57
	v_fma_f32 v56, v74, v32, -v56
	s_min_u32 s0, s56, s39
	v_add_f32_e32 v57, v57, v71
	v_add_f32_e32 v71, v56, v73
	v_lshlrev_b32_e32 v56, 16, v33
	v_and_b32_e32 v33, 0xffff0000, v33
	s_sub_i32 s0, s0, s60
	v_fma_f32 v55, v74, v56, -v55
	v_fma_f32 v54, v74, v33, -v54
	s_add_i32 s0, s0, 4
	v_add_f32_e32 v55, v55, v70
	v_add_f32_e32 v70, v54, v72
	v_cvt_f32_i32_e32 v54, s0
	v_add_co_u32_e32 v68, vcc, s24, v20
	s_cmp_lt_u32 s59, s2
	v_div_scale_f32 v72, s[0:1], v54, v54, 1.0
	v_rcp_f32_e32 v73, v72
	v_addc_co_u32_e32 v69, vcc, 0, v21, vcc
	global_store_dword v[68:69], v75, off offset:1024
	v_fma_f32 v74, -v72, v73, 1.0
	v_fmac_f32_e32 v73, v74, v73
	v_div_scale_f32 v74, vcc, 1.0, v54, 1.0
	v_mul_f32_e32 v75, v74, v73
	v_fma_f32 v76, -v72, v75, v74
	v_fmac_f32_e32 v75, v76, v73
	v_fma_f32 v72, -v72, v75, v74
	v_div_fmas_f32 v72, v72, v73, v75
	v_div_fixup_f32 v54, v72, v54, 1.0
	v_fma_f32 v72, v54, v57, -v60
	v_fma_f32 v73, v54, v71, -v38
	v_mul_f32_e32 v72, 0x41800000, v72
	v_mul_f32_e32 v73, 0x41800000, v73
	v_med3_f32 v72, v72, s21, v62
	v_med3_f32 v73, v73, s21, v62
	v_mov_b32_e32 v75, 0
	v_cvt_pk_fp8_f32 v75, v72, v73
	v_fma_f32 v74, v54, v55, -v61
	v_fma_f32 v54, v54, v70, -v39
	v_mul_f32_e32 v74, 0x41800000, v74
	v_mul_f32_e32 v54, 0x41800000, v54
	v_med3_f32 v72, v74, s21, v62
	v_med3_f32 v54, v54, s21, v62
	v_cvt_pk_fp8_f32 v75, v72, v54 op_sel:[0,0,1]
	s_cselect_b64 s[0:1], -1, 0
	s_waitcnt vmcnt(14)
	v_lshlrev_b32_e32 v54, 16, v30
	global_store_dword v[68:69], v75, off offset:3072
	v_cndmask_b32_e64 v68, 0, 1.0, s[0:1]
	v_fma_f32 v53, v68, v54, -v53
	v_add_f32_e32 v57, v53, v57
	v_and_b32_e32 v53, 0xffff0000, v30
	v_fma_f32 v30, v68, v53, -v52
	v_lshlrev_b32_e32 v52, 16, v31
	s_min_u32 s0, s49, s39
	v_add_f32_e32 v69, v30, v71
	v_fma_f32 v30, v68, v52, -v51
	v_and_b32_e32 v31, 0xffff0000, v31
	s_sub_i32 s0, s0, s59
	v_add_f32_e32 v55, v30, v55
	v_fma_f32 v30, v68, v31, -v50
	s_add_i32 s0, s0, 4
	v_add_f32_e32 v68, v30, v70
	v_cvt_f32_i32_e32 v30, s0
	s_cmp_lt_u32 s58, s2
	v_div_scale_f32 v50, s[0:1], v30, v30, 1.0
	v_rcp_f32_e32 v51, v50
	s_cselect_b64 s[0:1], -1, 0
	v_fma_f32 v70, -v50, v51, 1.0
	v_fmac_f32_e32 v51, v70, v51
	v_div_scale_f32 v70, vcc, 1.0, v30, 1.0
	v_mul_f32_e32 v71, v70, v51
	v_fma_f32 v72, -v50, v71, v70
	v_fmac_f32_e32 v71, v72, v51
	v_fma_f32 v50, -v50, v71, v70
	v_div_fmas_f32 v50, v50, v51, v71
	v_div_fixup_f32 v30, v50, v30, 1.0
	v_fma_f32 v50, v30, v57, -v63
	v_fma_f32 v51, v30, v69, -v36
	v_mul_f32_e32 v50, 0x41800000, v50
	v_mul_f32_e32 v51, 0x41800000, v51
	v_med3_f32 v50, v50, s21, v62
	v_med3_f32 v51, v51, s21, v62
	v_mov_b32_e32 v71, 0
	v_cvt_pk_fp8_f32 v71, v50, v51
	v_fma_f32 v70, v30, v55, -v64
	v_fma_f32 v30, v30, v68, -v37
	v_mul_f32_e32 v70, 0x41800000, v70
	v_mul_f32_e32 v30, 0x41800000, v30
	v_med3_f32 v50, v70, s21, v62
	v_med3_f32 v30, v30, s21, v62
	v_cvt_pk_fp8_f32 v71, v50, v30 op_sel:[0,0,1]
	v_cndmask_b32_e64 v70, 0, 1.0, s[0:1]
	s_waitcnt vmcnt(14)
	v_lshlrev_b32_e32 v30, 16, v28
	v_and_b32_e32 v28, 0xffff0000, v28
	v_fma_f32 v49, v70, v30, -v49
	v_fma_f32 v48, v70, v28, -v48
	s_min_u32 s0, s48, s39
	v_add_f32_e32 v49, v49, v57
	v_add_f32_e32 v57, v48, v69
	v_lshlrev_b32_e32 v48, 16, v29
	v_and_b32_e32 v29, 0xffff0000, v29
	s_sub_i32 s0, s0, s58
	v_fma_f32 v47, v70, v48, -v47
	v_fma_f32 v46, v70, v29, -v46
	s_add_i32 s0, s0, 4
	v_add_f32_e32 v47, v47, v55
	v_add_f32_e32 v55, v46, v68
	v_cvt_f32_i32_e32 v46, s0
	v_add_co_u32_e32 v50, vcc, s25, v20
	s_cmp_lt_u32 s57, s2
	v_div_scale_f32 v68, s[0:1], v46, v46, 1.0
	v_rcp_f32_e32 v69, v68
	v_addc_co_u32_e32 v51, vcc, 0, v21, vcc
	global_store_dword v[50:51], v71, off offset:1024
	v_fma_f32 v70, -v68, v69, 1.0
	v_fmac_f32_e32 v69, v70, v69
	v_div_scale_f32 v70, vcc, 1.0, v46, 1.0
	v_mul_f32_e32 v71, v70, v69
	v_fma_f32 v72, -v68, v71, v70
	v_fmac_f32_e32 v71, v72, v69
	v_fma_f32 v68, -v68, v71, v70
	v_div_fmas_f32 v68, v68, v69, v71
	v_div_fixup_f32 v46, v68, v46, 1.0
	v_fma_f32 v68, v46, v49, -v65
	v_fma_f32 v69, v46, v57, -v34
	v_mul_f32_e32 v68, 0x41800000, v68
	v_mul_f32_e32 v69, 0x41800000, v69
	v_med3_f32 v68, v68, s21, v62
	v_med3_f32 v69, v69, s21, v62
	v_mov_b32_e32 v71, 0
	v_cvt_pk_fp8_f32 v71, v68, v69
	v_fma_f32 v70, v46, v47, -v66
	v_fma_f32 v46, v46, v55, -v35
	v_mul_f32_e32 v70, 0x41800000, v70
	v_mul_f32_e32 v46, 0x41800000, v46
	v_med3_f32 v68, v70, s21, v62
	v_med3_f32 v46, v46, s21, v62
	v_cvt_pk_fp8_f32 v71, v68, v46 op_sel:[0,0,1]
	s_cselect_b64 s[0:1], -1, 0
	s_waitcnt vmcnt(14)
	v_lshlrev_b32_e32 v46, 16, v26
	global_store_dword v[50:51], v71, off offset:3072
	v_cndmask_b32_e64 v50, 0, 1.0, s[0:1]
	v_fma_f32 v45, v50, v46, -v45
	v_add_f32_e32 v49, v45, v49
	v_and_b32_e32 v45, 0xffff0000, v26
	v_fma_f32 v26, v50, v45, -v44
	v_lshlrev_b32_e32 v44, 16, v27
	s_min_u32 s0, s46, s39
	v_add_f32_e32 v57, v26, v57
	v_fma_f32 v26, v50, v44, -v43
	v_and_b32_e32 v43, 0xffff0000, v27
	s_sub_i32 s0, s0, s57
	v_add_f32_e32 v47, v26, v47
	v_fma_f32 v26, v50, v43, -v42
	s_add_i32 s0, s0, 4
	v_add_f32_e32 v42, v26, v55
	v_cvt_f32_i32_e32 v26, s0
	s_cmp_lt_u32 s56, s2
	v_div_scale_f32 v27, s[0:1], v26, v26, 1.0
	v_rcp_f32_e32 v50, v27
	s_cselect_b64 s[0:1], -1, 0
	v_fma_f32 v51, -v27, v50, 1.0
	v_fmac_f32_e32 v50, v51, v50
	v_div_scale_f32 v51, vcc, 1.0, v26, 1.0
	v_mul_f32_e32 v55, v51, v50
	v_fma_f32 v68, -v27, v55, v51
	v_fmac_f32_e32 v55, v68, v50
	v_fma_f32 v27, -v27, v55, v51
	v_div_fmas_f32 v27, v27, v50, v55
	v_div_fixup_f32 v26, v27, v26, 1.0
	v_fma_f32 v27, v26, v49, -v67
	v_fma_f32 v50, v26, v57, -v32
	v_mul_f32_e32 v27, 0x41800000, v27
	v_mul_f32_e32 v50, 0x41800000, v50
	v_med3_f32 v27, v27, s21, v62
	v_med3_f32 v50, v50, s21, v62
	v_mov_b32_e32 v55, 0
	v_cvt_pk_fp8_f32 v55, v27, v50
	v_fma_f32 v51, v26, v47, -v56
	v_fma_f32 v26, v26, v42, -v33
	v_mul_f32_e32 v51, 0x41800000, v51
	v_mul_f32_e32 v26, 0x41800000, v26
	v_med3_f32 v27, v51, s21, v62
	v_med3_f32 v26, v26, s21, v62
	v_cvt_pk_fp8_f32 v55, v27, v26 op_sel:[0,0,1]
	v_add_co_u32_e32 v50, vcc, s26, v20
	s_waitcnt vmcnt(14)
	v_lshlrev_b32_e32 v26, 16, v24
	v_addc_co_u32_e32 v51, vcc, 0, v21, vcc
	global_store_dword v[50:51], v55, off offset:1024
	v_cndmask_b32_e64 v55, 0, 1.0, s[0:1]
	v_fma_f32 v27, v55, v26, -v58
	v_and_b32_e32 v24, 0xffff0000, v24
	v_add_f32_e32 v49, v27, v49
	v_fma_f32 v27, v55, v24, -v40
	v_add_f32_e32 v57, v27, v57
	v_lshlrev_b32_e32 v27, 16, v25
	s_min_u32 s0, s31, s39
	v_fma_f32 v40, v55, v27, -v59
	v_and_b32_e32 v25, 0xffff0000, v25
	s_sub_i32 s0, s0, s56
	v_add_f32_e32 v47, v40, v47
	v_fma_f32 v40, v55, v25, -v41
	s_add_i32 s0, s0, 4
	v_add_f32_e32 v55, v40, v42
	v_cvt_f32_i32_e32 v40, s0
	s_cmp_lt_u32 s49, s2
	v_div_scale_f32 v41, s[0:1], v40, v40, 1.0
	v_rcp_f32_e32 v42, v41
	s_cselect_b64 s[0:1], -1, 0
	v_fma_f32 v58, -v41, v42, 1.0
	v_fmac_f32_e32 v42, v58, v42
	v_div_scale_f32 v58, vcc, 1.0, v40, 1.0
	v_mul_f32_e32 v59, v58, v42
	v_fma_f32 v68, -v41, v59, v58
	v_fmac_f32_e32 v59, v68, v42
	v_fma_f32 v41, -v41, v59, v58
	v_div_fmas_f32 v41, v41, v42, v59
	v_div_fixup_f32 v40, v41, v40, 1.0
	v_fma_f32 v41, v40, v49, -v54
	v_fma_f32 v42, v40, v57, -v53
	v_mul_f32_e32 v41, 0x41800000, v41
	v_mul_f32_e32 v42, 0x41800000, v42
	v_med3_f32 v41, v41, s21, v62
	v_med3_f32 v42, v42, s21, v62
	v_mov_b32_e32 v59, 0
	v_cvt_pk_fp8_f32 v59, v41, v42
	v_fma_f32 v58, v40, v47, -v52
	v_fma_f32 v40, v40, v55, -v31
	v_mul_f32_e32 v58, 0x41800000, v58
	v_mul_f32_e32 v40, 0x41800000, v40
	v_med3_f32 v41, v58, s21, v62
	v_med3_f32 v40, v40, s21, v62
	v_cvt_pk_fp8_f32 v59, v41, v40 op_sel:[0,0,1]
	s_waitcnt vmcnt(14)
	v_lshlrev_b32_e32 v40, 16, v22
	v_and_b32_e32 v42, 0xffff0000, v23
	global_store_dword v[50:51], v59, off offset:3072
	v_cndmask_b32_e64 v50, 0, 1.0, s[0:1]
	v_fma_f32 v41, v50, v40, -v60
	v_add_f32_e32 v49, v41, v49
	v_and_b32_e32 v41, 0xffff0000, v22
	v_fma_f32 v22, v50, v41, -v38
	v_lshlrev_b32_e32 v38, 16, v23
	s_min_u32 s0, s28, s39
	v_add_f32_e32 v57, v22, v57
	v_fma_f32 v22, v50, v38, -v61
	s_sub_i32 s0, s0, s49
	v_add_f32_e32 v47, v22, v47
	v_fma_f32 v22, v50, v42, -v39
	s_add_i32 s0, s0, 4
	v_add_f32_e32 v39, v22, v55
	v_cvt_f32_i32_e32 v22, s0
	s_cmp_lt_u32 s48, s2
	v_div_scale_f32 v23, s[0:1], v22, v22, 1.0
	v_rcp_f32_e32 v50, v23
	s_cselect_b64 s[0:1], -1, 0
	v_fma_f32 v51, -v23, v50, 1.0
	v_fmac_f32_e32 v50, v51, v50
	v_div_scale_f32 v51, vcc, 1.0, v22, 1.0
	v_mul_f32_e32 v55, v51, v50
	v_fma_f32 v58, -v23, v55, v51
	v_fmac_f32_e32 v55, v58, v50
	v_fma_f32 v23, -v23, v55, v51
	v_div_fmas_f32 v23, v23, v50, v55
	v_div_fixup_f32 v22, v23, v22, 1.0
	v_fma_f32 v23, v22, v49, -v30
	v_fma_f32 v50, v22, v57, -v28
	v_mul_f32_e32 v23, 0x41800000, v23
	v_mul_f32_e32 v50, 0x41800000, v50
	v_med3_f32 v23, v23, s21, v62
	v_med3_f32 v50, v50, s21, v62
	v_mov_b32_e32 v55, 0
	v_cvt_pk_fp8_f32 v55, v23, v50
	v_fma_f32 v51, v22, v47, -v48
	v_fma_f32 v22, v22, v39, -v29
	v_mul_f32_e32 v51, 0x41800000, v51
	v_mul_f32_e32 v22, 0x41800000, v22
	v_med3_f32 v23, v51, s21, v62
	v_med3_f32 v22, v22, s21, v62
	v_cvt_pk_fp8_f32 v55, v23, v22 op_sel:[0,0,1]
	v_add_co_u32_e32 v50, vcc, s27, v20
	s_waitcnt vmcnt(14)
	v_lshlrev_b32_e32 v22, 16, v18
	v_addc_co_u32_e32 v51, vcc, 0, v21, vcc
	global_store_dword v[50:51], v55, off offset:1024
	v_cndmask_b32_e64 v55, 0, 1.0, s[0:1]
	v_fma_f32 v23, v55, v22, -v63
	v_and_b32_e32 v18, 0xffff0000, v18
	v_add_f32_e32 v49, v23, v49
	v_fma_f32 v23, v55, v18, -v36
	v_add_f32_e32 v57, v23, v57
	v_lshlrev_b32_e32 v23, 16, v19
	s_min_u32 s0, s5, s39
	v_fma_f32 v36, v55, v23, -v64
	v_and_b32_e32 v19, 0xffff0000, v19
	s_sub_i32 s0, s0, s48
	v_add_f32_e32 v47, v36, v47
	v_fma_f32 v36, v55, v19, -v37
	s_add_i32 s0, s0, 4
	v_add_f32_e32 v37, v36, v39
	v_cvt_f32_i32_e32 v36, s0
	s_cmp_lt_u32 s46, s2
	v_div_scale_f32 v39, s[0:1], v36, v36, 1.0
	v_rcp_f32_e32 v55, v39
	s_cselect_b64 s[0:1], -1, 0
	v_fma_f32 v58, -v39, v55, 1.0
	v_fmac_f32_e32 v55, v58, v55
	v_div_scale_f32 v58, vcc, 1.0, v36, 1.0
	v_mul_f32_e32 v59, v58, v55
	v_fma_f32 v60, -v39, v59, v58
	v_fmac_f32_e32 v59, v60, v55
	v_fma_f32 v39, -v39, v59, v58
	v_div_fmas_f32 v39, v39, v55, v59
	v_div_fixup_f32 v36, v39, v36, 1.0
	v_fma_f32 v39, v36, v49, -v46
	v_fma_f32 v45, v36, v57, -v45
	v_mul_f32_e32 v39, 0x41800000, v39
	v_mul_f32_e32 v45, 0x41800000, v45
	v_fma_f32 v44, v36, v47, -v44
	v_fma_f32 v36, v36, v37, -v43
	v_med3_f32 v39, v39, s21, v62
	v_med3_f32 v43, v45, s21, v62
	v_mov_b32_e32 v45, 0
	v_cvt_pk_fp8_f32 v45, v39, v43
	v_mul_f32_e32 v44, 0x41800000, v44
	v_mul_f32_e32 v36, 0x41800000, v36
	v_med3_f32 v39, v44, s21, v62
	v_med3_f32 v36, v36, s21, v62
	v_cvt_pk_fp8_f32 v45, v39, v36 op_sel:[0,0,1]
	v_cndmask_b32_e64 v39, 0, 1.0, s[0:1]
	s_waitcnt vmcnt(14)
	v_lshlrev_b32_e32 v36, 16, v16
	v_and_b32_e32 v16, 0xffff0000, v16
	v_fma_f32 v34, v39, v16, -v34
	s_min_u32 s0, s47, s39
	v_add_f32_e32 v44, v34, v57
	v_lshlrev_b32_e32 v34, 16, v17
	v_and_b32_e32 v17, 0xffff0000, v17
	s_sub_i32 s0, s0, s46
	v_fma_f32 v35, v39, v17, -v35
	s_add_i32 s0, s0, 4
	v_add_f32_e32 v35, v35, v37
	v_cvt_f32_i32_e32 v37, s0
	global_store_dword v[50:51], v45, off offset:3072
	v_fma_f32 v43, v39, v36, -v65
	v_fma_f32 v45, v39, v34, -v66
	v_div_scale_f32 v39, s[0:1], v37, v37, 1.0
	v_rcp_f32_e32 v46, v39
	v_add_f32_e32 v45, v45, v47
	v_add_f32_e32 v43, v43, v49
	s_cmp_lt_u32 s31, s2
	v_fma_f32 v47, -v39, v46, 1.0
	v_fmac_f32_e32 v46, v47, v46
	v_div_scale_f32 v47, vcc, 1.0, v37, 1.0
	v_mul_f32_e32 v49, v47, v46
	v_fma_f32 v50, -v39, v49, v47
	v_fmac_f32_e32 v49, v50, v46
	v_fma_f32 v39, -v39, v49, v47
	v_div_fmas_f32 v39, v39, v46, v49
	v_div_fixup_f32 v37, v39, v37, 1.0
	v_fma_f32 v26, v37, v43, -v26
	v_fma_f32 v24, v37, v44, -v24
	v_mul_f32_e32 v26, 0x41800000, v26
	v_mul_f32_e32 v24, 0x41800000, v24
	v_fma_f32 v27, v37, v45, -v27
	v_fma_f32 v25, v37, v35, -v25
	v_med3_f32 v26, v26, s21, v62
	v_med3_f32 v24, v24, s21, v62
	v_mov_b32_e32 v37, 0
	s_cselect_b64 s[0:1], -1, 0
	v_mul_f32_e32 v27, 0x41800000, v27
	v_cvt_pk_fp8_f32 v37, v26, v24
	v_cndmask_b32_e64 v26, 0, 1.0, s[0:1]
	s_min_u32 s0, s45, s39
	v_med3_f32 v24, v27, s21, v62
	s_waitcnt vmcnt(14)
	v_lshlrev_b32_e32 v27, 16, v14
	v_and_b32_e32 v14, 0xffff0000, v14
	s_sub_i32 s0, s0, s31
	v_fma_f32 v14, v26, v14, -v32
	v_lshlrev_b32_e32 v32, 16, v15
	v_and_b32_e32 v15, 0xffff0000, v15
	s_add_i32 s0, s0, 4
	v_fma_f32 v27, v26, v27, -v67
	v_fma_f32 v32, v26, v32, -v56
	v_fma_f32 v15, v26, v15, -v33
	v_cvt_f32_i32_e32 v26, s0
	v_mul_f32_e32 v25, 0x41800000, v25
	v_med3_f32 v25, v25, s21, v62
	v_cvt_pk_fp8_f32 v37, v24, v25 op_sel:[0,0,1]
	v_div_scale_f32 v33, s[0:1], v26, v26, 1.0
	v_add_f32_e32 v15, v15, v35
	v_rcp_f32_e32 v35, v33
	v_add_co_u32_e32 v24, vcc, s36, v20
	v_add_f32_e32 v27, v27, v43
	s_nop 0
	v_addc_co_u32_e32 v25, vcc, 0, v21, vcc
	global_store_dword v[24:25], v37, off offset:1024
	v_fma_f32 v37, -v33, v35, 1.0
	v_fmac_f32_e32 v35, v37, v35
	v_div_scale_f32 v37, vcc, 1.0, v26, 1.0
	v_mul_f32_e32 v39, v37, v35
	v_fma_f32 v43, -v33, v39, v37
	v_fmac_f32_e32 v39, v43, v35
	v_fma_f32 v33, -v33, v39, v37
	v_div_fmas_f32 v33, v33, v35, v39
	v_add_f32_e32 v14, v14, v44
	v_div_fixup_f32 v26, v33, v26, 1.0
	v_fma_f32 v33, v26, v27, -v40
	v_fma_f32 v35, v26, v14, -v41
	v_add_f32_e32 v32, v32, v45
	v_mul_f32_e32 v33, 0x41800000, v33
	v_mul_f32_e32 v35, 0x41800000, v35
	v_fma_f32 v37, v26, v32, -v38
	v_med3_f32 v33, v33, s21, v62
	v_med3_f32 v35, v35, s21, v62
	v_mov_b32_e32 v38, 0
	v_cvt_pk_fp8_f32 v38, v33, v35
	v_fma_f32 v26, v26, v15, -v42
	v_mul_f32_e32 v37, 0x41800000, v37
	v_mul_f32_e32 v26, 0x41800000, v26
	v_med3_f32 v33, v37, s21, v62
	v_med3_f32 v26, v26, s21, v62
	v_cvt_pk_fp8_f32 v38, v33, v26 op_sel:[0,0,1]
	s_cmp_lt_u32 s28, s2
	s_cselect_b64 s[0:1], -1, 0
	global_store_dword v[24:25], v38, off offset:3072
	v_cndmask_b32_e64 v24, 0, 1.0, s[0:1]
	s_waitcnt vmcnt(15)
	v_lshlrev_b32_e32 v25, 16, v12
	v_and_b32_e32 v12, 0xffff0000, v12
	v_fma_f32 v12, v24, v12, -v53
	v_add_f32_e32 v14, v12, v14
	v_lshlrev_b32_e32 v12, 16, v13
	v_fma_f32 v12, v24, v12, -v52
	s_min_u32 s0, s29, s39
	v_add_f32_e32 v26, v12, v32
	v_and_b32_e32 v12, 0xffff0000, v13
	s_sub_i32 s0, s0, s28
	v_fma_f32 v12, v24, v12, -v31
	s_add_i32 s0, s0, 4
	v_add_f32_e32 v15, v12, v15
	v_cvt_f32_i32_e32 v12, s0
	v_fma_f32 v25, v24, v25, -v54
	v_add_f32_e32 v25, v25, v27
	s_cmp_lt_u32 s5, s2
	v_div_scale_f32 v13, s[0:1], v12, v12, 1.0
	v_rcp_f32_e32 v24, v13
	s_cselect_b64 s[0:1], -1, 0
	s_add_i32 s4, s4, 19
	s_add_i32 s3, s3, 16
	v_fma_f32 v27, -v13, v24, 1.0
	v_fmac_f32_e32 v24, v27, v24
	v_div_scale_f32 v27, vcc, 1.0, v12, 1.0
	v_mul_f32_e32 v31, v27, v24
	v_fma_f32 v32, -v13, v31, v27
	v_fmac_f32_e32 v31, v32, v24
	v_fma_f32 v13, -v13, v31, v27
	v_div_fmas_f32 v13, v13, v24, v31
	v_div_fixup_f32 v12, v13, v12, 1.0
	v_fma_f32 v13, v12, v25, -v22
	v_fma_f32 v18, v12, v14, -v18
	v_mul_f32_e32 v13, 0x41800000, v13
	v_mul_f32_e32 v18, 0x41800000, v18
	v_fma_f32 v22, v12, v26, -v23
	v_fma_f32 v12, v12, v15, -v19
	v_med3_f32 v13, v13, s21, v62
	v_med3_f32 v18, v18, s21, v62
	v_mov_b32_e32 v19, 0
	v_cvt_pk_fp8_f32 v19, v13, v18
	v_mul_f32_e32 v22, 0x41800000, v22
	v_mul_f32_e32 v12, 0x41800000, v12
	v_med3_f32 v13, v22, s21, v62
	v_med3_f32 v12, v12, s21, v62
	v_cvt_pk_fp8_f32 v19, v13, v12 op_sel:[0,0,1]
	v_add_co_u32_e32 v12, vcc, s37, v20
	v_cndmask_b32_e64 v18, 0, 1.0, s[0:1]
	s_nop 0
	v_addc_co_u32_e32 v13, vcc, 0, v21, vcc
	global_store_dword v[12:13], v19, off offset:1024
	s_waitcnt vmcnt(15)
	v_and_b32_e32 v19, 0xffff0000, v11
	s_min_u32 s0, s4, s39
	v_fma_f32 v19, v18, v19, -v29
	s_sub_i32 s0, s0, s5
	v_add_f32_e32 v15, v19, v15
	v_lshlrev_b32_e32 v11, 16, v11
	v_and_b32_e32 v19, 0xffff0000, v10
	v_lshlrev_b32_e32 v10, 16, v10
	s_add_i32 s0, s0, 4
	v_fma_f32 v11, v18, v11, -v48
	v_fma_f32 v19, v18, v19, -v28
	v_fma_f32 v10, v18, v10, -v30
	v_cvt_f32_i32_e32 v18, s0
	v_add_f32_e32 v14, v19, v14
	v_add_f32_e32 v10, v10, v25
	v_add_f32_e32 v11, v11, v26
	v_div_scale_f32 v19, s[0:1], v18, v18, 1.0
	v_rcp_f32_e32 v20, v19
	s_cmp_eq_u32 s3, 64
	v_fma_f32 v21, -v19, v20, 1.0
	v_fmac_f32_e32 v20, v21, v20
	v_div_scale_f32 v21, vcc, 1.0, v18, 1.0
	v_mul_f32_e32 v22, v21, v20
	v_fma_f32 v23, -v19, v22, v21
	v_fmac_f32_e32 v22, v23, v20
	v_fma_f32 v19, -v19, v22, v21
	v_div_fmas_f32 v19, v19, v20, v22
	v_div_fixup_f32 v18, v19, v18, 1.0
	v_fma_f32 v10, v18, v10, -v36
	v_fma_f32 v14, v18, v14, -v16
	v_mul_f32_e32 v10, 0x41800000, v10
	v_mul_f32_e32 v14, 0x41800000, v14
	v_med3_f32 v10, v10, s21, v62
	v_med3_f32 v14, v14, s21, v62
	v_mov_b32_e32 v16, 0
	v_cvt_pk_fp8_f32 v16, v10, v14
	v_fma_f32 v11, v18, v11, -v34
	v_fma_f32 v15, v18, v15, -v17
	v_mul_f32_e32 v11, 0x41800000, v11
	v_mul_f32_e32 v15, 0x41800000, v15
	v_med3_f32 v10, v11, s21, v62
	v_med3_f32 v11, v15, s21, v62
	v_cvt_pk_fp8_f32 v16, v10, v11 op_sel:[0,0,1]
	global_store_dword v[12:13], v16, off offset:3072
	s_cbranch_scc0 .LBB0_500

.LBB0_505:
	v_lshl_add_u64 v[14:15], s[74:75], 0, v[6:7]
	v_add_co_u32_e32 v26, vcc, s22, v14
	s_add_i32 s0, s38, s28
	s_nop 0
	v_addc_co_u32_e32 v27, vcc, 0, v15, vcc
	v_add_co_u32_e32 v24, vcc, s23, v14
	s_and_b32 s29, s0, s40
	s_nop 0
	v_addc_co_u32_e32 v25, vcc, 0, v15, vcc
	v_add_co_u32_e32 v22, vcc, s24, v14
	s_or_b32 s4, s29, 1
	s_nop 0
	v_addc_co_u32_e32 v23, vcc, 0, v15, vcc
	v_add_co_u32_e32 v20, vcc, s25, v14
	v_sub_co_u32_e64 v29, s[2:3], s29, 1
	s_nop 0
	v_addc_co_u32_e32 v21, vcc, 0, v15, vcc
	v_add_co_u32_e32 v18, vcc, s26, v14
	s_or_b32 s50, s29, 3
	s_nop 0
	v_addc_co_u32_e32 v19, vcc, 0, v15, vcc
	s_waitcnt lgkmcnt(0)
	v_add_co_u32_e32 v16, vcc, s27, v14
	s_or_b32 s59, s29, 5
	s_nop 0
	v_addc_co_u32_e32 v17, vcc, 0, v15, vcc
	v_add_co_u32_e32 v12, vcc, s36, v14
	s_or_b32 s62, s29, 6
	s_or_b32 s58, s29, 7
	s_or_b32 s57, s29, 8
	s_or_b32 s56, s29, 9
	s_or_b32 s49, s29, 10
	v_sub_u32_e64 v28, s29, 1 clamp
	v_readfirstlane_b32 s1, v29
	s_min_u32 s80, s4, s39
	v_addc_co_u32_e32 v13, vcc, 0, v15, vcc
	s_or_b32 s5, s29, 2
	s_or_b32 s51, s29, 4
	s_or_b32 s48, s29, 11
	s_or_b32 s47, s29, 12
	s_or_b32 s46, s29, 13
	s_or_b32 s45, s29, 14
	s_or_b32 s31, s29, 15
	v_cndmask_b32_e64 v77, 1.0, 0, s[2:3]
	s_min_u32 s2, s4, s40
	s_min_u32 s60, s50, s40
	s_min_u32 s63, s59, s40
	s_min_u32 s64, s62, s40
	s_min_u32 s65, s58, s40
	s_min_u32 s66, s57, s40
	s_min_u32 s67, s56, s40
	s_min_u32 s68, s49, s40
	s_max_i32 s1, s1, 0
	v_sub_u32_e32 v28, s80, v28
	v_add_co_u32_e32 v14, vcc, s37, v14
	s_min_u32 s3, s5, s40
	s_min_u32 s61, s51, s40
	s_min_u32 s69, s48, s40
	s_min_u32 s70, s47, s40
	s_min_u32 s71, s46, s40
	s_min_u32 s78, s45, s40
	s_min_u32 s79, s31, s40
	s_sub_i32 s2, s2, s29
	s_sub_i32 s60, s60, s29
	s_sub_i32 s63, s63, s29
	s_sub_i32 s64, s64, s29
	s_sub_i32 s65, s65, s29
	s_sub_i32 s66, s66, s29
	s_sub_i32 s67, s67, s29
	s_sub_i32 s68, s68, s29
	s_min_u32 s1, s1, s40
	v_cvt_f32_i32_e32 v91, v28
	v_addc_co_u32_e32 v15, vcc, 0, v15, vcc
	s_sub_i32 s3, s3, s29
	s_sub_i32 s61, s61, s29
	s_sub_i32 s69, s69, s29
	s_sub_i32 s70, s70, s29
	s_sub_i32 s71, s71, s29
	s_sub_i32 s78, s78, s29
	s_sub_i32 s79, s79, s29
	s_add_i32 s2, s0, s2
	s_add_i32 s60, s0, s60
	s_add_i32 s63, s0, s63
	s_add_i32 s64, s0, s64
	s_add_i32 s65, s0, s65
	s_add_i32 s66, s0, s66
	s_add_i32 s67, s0, s67
	s_add_i32 s68, s0, s68
	s_sub_i32 s1, s1, s29
	v_cmp_gt_u32_e32 vcc, s39, v29
	s_add_i32 s80, s0, s3
	s_add_i32 s61, s0, s61
	s_add_i32 s69, s0, s69
	s_add_i32 s70, s0, s70
	s_add_i32 s71, s0, s71
	s_add_i32 s78, s0, s78
	s_add_i32 s79, s0, s79
	v_mad_i64_i32 v[28:29], s[2:3], s2, v1, v[2:3]
	v_mad_i64_i32 v[30:31], s[2:3], s60, v1, v[2:3]
	v_mad_i64_i32 v[34:35], s[2:3], s63, v1, v[2:3]
	v_mad_i64_i32 v[36:37], s[2:3], s64, v1, v[2:3]
	v_mad_i64_i32 v[38:39], s[2:3], s65, v1, v[2:3]
	v_mad_i64_i32 v[40:41], s[2:3], s66, v1, v[2:3]
	v_mad_i64_i32 v[42:43], s[2:3], s67, v1, v[2:3]
	v_mad_i64_i32 v[44:45], s[2:3], s68, v1, v[2:3]
	s_add_i32 s0, s0, s1
	v_lshl_add_u64 v[10:11], s[74:75], 0, v[8:9]
	v_mad_i64_i32 v[78:79], s[2:3], s80, v1, v[2:3]
	v_mad_i64_i32 v[32:33], s[2:3], s61, v1, v[2:3]
	v_mad_i64_i32 v[80:81], s[2:3], s69, v1, v[2:3]
	v_mad_i64_i32 v[82:83], s[2:3], s70, v1, v[2:3]
	v_mad_i64_i32 v[84:85], s[2:3], s71, v1, v[2:3]
	v_mad_i64_i32 v[86:87], s[2:3], s78, v1, v[2:3]
	v_mad_i64_i32 v[88:89], s[2:3], s79, v1, v[2:3]
	global_load_dwordx2 v[58:59], v[30:31], off nt
	global_load_dwordx2 v[56:57], v[32:33], off nt
	global_load_dwordx2 v[54:55], v[34:35], off nt
	global_load_dwordx2 v[52:53], v[36:37], off nt
	global_load_dwordx2 v[50:51], v[38:39], off nt
	global_load_dwordx2 v[48:49], v[40:41], off nt
	global_load_dwordx2 v[46:47], v[42:43], off nt
	s_nop 0
	global_load_dwordx2 v[44:45], v[44:45], off nt
	s_nop 0
	global_load_dwordx2 v[42:43], v[80:81], off nt
	global_load_dwordx2 v[40:41], v[82:83], off nt
	global_load_dwordx2 v[38:39], v[84:85], off nt
	global_load_dwordx2 v[36:37], v[86:87], off nt
	global_load_dwordx2 v[34:35], v[88:89], off nt
	v_mad_i64_i32 v[30:31], s[0:1], s0, v1, v[2:3]
	s_cmp_lt_u32 s4, s39
	global_load_dwordx2 v[32:33], v[30:31], off nt
	s_nop 0
	global_load_dwordx2 v[30:31], v[10:11], off nt
	s_nop 0
	global_load_dwordx2 v[28:29], v[28:29], off nt
	s_nop 0
	global_load_dwordx2 v[10:11], v[78:79], off nt
	v_div_scale_f32 v78, s[0:1], v91, v91, 1.0
	s_cselect_b64 s[0:1], -1, 0
	s_nop 0
	v_cndmask_b32_e64 v80, 0, 1.0, s[0:1]
	s_min_u32 s0, s5, s39
	s_sub_i32 s0, s0, s4
	s_add_i32 s0, s0, 1
	s_cmp_lt_u32 s5, s39
	v_rcp_f32_e32 v81, v78
	v_cvt_f32_i32_e32 v82, s0
	s_cselect_b64 s[0:1], -1, 0
	v_cndmask_b32_e64 v83, 0, 1.0, s[0:1]
	s_min_u32 s0, s50, s39
	s_sub_i32 s0, s0, s5
	s_add_i32 s2, s0, 1
	v_fma_f32 v84, -v78, v81, 1.0
	s_cmp_lt_u32 s50, s39
	v_cndmask_b32_e64 v90, 0, 1.0, vcc
	v_div_scale_f32 v79, vcc, 1.0, v91, 1.0
	v_fmac_f32_e32 v81, v84, v81
	v_cvt_f32_i32_e32 v87, s2
	s_cselect_b64 s[2:3], -1, 0
	v_mul_f32_e32 v84, v79, v81
	v_cndmask_b32_e64 v92, 0, 1.0, s[2:3]
	s_min_u32 s2, s51, s39
	v_fma_f32 v88, -v78, v84, v79
	s_sub_i32 s2, s2, s50
	v_div_scale_f32 v85, s[0:1], v82, v82, 1.0
	v_fmac_f32_e32 v84, v88, v81
	s_add_i32 s4, s2, 1
	v_rcp_f32_e32 v89, v85
	v_fma_f32 v78, -v78, v84, v79
	s_cmp_lt_u32 s51, s39
	v_div_fmas_f32 v78, v78, v81, v84
	v_cvt_f32_i32_e32 v84, s4
	s_cselect_b64 s[4:5], -1, 0
	v_cndmask_b32_e64 v93, 0, 1.0, s[4:5]
	s_min_u32 s4, s59, s39
	v_div_scale_f32 v79, s[2:3], v87, v87, 1.0
	s_sub_i32 s4, s4, s51
	v_div_fixup_f32 v78, v78, v91, 1.0
	v_fma_f32 v88, -v85, v89, 1.0
	v_rcp_f32_e32 v91, v79
	s_add_i32 s50, s4, 1
	v_div_scale_f32 v86, s[0:1], 1.0, v82, 1.0
	v_fmac_f32_e32 v89, v88, v89
	s_cmp_lt_u32 s59, s39
	v_mul_f32_e32 v88, v86, v89
	v_cvt_f32_i32_e32 v97, s50
	s_cselect_b64 s[60:61], -1, 0
	s_min_u32 s50, s62, s39
	v_fma_f32 v94, -v85, v88, v86
	v_div_scale_f32 v95, s[4:5], v84, v84, 1.0
	s_sub_i32 s50, s50, s59
	v_fmac_f32_e32 v88, v94, v89
	v_fma_f32 v94, -v79, v91, 1.0
	v_rcp_f32_e32 v98, v95
	s_add_i32 s50, s50, 1
	v_div_scale_f32 v81, s[2:3], 1.0, v87, 1.0
	v_fma_f32 v85, -v85, v88, v86
	v_fmac_f32_e32 v91, v94, v91
	s_mov_b64 vcc, s[0:1]
	s_cmp_lt_u32 s62, s39
	v_cndmask_b32_e64 v99, 0, 1.0, s[60:61]
	v_div_fmas_f32 v85, v85, v89, v88
	v_mul_f32_e32 v86, v81, v91
	v_cvt_f32_i32_e32 v94, s50
	s_cselect_b64 s[60:61], -1, 0
	s_min_u32 s50, s58, s39
	v_div_fixup_f32 v82, v85, v82, 1.0
	v_fma_f32 v85, -v79, v86, v81
	v_div_scale_f32 v88, s[0:1], v97, v97, 1.0
	s_sub_i32 s50, s50, s62
	v_fmac_f32_e32 v86, v85, v91
	v_fma_f32 v85, -v95, v98, 1.0
	v_rcp_f32_e32 v100, v88
	s_add_i32 s50, s50, 1
	v_div_scale_f32 v96, s[4:5], 1.0, v84, 1.0
	v_fma_f32 v79, -v79, v86, v81
	v_fmac_f32_e32 v98, v85, v98
	s_mov_b64 vcc, s[2:3]
	s_cmp_lt_u32 s58, s39
	v_cndmask_b32_e64 v101, 0, 1.0, s[60:61]
	v_div_fmas_f32 v79, v79, v91, v86
	v_mul_f32_e32 v81, v96, v98
	v_cvt_f32_i32_e32 v91, s50
	s_cselect_b64 s[60:61], -1, 0
	s_min_u32 s50, s57, s39
	v_fma_f32 v85, -v95, v81, v96
	v_div_scale_f32 v86, s[2:3], v94, v94, 1.0
	s_sub_i32 s50, s50, s58
	v_fmac_f32_e32 v81, v85, v98
	v_fma_f32 v85, -v88, v100, 1.0
	v_rcp_f32_e32 v102, v86
	s_add_i32 s50, s50, 1
	v_div_scale_f32 v89, s[0:1], 1.0, v97, 1.0
	v_fma_f32 v95, -v95, v81, v96
	v_fmac_f32_e32 v100, v85, v100
	s_mov_b64 vcc, s[4:5]
	s_cmp_lt_u32 s57, s39
	v_div_fmas_f32 v81, v95, v98, v81
	v_mul_f32_e32 v85, v89, v100
	v_cvt_f32_i32_e32 v98, s50
	s_cselect_b64 s[58:59], -1, 0
	s_min_u32 s50, s56, s39
	v_div_fixup_f32 v81, v81, v84, 1.0
	v_fma_f32 v84, -v88, v85, v89
	v_div_scale_f32 v95, s[4:5], v91, v91, 1.0
	s_sub_i32 s50, s50, s57
	v_fmac_f32_e32 v85, v84, v100
	v_fma_f32 v84, -v86, v102, 1.0
	v_rcp_f32_e32 v104, v95
	s_add_i32 s50, s50, 1
	v_div_fixup_f32 v79, v79, v87, 1.0
	v_div_scale_f32 v87, s[2:3], 1.0, v94, 1.0
	v_fma_f32 v88, -v88, v85, v89
	v_fmac_f32_e32 v102, v84, v102
	s_mov_b64 vcc, s[0:1]
	s_cmp_lt_u32 s56, s39
	v_cndmask_b32_e64 v105, 0, 1.0, s[58:59]
	v_div_fmas_f32 v84, v88, v100, v85
	v_mul_f32_e32 v85, v87, v102
	v_cvt_f32_i32_e32 v100, s50
	s_cselect_b64 s[58:59], -1, 0
	s_min_u32 s50, s49, s39
	v_fma_f32 v88, -v86, v85, v87
	v_div_scale_f32 v89, s[0:1], v98, v98, 1.0
	s_sub_i32 s50, s50, s56
	v_fmac_f32_e32 v85, v88, v102
	v_fma_f32 v88, -v95, v104, 1.0
	v_rcp_f32_e32 v106, v89
	s_add_i32 s50, s50, 1
	v_div_scale_f32 v96, s[4:5], 1.0, v91, 1.0
	v_fma_f32 v86, -v86, v85, v87
	v_fmac_f32_e32 v104, v88, v104
	s_mov_b64 vcc, s[2:3]
	s_cmp_lt_u32 s49, s39
	v_div_fmas_f32 v85, v86, v102, v85
	v_mul_f32_e32 v86, v96, v104
	v_cvt_f32_i32_e32 v102, s50
	s_cselect_b64 s[56:57], -1, 0
	s_min_u32 s50, s48, s39
	v_fma_f32 v87, -v95, v86, v96
	v_div_scale_f32 v88, s[2:3], v100, v100, 1.0
	s_sub_i32 s49, s50, s49
	v_fmac_f32_e32 v86, v87, v104
	v_fma_f32 v87, -v89, v106, 1.0
	v_rcp_f32_e32 v108, v88
	s_add_i32 s49, s49, 1
	v_div_fixup_f32 v84, v84, v97, 1.0
	v_div_scale_f32 v97, s[0:1], 1.0, v98, 1.0
	v_fma_f32 v95, -v95, v86, v96
	v_fmac_f32_e32 v106, v87, v106
	s_mov_b64 vcc, s[4:5]
	s_cmp_lt_u32 s48, s39
	v_cndmask_b32_e64 v109, 0, 1.0, s[56:57]
	v_div_fmas_f32 v86, v95, v104, v86
	v_mul_f32_e32 v87, v97, v106
	v_cvt_f32_i32_e32 v104, s49
	s_cselect_b64 s[56:57], -1, 0
	s_min_u32 s49, s47, s39
	v_div_fixup_f32 v86, v86, v91, 1.0
	v_fma_f32 v91, -v89, v87, v97
	v_div_scale_f32 v95, s[4:5], v102, v102, 1.0
	s_sub_i32 s48, s49, s48
	v_fmac_f32_e32 v87, v91, v106
	v_fma_f32 v91, -v88, v108, 1.0
	v_rcp_f32_e32 v110, v95
	s_add_i32 s48, s48, 1
	v_div_fixup_f32 v85, v85, v94, 1.0
	v_div_scale_f32 v94, s[2:3], 1.0, v100, 1.0
	v_fma_f32 v89, -v89, v87, v97
	v_fmac_f32_e32 v108, v91, v108
	s_mov_b64 vcc, s[0:1]
	s_cmp_lt_u32 s47, s39
	v_div_fmas_f32 v87, v89, v106, v87
	v_mul_f32_e32 v89, v94, v108
	v_cvt_f32_i32_e32 v106, s48
	s_cselect_b64 s[48:49], -1, 0
	v_fma_f32 v91, -v88, v89, v94
	v_div_scale_f32 v97, s[0:1], v104, v104, 1.0
	v_cndmask_b32_e64 v113, 0, 1.0, s[48:49]
	s_min_u32 s48, s46, s39
	v_fmac_f32_e32 v89, v91, v108
	v_fma_f32 v91, -v95, v110, 1.0
	v_rcp_f32_e32 v112, v97
	s_sub_i32 s47, s48, s47
	v_div_scale_f32 v96, s[4:5], 1.0, v102, 1.0
	v_fma_f32 v88, -v88, v89, v94
	v_fmac_f32_e32 v110, v91, v110
	s_mov_b64 vcc, s[2:3]
	s_add_i32 s47, s47, 1
	v_div_fmas_f32 v88, v88, v108, v89
	v_mul_f32_e32 v89, v96, v110
	s_cmp_lt_u32 s46, s39
	v_fma_f32 v91, -v95, v89, v96
	v_div_scale_f32 v94, s[2:3], v106, v106, 1.0
	v_cvt_f32_i32_e32 v108, s47
	s_cselect_b64 s[48:49], -1, 0
	s_min_u32 s47, s45, s39
	v_fmac_f32_e32 v89, v91, v110
	v_fma_f32 v91, -v97, v112, 1.0
	v_rcp_f32_e32 v114, v94
	s_sub_i32 s46, s47, s46
	v_div_fixup_f32 v87, v87, v98, 1.0
	v_div_scale_f32 v98, s[0:1], 1.0, v104, 1.0
	v_fmac_f32_e32 v112, v91, v112
	s_add_i32 s46, s46, 1
	v_fma_f32 v95, -v95, v89, v96
	s_mov_b64 vcc, s[4:5]
	v_mul_f32_e32 v91, v98, v112
	s_cmp_lt_u32 s45, s39
	v_div_fmas_f32 v89, v95, v110, v89
	v_fma_f32 v95, -v97, v91, v98
	v_div_scale_f32 v96, s[4:5], v108, v108, 1.0
	v_cvt_f32_i32_e32 v110, s46
	s_cselect_b64 s[46:47], -1, 0
	v_fmac_f32_e32 v91, v95, v112
	v_fma_f32 v95, -v94, v114, 1.0
	v_rcp_f32_e32 v116, v96
	v_cndmask_b32_e64 v117, 0, 1.0, s[46:47]
	s_min_u32 s46, s31, s39
	v_div_fixup_f32 v88, v88, v100, 1.0
	v_div_scale_f32 v100, s[2:3], 1.0, v106, 1.0
	v_fmac_f32_e32 v114, v95, v114
	s_sub_i32 s45, s46, s45
	v_fma_f32 v97, -v97, v91, v98
	s_mov_b64 vcc, s[0:1]
	v_mul_f32_e32 v95, v100, v114
	s_add_i32 s45, s45, 1
	v_div_fmas_f32 v91, v97, v112, v91
	v_fma_f32 v97, -v94, v95, v100
	v_div_scale_f32 v98, s[0:1], v110, v110, 1.0
	v_cvt_f32_i32_e32 v112, s45
	s_cmp_lt_u32 s31, s39
	v_fmac_f32_e32 v95, v97, v114
	v_fma_f32 v97, -v96, v116, 1.0
	v_rcp_f32_e32 v118, v98
	s_cselect_b64 s[46:47], -1, 0
	s_add_i32 s29, s29, 16
	v_div_fixup_f32 v89, v89, v102, 1.0
	v_div_scale_f32 v102, s[4:5], 1.0, v108, 1.0
	v_fma_f32 v94, -v94, v95, v100
	v_fmac_f32_e32 v116, v97, v116
	s_min_u32 s29, s29, s39
	s_mov_b64 vcc, s[2:3]
	v_div_fmas_f32 v94, v94, v114, v95
	v_mul_f32_e32 v95, v102, v116
	s_sub_i32 s29, s29, s31
	v_fma_f32 v97, -v96, v95, v102
	v_div_scale_f32 v100, s[2:3], v112, v112, 1.0
	s_add_i32 s29, s29, 1
	v_fmac_f32_e32 v95, v97, v116
	v_fma_f32 v97, -v98, v118, 1.0
	v_rcp_f32_e32 v114, v100
	v_cvt_f32_i32_e32 v120, s29
	v_div_fixup_f32 v91, v91, v104, 1.0
	v_div_scale_f32 v104, s[0:1], 1.0, v110, 1.0
	v_fma_f32 v96, -v96, v95, v102
	v_fmac_f32_e32 v118, v97, v118
	s_mov_b64 vcc, s[4:5]
	v_div_fmas_f32 v95, v96, v116, v95
	v_mul_f32_e32 v96, v104, v118
	v_fma_f32 v97, -v98, v96, v104
	v_fmac_f32_e32 v96, v97, v118
	v_fma_f32 v97, -v100, v114, 1.0
	v_div_scale_f32 v102, s[4:5], v120, v120, 1.0
	v_fmac_f32_e32 v114, v97, v114
	v_rcp_f32_e32 v97, v102
	v_div_fixup_f32 v94, v94, v106, 1.0
	v_div_scale_f32 v106, s[2:3], 1.0, v112, 1.0
	v_fma_f32 v98, -v98, v96, v104
	s_mov_b64 vcc, s[0:1]
	v_div_fmas_f32 v96, v98, v118, v96
	v_mul_f32_e32 v98, v106, v114
	v_fma_f32 v104, -v100, v98, v106
	v_fmac_f32_e32 v98, v104, v114
	v_fma_f32 v104, -v102, v97, 1.0
	v_div_fixup_f32 v95, v95, v108, 1.0
	v_div_scale_f32 v108, s[4:5], 1.0, v120, 1.0
	v_fma_f32 v100, -v100, v98, v106
	s_mov_b64 vcc, s[2:3]
	v_fmac_f32_e32 v97, v104, v97
	v_div_fmas_f32 v98, v100, v114, v98
	v_mul_f32_e32 v100, v108, v97
	v_fma_f32 v104, -v102, v100, v108
	s_waitcnt vmcnt(3)
	v_lshlrev_b32_e32 v169, 16, v32
	v_and_b32_e32 v32, 0xffff0000, v32
	v_lshlrev_b32_e32 v170, 16, v33
	v_and_b32_e32 v33, 0xffff0000, v33
	v_fmac_f32_e32 v100, v104, v97
	s_waitcnt vmcnt(2)
	v_lshlrev_b32_e32 v171, 16, v30
	v_and_b32_e32 v30, 0xffff0000, v30
	v_lshlrev_b32_e32 v172, 16, v31
	v_and_b32_e32 v31, 0xffff0000, v31
	s_waitcnt vmcnt(1)
	v_lshlrev_b32_e32 v173, 16, v28
	v_and_b32_e32 v28, 0xffff0000, v28
	v_lshlrev_b32_e32 v174, 16, v29
	v_and_b32_e32 v29, 0xffff0000, v29
	v_fma_f32 v177, v90, v169, 0
	v_fma_f32 v178, v90, v32, 0
	v_fma_f32 v179, v90, v170, 0
	v_fma_f32 v90, v90, v33, 0
	v_mul_f32_e32 v169, v77, v169
	v_mul_f32_e32 v32, v77, v32
	v_mul_f32_e32 v170, v77, v170
	v_mul_f32_e32 v33, v77, v33
	v_fma_f32 v102, -v102, v100, v108
	s_mov_b64 vcc, s[4:5]
	s_waitcnt vmcnt(0)
	v_lshlrev_b32_e32 v175, 16, v10
	v_and_b32_e32 v10, 0xffff0000, v10
	v_lshlrev_b32_e32 v176, 16, v11
	v_and_b32_e32 v11, 0xffff0000, v11
	v_add_f32_e32 v177, v177, v171
	v_add_f32_e32 v178, v178, v30
	v_add_f32_e32 v179, v179, v172
	v_add_f32_e32 v90, v90, v31
	v_fma_f32 v169, v80, v173, -v169
	v_fma_f32 v32, v80, v28, -v32
	v_fma_f32 v170, v80, v174, -v170
	v_fma_f32 v33, v80, v29, -v33
	v_div_fmas_f32 v97, v102, v97, v100
	v_lshlrev_b32_e32 v100, 16, v58
	v_and_b32_e32 v58, 0xffff0000, v58
	v_lshlrev_b32_e32 v102, 16, v59
	v_and_b32_e32 v59, 0xffff0000, v59
	v_fma_f32 v77, v83, v175, -v171
	v_fma_f32 v180, v83, v10, -v30
	v_fma_f32 v181, v83, v176, -v172
	v_fma_f32 v83, v83, v11, -v31
	v_fma_f32 v80, v78, v177, -v171
	v_fma_f32 v30, v78, v178, -v30
	v_fma_f32 v171, v78, v179, -v172
	v_fma_f32 v31, v78, v90, -v31
	v_add_f32_e32 v78, v169, v177
	v_add_f32_e32 v32, v32, v178
	v_add_f32_e32 v169, v170, v179
	v_add_f32_e32 v33, v33, v90
	v_lshlrev_b32_e32 v104, 16, v56
	v_and_b32_e32 v56, 0xffff0000, v56
	v_lshlrev_b32_e32 v106, 16, v57
	v_and_b32_e32 v57, 0xffff0000, v57
	v_fma_f32 v182, v92, v100, -v173
	v_fma_f32 v183, v92, v58, -v28
	v_fma_f32 v184, v92, v102, -v174
	v_fma_f32 v92, v92, v59, -v29
	v_mul_f32_e32 v80, 0x41800000, v80
	v_mul_f32_e32 v30, 0x41800000, v30
	v_mul_f32_e32 v90, 0x41800000, v171
	v_fma_f32 v170, v82, v78, -v173
	v_fma_f32 v28, v82, v32, -v28
	v_fma_f32 v171, v82, v169, -v174
	v_fma_f32 v29, v82, v33, -v29
	v_add_f32_e32 v77, v77, v78
	v_add_f32_e32 v32, v180, v32
	v_add_f32_e32 v78, v181, v169
	v_add_f32_e32 v33, v83, v33
	v_mov_b32_e32 v60, 0
	v_div_fixup_f32 v96, v96, v110, 1.0
	v_lshlrev_b32_e32 v108, 16, v54
	v_and_b32_e32 v54, 0xffff0000, v54
	v_lshlrev_b32_e32 v110, 16, v55
	v_and_b32_e32 v55, 0xffff0000, v55
	v_fma_f32 v185, v93, v104, -v175
	v_fma_f32 v186, v93, v56, -v10
	v_fma_f32 v187, v93, v106, -v176
	v_fma_f32 v93, v93, v57, -v11
	v_med3_f32 v80, v80, s21, v62
	v_med3_f32 v30, v30, s21, v62
	v_med3_f32 v82, v90, s21, v62
	v_mul_f32_e32 v83, 0x41800000, v170
	v_mul_f32_e32 v28, 0x41800000, v28
	v_mul_f32_e32 v90, 0x41800000, v171
	v_fma_f32 v169, v79, v77, -v175
	v_fma_f32 v10, v79, v32, -v10
	v_fma_f32 v170, v79, v78, -v176
	v_fma_f32 v11, v79, v33, -v11
	v_add_f32_e32 v77, v182, v77
	v_add_f32_e32 v32, v183, v32
	v_add_f32_e32 v78, v184, v78
	v_add_f32_e32 v33, v92, v33
	v_mov_b32_e32 v61, 0
	v_div_fixup_f32 v98, v98, v112, 1.0
	v_lshlrev_b32_e32 v112, 16, v52
	v_and_b32_e32 v52, 0xffff0000, v52
	v_lshlrev_b32_e32 v114, 16, v53
	v_and_b32_e32 v53, 0xffff0000, v53
	v_fma_f32 v136, v99, v108, -v100
	v_fma_f32 v137, v99, v54, -v58
	v_fma_f32 v138, v99, v110, -v102
	v_fma_f32 v99, v99, v55, -v59
	v_cvt_pk_fp8_f32 v60, v80, v30
	v_med3_f32 v30, v83, s21, v62
	v_med3_f32 v28, v28, s21, v62
	v_med3_f32 v79, v90, s21, v62
	v_mul_f32_e32 v80, 0x41800000, v169
	v_mul_f32_e32 v10, 0x41800000, v10
	v_mul_f32_e32 v83, 0x41800000, v170
	v_fma_f32 v90, v81, v77, -v100
	v_fma_f32 v58, v81, v32, -v58
	v_fma_f32 v92, v81, v78, -v102
	v_fma_f32 v59, v81, v33, -v59
	v_add_f32_e32 v77, v185, v77
	v_add_f32_e32 v32, v186, v32
	v_add_f32_e32 v78, v187, v78
	v_add_f32_e32 v33, v93, v33
	v_mov_b32_e32 v63, 0
	v_cndmask_b32_e64 v103, 0, 1.0, s[60:61]
	v_lshlrev_b32_e32 v116, 16, v50
	v_and_b32_e32 v50, 0xffff0000, v50
	v_lshlrev_b32_e32 v118, 16, v51
	v_and_b32_e32 v51, 0xffff0000, v51
	v_fma_f32 v139, v101, v112, -v104
	v_fma_f32 v140, v101, v52, -v56
	v_fma_f32 v141, v101, v114, -v106
	v_fma_f32 v101, v101, v53, -v57
	v_cvt_pk_fp8_f32 v61, v30, v28
	v_med3_f32 v28, v80, s21, v62
	v_med3_f32 v10, v10, s21, v62
	v_med3_f32 v30, v83, s21, v62
	v_mul_f32_e32 v80, 0x41800000, v90
	v_mul_f32_e32 v58, 0x41800000, v58
	v_mul_f32_e32 v81, 0x41800000, v92
	v_fma_f32 v83, v84, v77, -v104
	v_fma_f32 v56, v84, v32, -v56
	v_fma_f32 v90, v84, v78, -v106
	v_fma_f32 v57, v84, v33, -v57
	v_add_f32_e32 v77, v136, v77
	v_add_f32_e32 v32, v137, v32
	v_add_f32_e32 v78, v138, v78
	v_add_f32_e32 v33, v99, v33
	v_mov_b32_e32 v64, 0
	v_div_fixup_f32 v97, v97, v120, 1.0
	v_lshlrev_b32_e32 v120, 16, v48
	v_and_b32_e32 v48, 0xffff0000, v48
	v_lshlrev_b32_e32 v121, 16, v49
	v_and_b32_e32 v49, 0xffff0000, v49
	v_fma_f32 v142, v103, v116, -v108
	v_fma_f32 v143, v103, v50, -v54
	v_fma_f32 v144, v103, v118, -v110
	v_fma_f32 v103, v103, v51, -v55
	v_mul_f32_e32 v31, 0x41800000, v31
	v_cvt_pk_fp8_f32 v63, v28, v10
	v_med3_f32 v10, v80, s21, v62
	v_med3_f32 v28, v58, s21, v62
	v_med3_f32 v58, v81, s21, v62
	v_mul_f32_e32 v80, 0x41800000, v83
	v_mul_f32_e32 v56, 0x41800000, v56
	v_mul_f32_e32 v81, 0x41800000, v90
	v_fma_f32 v83, v85, v77, -v108
	v_fma_f32 v54, v85, v32, -v54
	v_fma_f32 v84, v85, v78, -v110
	v_fma_f32 v55, v85, v33, -v55
	v_add_f32_e32 v77, v139, v77
	v_add_f32_e32 v32, v140, v32
	v_add_f32_e32 v78, v141, v78
	v_add_f32_e32 v33, v101, v33
	v_mov_b32_e32 v65, 0
	v_cndmask_b32_e64 v107, 0, 1.0, s[58:59]
	v_lshlrev_b32_e32 v122, 16, v46
	v_and_b32_e32 v46, 0xffff0000, v46
	v_lshlrev_b32_e32 v123, 16, v47
	v_and_b32_e32 v47, 0xffff0000, v47
	v_fma_f32 v145, v105, v120, -v112
	v_fma_f32 v146, v105, v48, -v52
	v_fma_f32 v147, v105, v121, -v114
	v_fma_f32 v105, v105, v49, -v53
	v_med3_f32 v31, v31, s21, v62
	v_mul_f32_e32 v29, 0x41800000, v29
	v_cvt_pk_fp8_f32 v64, v10, v28
	v_med3_f32 v10, v80, s21, v62
	v_med3_f32 v28, v56, s21, v62
	v_med3_f32 v56, v81, s21, v62
	v_mul_f32_e32 v80, 0x41800000, v83
	v_mul_f32_e32 v54, 0x41800000, v54
	v_mul_f32_e32 v81, 0x41800000, v84
	v_mul_f32_e32 v55, 0x41800000, v55
	v_fma_f32 v83, v86, v77, -v112
	v_fma_f32 v52, v86, v32, -v52
	v_fma_f32 v84, v86, v78, -v114
	v_fma_f32 v53, v86, v33, -v53
	v_add_f32_e32 v77, v142, v77
	v_add_f32_e32 v32, v143, v32
	v_add_f32_e32 v78, v144, v78
	v_add_f32_e32 v33, v103, v33
	v_mov_b32_e32 v66, 0
	v_lshlrev_b32_e32 v124, 16, v44
	v_and_b32_e32 v44, 0xffff0000, v44
	v_lshlrev_b32_e32 v125, 16, v45
	v_and_b32_e32 v45, 0xffff0000, v45
	v_fma_f32 v148, v107, v122, -v116
	v_fma_f32 v149, v107, v46, -v50
	v_fma_f32 v150, v107, v123, -v118
	v_fma_f32 v107, v107, v47, -v51
	v_med3_f32 v29, v29, s21, v62
	v_mul_f32_e32 v11, 0x41800000, v11
	v_cvt_pk_fp8_f32 v60, v82, v31 op_sel:[0,0,1]
	v_cvt_pk_fp8_f32 v65, v10, v28
	v_med3_f32 v10, v80, s21, v62
	v_med3_f32 v28, v54, s21, v62
	v_med3_f32 v31, v81, s21, v62
	v_med3_f32 v54, v55, s21, v62
	v_mul_f32_e32 v55, 0x41800000, v83
	v_mul_f32_e32 v52, 0x41800000, v52
	v_mul_f32_e32 v80, 0x41800000, v84
	v_mul_f32_e32 v53, 0x41800000, v53
	v_fma_f32 v81, v87, v77, -v116
	v_fma_f32 v50, v87, v32, -v50
	v_fma_f32 v82, v87, v78, -v118
	v_fma_f32 v51, v87, v33, -v51
	v_add_f32_e32 v77, v145, v77
	v_add_f32_e32 v32, v146, v32
	v_add_f32_e32 v78, v147, v78
	v_add_f32_e32 v33, v105, v33
	v_mov_b32_e32 v67, 0
	v_cndmask_b32_e64 v111, 0, 1.0, s[56:57]
	v_lshlrev_b32_e32 v126, 16, v42
	v_and_b32_e32 v42, 0xffff0000, v42
	v_lshlrev_b32_e32 v127, 16, v43
	v_and_b32_e32 v43, 0xffff0000, v43
	v_fma_f32 v151, v109, v124, -v120
	v_fma_f32 v152, v109, v44, -v48
	v_fma_f32 v153, v109, v125, -v121
	v_fma_f32 v109, v109, v45, -v49
	v_med3_f32 v11, v11, s21, v62
	v_mul_f32_e32 v59, 0x41800000, v59
	v_cvt_pk_fp8_f32 v61, v79, v29 op_sel:[0,0,1]
	v_cvt_pk_fp8_f32 v66, v10, v28
	v_med3_f32 v10, v55, s21, v62
	v_med3_f32 v28, v52, s21, v62
	v_med3_f32 v29, v80, s21, v62
	v_med3_f32 v52, v53, s21, v62
	v_mul_f32_e32 v53, 0x41800000, v81
	v_mul_f32_e32 v50, 0x41800000, v50
	v_mul_f32_e32 v55, 0x41800000, v82
	v_mul_f32_e32 v51, 0x41800000, v51
	v_fma_f32 v79, v88, v77, -v120
	v_fma_f32 v48, v88, v32, -v48
	v_fma_f32 v80, v88, v78, -v121
	v_fma_f32 v49, v88, v33, -v49
	v_add_f32_e32 v77, v148, v77
	v_add_f32_e32 v32, v149, v32
	v_add_f32_e32 v78, v150, v78
	v_add_f32_e32 v33, v107, v33
	v_mov_b32_e32 v68, 0
	v_lshlrev_b32_e32 v128, 16, v40
	v_and_b32_e32 v40, 0xffff0000, v40
	v_lshlrev_b32_e32 v129, 16, v41
	v_and_b32_e32 v41, 0xffff0000, v41
	v_fma_f32 v154, v111, v126, -v122
	v_fma_f32 v155, v111, v42, -v46
	v_fma_f32 v156, v111, v127, -v123
	v_fma_f32 v111, v111, v43, -v47
	v_med3_f32 v59, v59, s21, v62
	v_mul_f32_e32 v57, 0x41800000, v57
	v_cvt_pk_fp8_f32 v63, v30, v11 op_sel:[0,0,1]
	v_cvt_pk_fp8_f32 v67, v10, v28
	v_med3_f32 v10, v53, s21, v62
	v_med3_f32 v11, v50, s21, v62
	v_med3_f32 v28, v55, s21, v62
	v_med3_f32 v30, v51, s21, v62
	v_mul_f32_e32 v50, 0x41800000, v79
	v_mul_f32_e32 v48, 0x41800000, v48
	v_mul_f32_e32 v51, 0x41800000, v80
	v_fma_f32 v53, v89, v77, -v122
	v_fma_f32 v46, v89, v32, -v46
	v_fma_f32 v55, v89, v78, -v123
	v_fma_f32 v47, v89, v33, -v47
	v_add_f32_e32 v77, v151, v77
	v_add_f32_e32 v32, v152, v32
	v_add_f32_e32 v78, v153, v78
	v_add_f32_e32 v33, v109, v33
	v_mov_b32_e32 v69, 0
	v_cndmask_b32_e64 v115, 0, 1.0, s[48:49]
	v_lshlrev_b32_e32 v130, 16, v38
	v_and_b32_e32 v38, 0xffff0000, v38
	v_lshlrev_b32_e32 v131, 16, v39
	v_and_b32_e32 v39, 0xffff0000, v39
	v_fma_f32 v157, v113, v128, -v124
	v_fma_f32 v158, v113, v40, -v44
	v_fma_f32 v159, v113, v129, -v125
	v_fma_f32 v113, v113, v41, -v45
	v_med3_f32 v57, v57, s21, v62
	v_cvt_pk_fp8_f32 v64, v58, v59 op_sel:[0,0,1]
	v_cvt_pk_fp8_f32 v68, v10, v11
	v_med3_f32 v10, v50, s21, v62
	v_med3_f32 v11, v48, s21, v62
	v_med3_f32 v48, v51, s21, v62
	v_mul_f32_e32 v50, 0x41800000, v53
	v_mul_f32_e32 v46, 0x41800000, v46
	v_mul_f32_e32 v51, 0x41800000, v55
	v_fma_f32 v53, v91, v77, -v124
	v_fma_f32 v44, v91, v32, -v44
	v_fma_f32 v55, v91, v78, -v125
	v_fma_f32 v45, v91, v33, -v45
	v_add_f32_e32 v58, v154, v77
	v_add_f32_e32 v32, v155, v32
	v_add_f32_e32 v59, v156, v78
	v_add_f32_e32 v33, v111, v33
	v_mov_b32_e32 v70, 0
	v_lshlrev_b32_e32 v132, 16, v36
	v_and_b32_e32 v36, 0xffff0000, v36
	v_fma_f32 v160, v115, v130, -v126
	v_fma_f32 v161, v115, v38, -v42
	v_fma_f32 v162, v115, v131, -v127
	v_fma_f32 v115, v115, v39, -v43
	v_cvt_pk_fp8_f32 v65, v56, v57 op_sel:[0,0,1]
	v_cvt_pk_fp8_f32 v69, v10, v11
	v_med3_f32 v10, v50, s21, v62
	v_med3_f32 v11, v46, s21, v62
	v_med3_f32 v46, v51, s21, v62
	v_mul_f32_e32 v50, 0x41800000, v53
	v_mul_f32_e32 v44, 0x41800000, v44
	v_mul_f32_e32 v51, 0x41800000, v55
	v_mul_f32_e32 v45, 0x41800000, v45
	v_fma_f32 v53, v94, v58, -v126
	v_fma_f32 v42, v94, v32, -v42
	v_fma_f32 v55, v94, v59, -v127
	v_fma_f32 v43, v94, v33, -v43
	v_add_f32_e32 v56, v157, v58
	v_add_f32_e32 v32, v158, v32
	v_add_f32_e32 v57, v159, v59
	v_mov_b32_e32 v71, 0
	v_cndmask_b32_e64 v119, 0, 1.0, s[46:47]
	v_and_b32_e32 v134, 0xffff0000, v35
	v_lshlrev_b32_e32 v35, 16, v35
	v_and_b32_e32 v135, 0xffff0000, v34
	v_lshlrev_b32_e32 v34, 16, v34
	v_fma_f32 v163, v117, v132, -v128
	v_fma_f32 v164, v117, v36, -v40
	global_store_dword v[26:27], v60, off offset:1024
	global_store_dword v[26:27], v61, off offset:3072
	v_cvt_pk_fp8_f32 v66, v31, v54 op_sel:[0,0,1]
	v_cvt_pk_fp8_f32 v70, v10, v11
	v_med3_f32 v10, v50, s21, v62
	v_med3_f32 v11, v44, s21, v62
	v_med3_f32 v26, v51, s21, v62
	v_med3_f32 v27, v45, s21, v62
	v_mul_f32_e32 v31, 0x41800000, v53
	v_mul_f32_e32 v42, 0x41800000, v42
	v_mul_f32_e32 v44, 0x41800000, v55
	v_mul_f32_e32 v43, 0x41800000, v43
	v_fma_f32 v45, v95, v56, -v128
	v_fma_f32 v40, v95, v32, -v40
	v_fma_f32 v50, v95, v57, -v129
	v_add_f32_e32 v51, v160, v56
	v_add_f32_e32 v32, v161, v32
	v_add_f32_e32 v53, v162, v57
	v_mov_b32_e32 v72, 0
	v_fma_f32 v166, v119, v134, -v39
	v_fma_f32 v167, v119, v35, -v131
	v_fma_f32 v168, v119, v135, -v38
	v_fma_f32 v119, v119, v34, -v130
	v_cvt_pk_fp8_f32 v67, v29, v52 op_sel:[0,0,1]
	v_cvt_pk_fp8_f32 v71, v10, v11
	v_med3_f32 v10, v31, s21, v62
	v_med3_f32 v11, v42, s21, v62
	v_med3_f32 v29, v44, s21, v62
	v_med3_f32 v31, v43, s21, v62
	v_mul_f32_e32 v42, 0x41800000, v45
	v_mul_f32_e32 v40, 0x41800000, v40
	v_mul_f32_e32 v43, 0x41800000, v50
	v_fma_f32 v44, v96, v51, -v130
	v_fma_f32 v38, v96, v32, -v38
	v_fma_f32 v45, v96, v53, -v131
	v_add_f32_e32 v50, v163, v51
	v_add_f32_e32 v32, v164, v32
	v_mov_b32_e32 v73, 0
	global_store_dword v[24:25], v63, off offset:1024
	global_store_dword v[24:25], v64, off offset:3072
	v_cvt_pk_fp8_f32 v68, v28, v30 op_sel:[0,0,1]
	v_cvt_pk_fp8_f32 v72, v10, v11
	v_med3_f32 v10, v42, s21, v62
	v_med3_f32 v11, v40, s21, v62
	v_med3_f32 v24, v43, s21, v62
	v_mul_f32_e32 v28, 0x41800000, v44
	v_mul_f32_e32 v30, 0x41800000, v38
	v_mul_f32_e32 v38, 0x41800000, v45
	v_fma_f32 v40, v98, v50, -v132
	v_fma_f32 v36, v98, v32, -v36
	v_add_f32_e32 v32, v168, v32
	v_add_f32_e32 v43, v119, v50
	v_mov_b32_e32 v74, 0
	v_lshlrev_b32_e32 v133, 16, v37
	v_and_b32_e32 v37, 0xffff0000, v37
	v_add_f32_e32 v33, v113, v33
	v_cvt_pk_fp8_f32 v73, v10, v11
	v_med3_f32 v10, v28, s21, v62
	v_med3_f32 v11, v30, s21, v62
	v_med3_f32 v28, v38, s21, v62
	v_mul_f32_e32 v38, 0x41800000, v40
	v_mul_f32_e32 v36, 0x41800000, v36
	v_fma_f32 v34, v97, v43, -v34
	v_fma_f32 v32, v97, v32, -v135
	v_mov_b32_e32 v75, 0
	v_fma_f32 v165, v117, v133, -v129
	v_fma_f32 v117, v117, v37, -v41
	v_fma_f32 v41, v95, v33, -v41
	v_add_f32_e32 v33, v115, v33
	v_cvt_pk_fp8_f32 v74, v10, v11
	v_med3_f32 v10, v38, s21, v62
	v_med3_f32 v11, v36, s21, v62
	v_mul_f32_e32 v34, 0x41800000, v34
	v_mul_f32_e32 v32, 0x41800000, v32
	v_mov_b32_e32 v76, 0
	v_mul_f32_e32 v49, 0x41800000, v49
	v_mul_f32_e32 v47, 0x41800000, v47
	v_mul_f32_e32 v41, 0x41800000, v41
	v_fma_f32 v39, v96, v33, -v39
	v_add_f32_e32 v51, v165, v53
	v_add_f32_e32 v33, v117, v33
	v_cvt_pk_fp8_f32 v75, v10, v11
	v_med3_f32 v10, v34, s21, v62
	v_med3_f32 v11, v32, s21, v62
	v_med3_f32 v49, v49, s21, v62
	v_med3_f32 v47, v47, s21, v62
	v_med3_f32 v25, v41, s21, v62
	v_mul_f32_e32 v39, 0x41800000, v39
	v_fma_f32 v41, v98, v51, -v133
	v_fma_f32 v37, v98, v33, -v37
	v_add_f32_e32 v33, v166, v33
	v_add_f32_e32 v42, v167, v51
	v_cvt_pk_fp8_f32 v76, v10, v11
	v_cvt_pk_fp8_f32 v69, v48, v49 op_sel:[0,0,1]
	v_med3_f32 v30, v39, s21, v62
	v_mul_f32_e32 v39, 0x41800000, v41
	v_mul_f32_e32 v37, 0x41800000, v37
	v_fma_f32 v35, v97, v42, -v35
	v_fma_f32 v33, v97, v33, -v134
	v_cvt_pk_fp8_f32 v70, v46, v47 op_sel:[0,0,1]
	v_cvt_pk_fp8_f32 v71, v26, v27 op_sel:[0,0,1]
	v_cvt_pk_fp8_f32 v72, v29, v31 op_sel:[0,0,1]
	v_cvt_pk_fp8_f32 v73, v24, v25 op_sel:[0,0,1]
	global_store_dword v[22:23], v65, off offset:1024
	global_store_dword v[22:23], v66, off offset:3072
	v_med3_f32 v22, v39, s21, v62
	v_med3_f32 v23, v37, s21, v62
	v_mul_f32_e32 v35, 0x41800000, v35
	v_mul_f32_e32 v33, 0x41800000, v33
	v_cvt_pk_fp8_f32 v74, v28, v30 op_sel:[0,0,1]
	s_add_i32 s28, s28, 16
	v_med3_f32 v26, v35, s21, v62
	v_med3_f32 v27, v33, s21, v62
	v_cvt_pk_fp8_f32 v75, v22, v23 op_sel:[0,0,1]
	v_lshl_add_u64 v[6:7], v[6:7], 0, s[10:11]
	v_lshl_add_u64 v[8:9], v[8:9], 0, s[12:13]
	s_cmp_eq_u32 s28, 64
	v_cvt_pk_fp8_f32 v76, v26, v27 op_sel:[0,0,1]
	global_store_dword v[20:21], v67, off offset:1024
	global_store_dword v[20:21], v68, off offset:3072
	global_store_dword v[18:19], v69, off offset:1024
	global_store_dword v[18:19], v70, off offset:3072
	global_store_dword v[16:17], v71, off offset:1024
	global_store_dword v[16:17], v72, off offset:3072
	global_store_dword v[12:13], v73, off offset:1024
	global_store_dword v[12:13], v74, off offset:3072
	global_store_dword v[14:15], v75, off offset:1024
	global_store_dword v[14:15], v76, off offset:3072
	s_cbranch_scc0 .LBB0_505
	s_mov_b64 s[0:1], 0

.LBB0_509:
	v_lshl_add_u64 v[12:13], s[74:75], 0, v[6:7]
	v_add_co_u32_e32 v24, vcc, s22, v12
	s_add_i32 s0, s38, s14
	s_nop 0
	v_addc_co_u32_e32 v25, vcc, 0, v13, vcc
	v_add_co_u32_e32 v22, vcc, s23, v12
	s_and_b32 s15, s0, s40
	s_nop 0
	v_addc_co_u32_e32 v23, vcc, 0, v13, vcc
	v_add_co_u32_e32 v20, vcc, s24, v12
	v_sub_co_u32_e64 v26, s[2:3], s15, 1
	s_nop 0
	v_addc_co_u32_e32 v21, vcc, 0, v13, vcc
	v_add_co_u32_e32 v18, vcc, s25, v12
	s_add_i32 s4, s15, -2
	s_nop 0
	v_addc_co_u32_e32 v19, vcc, 0, v13, vcc
	s_waitcnt lgkmcnt(0)
	v_add_co_u32_e32 v16, vcc, s26, v12
	s_or_b32 s5, s15, 1
	s_nop 0
	v_addc_co_u32_e32 v17, vcc, 0, v13, vcc
	v_add_co_u32_e32 v14, vcc, s27, v12
	s_or_b32 s49, s15, 2
	s_nop 0
	v_addc_co_u32_e32 v15, vcc, 0, v13, vcc
	v_add_co_u32_e32 v10, vcc, s36, v12
	s_or_b32 s58, s15, 5
	s_or_b32 s48, s15, 6
	s_or_b32 s47, s15, 7
	s_or_b32 s46, s15, 8
	s_or_b32 s45, s15, 9
	s_or_b32 s44, s15, 10
	v_cndmask_b32_e64 v79, 1.0, 0, s[2:3]
	v_readfirstlane_b32 s2, v26
	v_addc_co_u32_e32 v11, vcc, 0, v13, vcc
	s_or_b32 s50, s15, 3
	s_or_b32 s51, s15, 4
	s_or_b32 s43, s15, 11
	s_or_b32 s42, s15, 12
	s_or_b32 s41, s15, 13
	s_or_b32 s29, s15, 14
	s_or_b32 s28, s15, 15
	s_add_i32 s31, s15, 16
	s_max_i32 s1, s4, 0
	s_min_u32 s3, s5, s40
	s_min_u32 s56, s49, s40
	s_min_u32 s60, s58, s40
	s_min_u32 s61, s48, s40
	s_min_u32 s62, s47, s40
	s_min_u32 s63, s46, s40
	s_min_u32 s64, s45, s40
	s_min_u32 s65, s44, s40
	s_max_i32 s2, s2, 0
	v_add_co_u32_e32 v12, vcc, s37, v12
	s_min_u32 s57, s50, s40
	s_min_u32 s59, s51, s40
	s_min_u32 s66, s43, s40
	s_min_u32 s67, s42, s40
	s_min_u32 s68, s41, s40
	s_min_u32 s69, s29, s40
	s_min_u32 s70, s28, s40
	s_min_u32 s71, s31, s40
	s_min_u32 s1, s1, s40
	s_sub_i32 s3, s3, s15
	s_sub_i32 s56, s56, s15
	s_sub_i32 s60, s60, s15
	s_sub_i32 s61, s61, s15
	s_sub_i32 s62, s62, s15
	s_sub_i32 s63, s63, s15
	s_sub_i32 s64, s64, s15
	s_sub_i32 s65, s65, s15
	s_min_u32 s2, s2, s40
	v_addc_co_u32_e32 v13, vcc, 0, v13, vcc
	s_sub_i32 s57, s57, s15
	s_sub_i32 s59, s59, s15
	s_sub_i32 s66, s66, s15
	s_sub_i32 s67, s67, s15
	s_sub_i32 s68, s68, s15
	s_sub_i32 s69, s69, s15
	s_sub_i32 s70, s70, s15
	s_sub_i32 s71, s71, s15
	s_sub_i32 s1, s1, s15
	s_add_i32 s3, s0, s3
	s_add_i32 s56, s0, s56
	s_add_i32 s60, s0, s60
	s_add_i32 s61, s0, s61
	s_add_i32 s62, s0, s62
	s_add_i32 s63, s0, s63
	s_add_i32 s64, s0, s64
	s_add_i32 s65, s0, s65
	s_sub_i32 s78, s2, s15
	v_cmp_gt_u32_e32 vcc, s39, v26
	s_add_i32 s57, s0, s57
	s_add_i32 s59, s0, s59
	s_add_i32 s66, s0, s66
	s_add_i32 s67, s0, s67
	s_add_i32 s68, s0, s68
	s_add_i32 s69, s0, s69
	s_add_i32 s70, s0, s70
	s_add_i32 s71, s0, s71
	s_add_i32 s1, s0, s1
	v_mad_i64_i32 v[82:83], s[2:3], s3, v1, v[2:3]
	v_mad_i64_i32 v[26:27], s[2:3], s56, v1, v[2:3]
	v_mad_i64_i32 v[32:33], s[2:3], s60, v1, v[2:3]
	v_mad_i64_i32 v[34:35], s[2:3], s61, v1, v[2:3]
	v_mad_i64_i32 v[36:37], s[2:3], s62, v1, v[2:3]
	v_mad_i64_i32 v[38:39], s[2:3], s63, v1, v[2:3]
	v_mad_i64_i32 v[40:41], s[2:3], s64, v1, v[2:3]
	v_mad_i64_i32 v[42:43], s[2:3], s65, v1, v[2:3]
	s_add_i32 s0, s0, s78
	v_mad_i64_i32 v[28:29], s[2:3], s57, v1, v[2:3]
	v_mad_i64_i32 v[30:31], s[2:3], s59, v1, v[2:3]
	v_mad_i64_i32 v[84:85], s[2:3], s66, v1, v[2:3]
	v_mad_i64_i32 v[86:87], s[2:3], s67, v1, v[2:3]
	v_mad_i64_i32 v[88:89], s[2:3], s68, v1, v[2:3]
	v_mad_i64_i32 v[90:91], s[2:3], s69, v1, v[2:3]
	v_mad_i64_i32 v[92:93], s[2:3], s70, v1, v[2:3]
	v_mad_i64_i32 v[94:95], s[2:3], s71, v1, v[2:3]
	v_mad_i64_i32 v[96:97], s[2:3], s1, v1, v[2:3]
	global_load_dwordx2 v[60:61], v[26:27], off nt
	global_load_dwordx2 v[58:59], v[28:29], off nt
	global_load_dwordx2 v[56:57], v[30:31], off nt
	global_load_dwordx2 v[54:55], v[32:33], off nt
	global_load_dwordx2 v[52:53], v[34:35], off nt
	global_load_dwordx2 v[50:51], v[36:37], off nt
	global_load_dwordx2 v[48:49], v[38:39], off nt
	global_load_dwordx2 v[46:47], v[40:41], off nt
	global_load_dwordx2 v[44:45], v[42:43], off nt
	s_nop 0
	global_load_dwordx2 v[42:43], v[84:85], off nt
	global_load_dwordx2 v[40:41], v[86:87], off nt
	global_load_dwordx2 v[38:39], v[88:89], off nt
	global_load_dwordx2 v[36:37], v[90:91], off nt
	global_load_dwordx2 v[34:35], v[92:93], off nt
	global_load_dwordx2 v[32:33], v[94:95], off nt
	v_mad_i64_i32 v[26:27], s[0:1], s0, v1, v[2:3]
	s_cmp_lt_u32 s4, s39
	v_lshl_add_u64 v[8:9], s[74:75], 0, v[4:5]
	s_cselect_b64 s[0:1], -1, 0
	s_cmp_lt_u32 s5, s39
	global_load_dwordx2 v[30:31], v[96:97], off nt
	global_load_dwordx2 v[28:29], v[26:27], off nt
	s_nop 0
	global_load_dwordx2 v[26:27], v[8:9], off nt
	s_nop 0
	global_load_dwordx2 v[8:9], v[82:83], off nt
	v_cndmask_b32_e64 v82, 0, 1.0, s[0:1]
	s_cselect_b64 s[0:1], -1, 0
	v_cndmask_b32_e64 v83, 0, 1.0, s[0:1]
	s_min_u32 s0, s49, s39
	v_sub_u32_e64 v81, s15, 2 clamp
	s_cmp_lt_u32 s5, s40
	v_sub_u32_e32 v81, s0, v81
	s_cselect_b64 s[0:1], -1, 0
	v_cndmask_b32_e64 v84, 0, 1.0, s[0:1]
	s_min_u32 s0, s50, s39
	v_sub_u32_e64 v98, s5, 2 clamp
	s_cmp_lt_u32 s49, s40
	v_sub_u32_e32 v85, s0, v98
	s_cselect_b64 s[0:1], -1, 0
	v_cndmask_b32_e64 v86, 0, 1.0, s[0:1]
	s_min_u32 s0, s51, s39
	v_cvt_f32_i32_e32 v81, v81
	s_sub_i32 s2, s0, s49
	s_add_i32 s2, s2, 2
	v_cvt_f32_i32_e32 v85, v85
	s_cmp_lt_u32 s50, s40
	v_cvt_f32_i32_e32 v90, s2
	s_cselect_b64 s[2:3], -1, 0
	v_div_scale_f32 v87, s[0:1], v81, v81, 1.0
	v_cndmask_b32_e64 v93, 0, 1.0, s[2:3]
	s_min_u32 s2, s58, s39
	v_rcp_f32_e32 v89, v87
	s_sub_i32 s2, s2, s50
	v_div_scale_f32 v91, s[0:1], v85, v85, 1.0
	s_add_i32 s4, s2, 2
	v_rcp_f32_e32 v94, v91
	s_cmp_lt_u32 s51, s40
	v_cvt_f32_i32_e32 v98, s4
	s_cselect_b64 s[4:5], -1, 0
	v_fma_f32 v95, -v87, v89, 1.0
	v_cndmask_b32_e64 v99, 0, 1.0, s[4:5]
	s_min_u32 s4, s48, s39
	v_cndmask_b32_e64 v80, 0, 1.0, vcc
	v_div_scale_f32 v88, vcc, 1.0, v81, 1.0
	v_div_scale_f32 v96, s[2:3], v90, v90, 1.0
	v_fmac_f32_e32 v89, v95, v89
	s_sub_i32 s4, s4, s51
	v_rcp_f32_e32 v95, v96
	v_mul_f32_e32 v100, v88, v89
	v_fma_f32 v101, -v91, v94, 1.0
	s_add_i32 s49, s4, 2
	v_div_scale_f32 v92, s[0:1], 1.0, v85, 1.0
	v_fma_f32 v102, -v87, v100, v88
	v_fmac_f32_e32 v94, v101, v94
	s_cmp_lt_u32 s58, s40
	v_fmac_f32_e32 v100, v102, v89
	v_mul_f32_e32 v101, v92, v94
	v_cvt_f32_i32_e32 v104, s49
	s_cselect_b64 s[56:57], -1, 0
	s_min_u32 s49, s47, s39
	v_div_scale_f32 v102, s[4:5], v98, v98, 1.0
	v_fma_f32 v87, -v87, v100, v88
	v_fma_f32 v88, -v91, v101, v92
	s_sub_i32 s49, s49, s58
	v_fma_f32 v105, -v96, v95, 1.0
	v_rcp_f32_e32 v106, v102
	v_div_fmas_f32 v87, v87, v89, v100
	v_fmac_f32_e32 v101, v88, v94
	s_add_i32 s49, s49, 2
	v_div_scale_f32 v97, s[2:3], 1.0, v90, 1.0
	v_fmac_f32_e32 v95, v105, v95
	v_div_fixup_f32 v81, v87, v81, 1.0
	v_fma_f32 v87, -v91, v101, v92
	s_mov_b64 vcc, s[0:1]
	s_cmp_lt_u32 s48, s40
	v_cndmask_b32_e64 v107, 0, 1.0, s[56:57]
	v_mul_f32_e32 v88, v97, v95
	v_div_fmas_f32 v87, v87, v94, v101
	v_cvt_f32_i32_e32 v94, s49
	s_cselect_b64 s[56:57], -1, 0
	s_min_u32 s49, s46, s39
	v_fma_f32 v89, -v96, v88, v97
	v_div_scale_f32 v91, s[0:1], v104, v104, 1.0
	s_sub_i32 s48, s49, s48
	v_div_fixup_f32 v85, v87, v85, 1.0
	v_fmac_f32_e32 v88, v89, v95
	v_fma_f32 v87, -v102, v106, 1.0
	v_rcp_f32_e32 v89, v91
	s_add_i32 s48, s48, 2
	v_div_scale_f32 v103, s[4:5], 1.0, v98, 1.0
	v_fma_f32 v96, -v96, v88, v97
	v_fmac_f32_e32 v106, v87, v106
	s_mov_b64 vcc, s[2:3]
	s_cmp_lt_u32 s47, s40
	v_div_fmas_f32 v87, v96, v95, v88
	v_mul_f32_e32 v88, v103, v106
	v_cvt_f32_i32_e32 v97, s48
	s_cselect_b64 s[48:49], -1, 0
	v_div_fixup_f32 v87, v87, v90, 1.0
	v_fma_f32 v90, -v102, v88, v103
	v_cndmask_b32_e64 v105, 0, 1.0, s[48:49]
	s_min_u32 s48, s45, s39
	v_fmac_f32_e32 v88, v90, v106
	v_fma_f32 v90, -v91, v89, 1.0
	s_sub_i32 s47, s48, s47
	v_div_scale_f32 v92, s[0:1], 1.0, v104, 1.0
	v_div_scale_f32 v95, s[2:3], v94, v94, 1.0
	v_fma_f32 v102, -v102, v88, v103
	v_fmac_f32_e32 v89, v90, v89
	s_mov_b64 vcc, s[4:5]
	s_add_i32 s47, s47, 2
	v_rcp_f32_e32 v101, v95
	v_div_fmas_f32 v88, v102, v106, v88
	v_mul_f32_e32 v90, v92, v89
	s_cmp_lt_u32 s46, s40
	v_div_fixup_f32 v88, v88, v98, 1.0
	v_fma_f32 v98, -v91, v90, v92
	v_cvt_f32_i32_e32 v106, s47
	s_cselect_b64 s[48:49], -1, 0
	s_min_u32 s47, s44, s39
	v_fmac_f32_e32 v90, v98, v89
	s_sub_i32 s46, s47, s46
	v_div_scale_f32 v102, s[4:5], v97, v97, 1.0
	v_fma_f32 v91, -v91, v90, v92
	s_mov_b64 vcc, s[0:1]
	s_add_i32 s46, s46, 2
	v_fma_f32 v98, -v95, v101, 1.0
	v_rcp_f32_e32 v108, v102
	v_div_fmas_f32 v89, v91, v89, v90
	s_cmp_lt_u32 s45, s40
	v_div_scale_f32 v96, s[2:3], 1.0, v94, 1.0
	v_fmac_f32_e32 v101, v98, v101
	v_div_fixup_f32 v89, v89, v104, 1.0
	v_cvt_f32_i32_e32 v104, s46
	s_cselect_b64 s[46:47], -1, 0
	v_mul_f32_e32 v90, v96, v101
	v_cndmask_b32_e64 v111, 0, 1.0, s[46:47]
	s_min_u32 s46, s43, s39
	v_fma_f32 v91, -v95, v90, v96
	v_div_scale_f32 v92, s[0:1], v106, v106, 1.0
	s_sub_i32 s45, s46, s45
	v_fmac_f32_e32 v90, v91, v101
	v_fma_f32 v91, -v102, v108, 1.0
	v_rcp_f32_e32 v110, v92
	s_add_i32 s45, s45, 2
	v_div_scale_f32 v103, s[4:5], 1.0, v97, 1.0
	v_fma_f32 v95, -v95, v90, v96
	v_fmac_f32_e32 v108, v91, v108
	s_mov_b64 vcc, s[2:3]
	s_cmp_lt_u32 s44, s40
	v_div_fmas_f32 v90, v95, v101, v90
	v_mul_f32_e32 v91, v103, v108
	v_cvt_f32_i32_e32 v101, s45
	s_cselect_b64 s[46:47], -1, 0
	s_min_u32 s45, s42, s39
	v_div_fixup_f32 v90, v90, v94, 1.0
	v_fma_f32 v94, -v102, v91, v103
	v_div_scale_f32 v95, s[2:3], v104, v104, 1.0
	s_sub_i32 s44, s45, s44
	v_fmac_f32_e32 v91, v94, v108
	v_fma_f32 v94, -v92, v110, 1.0
	v_rcp_f32_e32 v112, v95
	s_add_i32 s44, s44, 2
	v_div_scale_f32 v98, s[0:1], 1.0, v106, 1.0
	v_fma_f32 v102, -v102, v91, v103
	v_fmac_f32_e32 v110, v94, v110
	s_mov_b64 vcc, s[4:5]
	s_cmp_lt_u32 s43, s40
	v_div_fmas_f32 v91, v102, v108, v91
	v_mul_f32_e32 v94, v98, v110
	v_cvt_f32_i32_e32 v108, s44
	s_cselect_b64 s[44:45], -1, 0
	v_div_fixup_f32 v91, v91, v97, 1.0
	v_fma_f32 v97, -v92, v94, v98
	v_div_scale_f32 v102, s[4:5], v101, v101, 1.0
	v_cndmask_b32_e64 v115, 0, 1.0, s[44:45]
	s_min_u32 s44, s41, s39
	v_fmac_f32_e32 v94, v97, v110
	v_fma_f32 v97, -v95, v112, 1.0
	v_rcp_f32_e32 v114, v102
	s_sub_i32 s43, s44, s43
	v_div_scale_f32 v96, s[2:3], 1.0, v104, 1.0
	v_fma_f32 v92, -v92, v94, v98
	v_fmac_f32_e32 v112, v97, v112
	s_mov_b64 vcc, s[0:1]
	s_add_i32 s43, s43, 2
	v_div_fmas_f32 v92, v92, v110, v94
	v_mul_f32_e32 v94, v96, v112
	s_cmp_lt_u32 s42, s40
	v_fma_f32 v97, -v95, v94, v96
	v_div_scale_f32 v98, s[0:1], v108, v108, 1.0
	v_cvt_f32_i32_e32 v110, s43
	s_cselect_b64 s[44:45], -1, 0
	s_min_u32 s43, s29, s39
	v_fmac_f32_e32 v94, v97, v112
	v_fma_f32 v97, -v102, v114, 1.0
	v_rcp_f32_e32 v116, v98
	s_sub_i32 s42, s43, s42
	v_div_scale_f32 v103, s[4:5], 1.0, v101, 1.0
	v_fma_f32 v95, -v95, v94, v96
	v_fmac_f32_e32 v114, v97, v114
	s_mov_b64 vcc, s[2:3]
	s_add_i32 s42, s42, 2
	v_div_fmas_f32 v94, v95, v112, v94
	v_mul_f32_e32 v95, v103, v114
	s_cmp_lt_u32 s41, s40
	v_fma_f32 v96, -v102, v95, v103
	v_div_scale_f32 v97, s[2:3], v110, v110, 1.0
	v_cvt_f32_i32_e32 v112, s42
	s_cselect_b64 s[42:43], -1, 0
	v_fmac_f32_e32 v95, v96, v114
	v_fma_f32 v96, -v98, v116, 1.0
	v_rcp_f32_e32 v118, v97
	v_cndmask_b32_e64 v119, 0, 1.0, s[42:43]
	s_min_u32 s42, s28, s39
	v_div_fixup_f32 v92, v92, v106, 1.0
	v_div_scale_f32 v106, s[0:1], 1.0, v108, 1.0
	v_fma_f32 v102, -v102, v95, v103
	v_fmac_f32_e32 v116, v96, v116
	s_sub_i32 s41, s42, s41
	s_mov_b64 vcc, s[4:5]
	v_div_fmas_f32 v95, v102, v114, v95
	v_mul_f32_e32 v96, v106, v116
	s_add_i32 s41, s41, 2
	v_div_fixup_f32 v95, v95, v101, 1.0
	v_fma_f32 v101, -v98, v96, v106
	v_div_scale_f32 v102, s[4:5], v112, v112, 1.0
	v_cvt_f32_i32_e32 v114, s41
	s_cmp_lt_u32 s29, s40
	v_fmac_f32_e32 v96, v101, v116
	v_fma_f32 v101, -v97, v118, 1.0
	v_rcp_f32_e32 v120, v102
	s_cselect_b64 s[42:43], -1, 0
	s_min_u32 s31, s31, s39
	v_div_fixup_f32 v94, v94, v104, 1.0
	v_div_scale_f32 v104, s[2:3], 1.0, v110, 1.0
	v_fma_f32 v98, -v98, v96, v106
	v_fmac_f32_e32 v118, v101, v118
	s_sub_i32 s29, s31, s29
	s_mov_b64 vcc, s[0:1]
	v_div_fmas_f32 v96, v98, v116, v96
	v_mul_f32_e32 v98, v104, v118
	s_add_i32 s29, s29, 2
	v_fma_f32 v101, -v97, v98, v104
	v_div_scale_f32 v106, s[0:1], v114, v114, 1.0
	v_cvt_f32_i32_e32 v116, s29
	s_cmp_lt_u32 s28, s40
	v_cndmask_b32_e64 v121, 0, 1.0, s[42:43]
	v_fmac_f32_e32 v98, v101, v118
	v_fma_f32 v101, -v102, v120, 1.0
	v_rcp_f32_e32 v122, v106
	s_cselect_b64 s[42:43], -1, 0
	s_add_i32 s15, s15, 17
	v_div_scale_f32 v103, s[4:5], 1.0, v112, 1.0
	v_fma_f32 v97, -v97, v98, v104
	v_fmac_f32_e32 v120, v101, v120
	s_min_u32 s15, s15, s39
	s_mov_b64 vcc, s[2:3]
	v_div_fmas_f32 v97, v97, v118, v98
	v_mul_f32_e32 v98, v103, v120
	s_sub_i32 s15, s15, s28
	v_fma_f32 v101, -v102, v98, v103
	v_div_scale_f32 v104, s[2:3], v116, v116, 1.0
	s_add_i32 s15, s15, 2
	v_fmac_f32_e32 v98, v101, v120
	v_fma_f32 v101, -v106, v122, 1.0
	v_rcp_f32_e32 v118, v104
	v_cvt_f32_i32_e32 v124, s15
	v_div_fixup_f32 v96, v96, v108, 1.0
	v_div_scale_f32 v108, s[0:1], 1.0, v114, 1.0
	v_fmac_f32_e32 v122, v101, v122
	v_fma_f32 v102, -v102, v98, v103
	s_mov_b64 vcc, s[4:5]
	v_mul_f32_e32 v101, v108, v122
	v_div_fmas_f32 v98, v102, v120, v98
	v_fma_f32 v102, -v106, v101, v108
	v_fmac_f32_e32 v101, v102, v122
	v_fma_f32 v102, -v104, v118, 1.0
	v_div_scale_f32 v103, s[4:5], v124, v124, 1.0
	v_fmac_f32_e32 v118, v102, v118
	v_rcp_f32_e32 v102, v103
	v_div_fixup_f32 v97, v97, v110, 1.0
	v_div_scale_f32 v110, s[2:3], 1.0, v116, 1.0
	v_fma_f32 v106, -v106, v101, v108
	s_mov_b64 vcc, s[0:1]
	v_div_fmas_f32 v101, v106, v122, v101
	v_mul_f32_e32 v106, v110, v118
	v_fma_f32 v108, -v104, v106, v110
	v_fmac_f32_e32 v106, v108, v118
	v_fma_f32 v108, -v103, v102, 1.0
	v_div_fixup_f32 v98, v98, v112, 1.0
	v_div_scale_f32 v112, s[4:5], 1.0, v124, 1.0
	v_fma_f32 v104, -v104, v106, v110
	s_mov_b64 vcc, s[2:3]
	v_fmac_f32_e32 v102, v108, v102
	v_div_fmas_f32 v104, v104, v118, v106
	v_mul_f32_e32 v106, v112, v102
	v_cndmask_b32_e64 v123, 0, 1.0, s[42:43]
	v_fma_f32 v108, -v103, v106, v112
	s_waitcnt vmcnt(8)
	v_lshlrev_b32_e32 v134, 16, v40
	v_and_b32_e32 v40, 0xffff0000, v40
	v_lshlrev_b32_e32 v135, 16, v41
	v_and_b32_e32 v41, 0xffff0000, v41
	s_waitcnt vmcnt(4)
	v_and_b32_e32 v142, 0xffff0000, v33
	v_lshlrev_b32_e32 v33, 16, v33
	v_and_b32_e32 v143, 0xffff0000, v32
	v_lshlrev_b32_e32 v32, 16, v32
	s_waitcnt vmcnt(3)
	v_lshlrev_b32_e32 v144, 16, v30
	v_and_b32_e32 v30, 0xffff0000, v30
	v_lshlrev_b32_e32 v145, 16, v31
	v_and_b32_e32 v31, 0xffff0000, v31
	v_fmac_f32_e32 v106, v108, v102
	v_fma_f32 v142, v123, v142, -v41
	v_fma_f32 v33, v123, v33, -v135
	v_fma_f32 v143, v123, v143, -v40
	v_fma_f32 v32, v123, v32, -v134
	v_fma_f32 v123, v82, v144, 0
	v_fma_f32 v176, v82, v30, 0
	v_fma_f32 v177, v82, v145, 0
	v_fma_f32 v82, v82, v31, 0
	s_waitcnt vmcnt(2)
	v_lshlrev_b32_e32 v178, 16, v28
	v_and_b32_e32 v28, 0xffff0000, v28
	v_lshlrev_b32_e32 v179, 16, v29
	v_and_b32_e32 v29, 0xffff0000, v29
	v_fma_f32 v103, -v103, v106, v112
	s_mov_b64 vcc, s[4:5]
	s_waitcnt vmcnt(1)
	v_lshlrev_b32_e32 v180, 16, v26
	v_and_b32_e32 v26, 0xffff0000, v26
	v_lshlrev_b32_e32 v181, 16, v27
	v_and_b32_e32 v27, 0xffff0000, v27
	v_fmac_f32_e32 v123, v80, v178
	v_fmac_f32_e32 v176, v80, v28
	v_fmac_f32_e32 v177, v80, v179
	v_fmac_f32_e32 v82, v80, v29
	v_div_fmas_f32 v102, v103, v102, v106
	v_lshlrev_b32_e32 v103, 16, v60
	v_and_b32_e32 v60, 0xffff0000, v60
	v_lshlrev_b32_e32 v106, 16, v61
	v_and_b32_e32 v61, 0xffff0000, v61
	s_waitcnt vmcnt(0)
	v_lshlrev_b32_e32 v182, 16, v8
	v_and_b32_e32 v8, 0xffff0000, v8
	v_lshlrev_b32_e32 v183, 16, v9
	v_and_b32_e32 v9, 0xffff0000, v9
	v_mul_f32_e32 v144, v79, v144
	v_mul_f32_e32 v30, v79, v30
	v_mul_f32_e32 v145, v79, v145
	v_mul_f32_e32 v31, v79, v31
	v_add_f32_e32 v123, v123, v180
	v_add_f32_e32 v176, v176, v26
	v_add_f32_e32 v177, v177, v181
	v_add_f32_e32 v82, v82, v27
	v_div_fixup_f32 v101, v101, v114, 1.0
	v_lshlrev_b32_e32 v108, 16, v58
	v_and_b32_e32 v58, 0xffff0000, v58
	v_lshlrev_b32_e32 v110, 16, v59
	v_and_b32_e32 v59, 0xffff0000, v59
	v_lshlrev_b32_e32 v112, 16, v56
	v_and_b32_e32 v56, 0xffff0000, v56
	v_lshlrev_b32_e32 v114, 16, v57
	v_and_b32_e32 v57, 0xffff0000, v57
	v_fma_f32 v80, v84, v103, -v144
	v_fma_f32 v30, v84, v60, -v30
	v_fma_f32 v144, v84, v106, -v145
	v_fma_f32 v31, v84, v61, -v31
	v_mul_f32_e32 v84, v79, v178
	v_mul_f32_e32 v28, v79, v28
	v_mul_f32_e32 v145, v79, v179
	v_mul_f32_e32 v29, v79, v29
	v_fmac_f32_e32 v123, v83, v182
	v_fmac_f32_e32 v176, v83, v8
	v_fmac_f32_e32 v177, v83, v183
	v_fmac_f32_e32 v82, v83, v9
	v_div_fixup_f32 v104, v104, v116, 1.0
	v_lshlrev_b32_e32 v116, 16, v54
	v_and_b32_e32 v54, 0xffff0000, v54
	v_fma_f32 v79, v93, v112, -v180
	v_fma_f32 v178, v93, v56, -v26
	v_fma_f32 v179, v93, v114, -v181
	v_fma_f32 v93, v93, v57, -v27
	v_fma_f32 v84, v86, v108, -v84
	v_fma_f32 v28, v86, v58, -v28
	v_fma_f32 v145, v86, v110, -v145
	v_fma_f32 v29, v86, v59, -v29
	v_fma_f32 v83, v81, v123, -v180
	v_fma_f32 v26, v81, v176, -v26
	v_fma_f32 v86, v81, v177, -v181
	v_fma_f32 v27, v81, v82, -v27
	v_add_f32_e32 v80, v80, v123
	v_add_f32_e32 v30, v30, v176
	v_add_f32_e32 v81, v144, v177
	v_add_f32_e32 v31, v31, v82
	v_lshlrev_b32_e32 v118, 16, v55
	v_and_b32_e32 v55, 0xffff0000, v55
	v_lshlrev_b32_e32 v120, 16, v52
	v_and_b32_e32 v52, 0xffff0000, v52
	v_lshlrev_b32_e32 v122, 16, v53
	v_and_b32_e32 v53, 0xffff0000, v53
	v_fma_f32 v185, v99, v54, -v8
	v_mul_f32_e32 v82, 0x41800000, v83
	v_mul_f32_e32 v26, 0x41800000, v26
	v_mul_f32_e32 v83, 0x41800000, v86
	v_fma_f32 v86, v85, v80, -v182
	v_fma_f32 v8, v85, v30, -v8
	v_fma_f32 v123, v85, v81, -v183
	v_add_f32_e32 v80, v84, v80
	v_add_f32_e32 v28, v28, v30
	v_add_f32_e32 v30, v145, v81
	v_add_f32_e32 v29, v29, v31
	v_mov_b32_e32 v63, 0
	v_cndmask_b32_e64 v100, 0, 1.0, s[56:57]
	v_div_fixup_f32 v102, v102, v124, 1.0
	v_lshlrev_b32_e32 v124, 16, v50
	v_and_b32_e32 v50, 0xffff0000, v50
	v_lshlrev_b32_e32 v125, 16, v51
	v_and_b32_e32 v51, 0xffff0000, v51
	v_fma_f32 v146, v107, v120, -v103
	v_fma_f32 v147, v107, v52, -v60
	v_fma_f32 v148, v107, v122, -v106
	v_fma_f32 v107, v107, v53, -v61
	v_fma_f32 v184, v99, v116, -v182
	v_fma_f32 v186, v99, v118, -v183
	v_fma_f32 v99, v99, v55, -v9
	v_fma_f32 v9, v85, v31, -v9
	v_med3_f32 v31, v82, s21, v62
	v_med3_f32 v26, v26, s21, v62
	v_med3_f32 v81, v83, s21, v62
	v_mul_f32_e32 v82, 0x41800000, v86
	v_mul_f32_e32 v8, 0x41800000, v8
	v_mul_f32_e32 v83, 0x41800000, v123
	v_fma_f32 v84, v87, v80, -v103
	v_fma_f32 v60, v87, v28, -v60
	v_fma_f32 v85, v87, v30, -v106
	v_fma_f32 v61, v87, v29, -v61
	v_add_f32_e32 v79, v79, v80
	v_add_f32_e32 v28, v178, v28
	v_add_f32_e32 v30, v179, v30
	v_add_f32_e32 v29, v93, v29
	v_mov_b32_e32 v64, 0
	v_lshlrev_b32_e32 v126, 16, v48
	v_and_b32_e32 v48, 0xffff0000, v48
	v_lshlrev_b32_e32 v127, 16, v49
	v_and_b32_e32 v49, 0xffff0000, v49
	v_fma_f32 v149, v100, v124, -v108
	v_fma_f32 v150, v100, v50, -v58
	v_fma_f32 v151, v100, v125, -v110
	v_fma_f32 v100, v100, v51, -v59
	v_cvt_pk_fp8_f32 v63, v31, v26
	v_med3_f32 v26, v82, s21, v62
	v_med3_f32 v8, v8, s21, v62
	v_med3_f32 v31, v83, s21, v62
	v_mul_f32_e32 v80, 0x41800000, v84
	v_mul_f32_e32 v60, 0x41800000, v60
	v_mul_f32_e32 v82, 0x41800000, v85
	v_fma_f32 v83, v88, v79, -v108
	v_fma_f32 v58, v88, v28, -v58
	v_fma_f32 v84, v88, v30, -v110
	v_fma_f32 v59, v88, v29, -v59
	v_add_f32_e32 v79, v184, v79
	v_add_f32_e32 v28, v185, v28
	v_add_f32_e32 v30, v186, v30
	v_add_f32_e32 v29, v99, v29
	v_mov_b32_e32 v65, 0
	v_cndmask_b32_e64 v109, 0, 1.0, s[48:49]
	v_lshlrev_b32_e32 v128, 16, v46
	v_and_b32_e32 v46, 0xffff0000, v46
	v_lshlrev_b32_e32 v129, 16, v47
	v_and_b32_e32 v47, 0xffff0000, v47
	v_fma_f32 v152, v105, v126, -v112
	v_fma_f32 v153, v105, v48, -v56
	v_fma_f32 v154, v105, v127, -v114
	v_fma_f32 v105, v105, v49, -v57
	v_cvt_pk_fp8_f32 v64, v26, v8
	v_med3_f32 v8, v80, s21, v62
	v_med3_f32 v26, v60, s21, v62
	v_med3_f32 v60, v82, s21, v62
	v_mul_f32_e32 v80, 0x41800000, v83
	v_mul_f32_e32 v58, 0x41800000, v58
	v_mul_f32_e32 v82, 0x41800000, v84
	v_fma_f32 v83, v89, v79, -v112
	v_fma_f32 v56, v89, v28, -v56
	v_fma_f32 v84, v89, v30, -v114
	v_fma_f32 v57, v89, v29, -v57
	v_add_f32_e32 v79, v146, v79
	v_add_f32_e32 v28, v147, v28
	v_add_f32_e32 v30, v148, v30
	v_add_f32_e32 v29, v107, v29
	v_mov_b32_e32 v66, 0
	v_lshlrev_b32_e32 v130, 16, v44
	v_and_b32_e32 v44, 0xffff0000, v44
	v_lshlrev_b32_e32 v131, 16, v45
	v_and_b32_e32 v45, 0xffff0000, v45
	v_fma_f32 v155, v109, v128, -v116
	v_fma_f32 v156, v109, v46, -v54
	v_fma_f32 v157, v109, v129, -v118
	v_fma_f32 v109, v109, v47, -v55
	v_mul_f32_e32 v27, 0x41800000, v27
	v_cvt_pk_fp8_f32 v65, v8, v26
	v_med3_f32 v8, v80, s21, v62
	v_med3_f32 v26, v58, s21, v62
	v_med3_f32 v58, v82, s21, v62
	v_mul_f32_e32 v80, 0x41800000, v83
	v_mul_f32_e32 v56, 0x41800000, v56
	v_mul_f32_e32 v82, 0x41800000, v84
	v_fma_f32 v83, v90, v79, -v116
	v_fma_f32 v54, v90, v28, -v54
	v_fma_f32 v84, v90, v30, -v118
	v_fma_f32 v55, v90, v29, -v55
	v_add_f32_e32 v79, v149, v79
	v_add_f32_e32 v28, v150, v28
	v_add_f32_e32 v30, v151, v30
	v_add_f32_e32 v29, v100, v29
	v_mov_b32_e32 v67, 0
	v_cndmask_b32_e64 v113, 0, 1.0, s[46:47]
	v_lshlrev_b32_e32 v132, 16, v42
	v_and_b32_e32 v42, 0xffff0000, v42
	v_lshlrev_b32_e32 v133, 16, v43
	v_and_b32_e32 v43, 0xffff0000, v43
	v_fma_f32 v158, v111, v130, -v120
	v_fma_f32 v159, v111, v44, -v52
	v_fma_f32 v160, v111, v131, -v122
	v_fma_f32 v111, v111, v45, -v53
	v_med3_f32 v27, v27, s21, v62
	v_mul_f32_e32 v9, 0x41800000, v9
	v_cvt_pk_fp8_f32 v66, v8, v26
	v_med3_f32 v8, v80, s21, v62
	v_med3_f32 v26, v56, s21, v62
	v_med3_f32 v56, v82, s21, v62
	v_mul_f32_e32 v80, 0x41800000, v83
	v_mul_f32_e32 v54, 0x41800000, v54
	v_mul_f32_e32 v82, 0x41800000, v84
	v_mul_f32_e32 v55, 0x41800000, v55
	v_fma_f32 v83, v91, v79, -v120
	v_fma_f32 v52, v91, v28, -v52
	v_fma_f32 v84, v91, v30, -v122
	v_fma_f32 v53, v91, v29, -v53
	v_add_f32_e32 v79, v152, v79
	v_add_f32_e32 v28, v153, v28
	v_add_f32_e32 v30, v154, v30
	v_add_f32_e32 v29, v105, v29
	v_mov_b32_e32 v68, 0
	v_fma_f32 v161, v113, v132, -v124
	v_fma_f32 v162, v113, v42, -v50
	v_fma_f32 v163, v113, v133, -v125
	v_fma_f32 v113, v113, v43, -v51
	v_med3_f32 v9, v9, s21, v62
	v_mul_f32_e32 v61, 0x41800000, v61
	v_cvt_pk_fp8_f32 v63, v81, v27 op_sel:[0,0,1]
	v_cvt_pk_fp8_f32 v67, v8, v26
	v_med3_f32 v8, v80, s21, v62
	v_med3_f32 v26, v54, s21, v62
	v_med3_f32 v27, v82, s21, v62
	v_med3_f32 v54, v55, s21, v62
	v_mul_f32_e32 v55, 0x41800000, v83
	v_mul_f32_e32 v52, 0x41800000, v52
	v_mul_f32_e32 v80, 0x41800000, v84
	v_mul_f32_e32 v53, 0x41800000, v53
	v_fma_f32 v81, v92, v79, -v124
	v_fma_f32 v50, v92, v28, -v50
	v_fma_f32 v82, v92, v30, -v125
	v_fma_f32 v51, v92, v29, -v51
	v_add_f32_e32 v79, v155, v79
	v_add_f32_e32 v28, v156, v28
	v_add_f32_e32 v30, v157, v30
	v_add_f32_e32 v29, v109, v29
	v_mov_b32_e32 v69, 0
	v_cndmask_b32_e64 v117, 0, 1.0, s[44:45]
	v_lshlrev_b32_e32 v136, 16, v38
	v_and_b32_e32 v38, 0xffff0000, v38
	v_lshlrev_b32_e32 v137, 16, v39
	v_and_b32_e32 v39, 0xffff0000, v39
	v_fma_f32 v164, v115, v134, -v126
	v_fma_f32 v165, v115, v40, -v48
	v_fma_f32 v166, v115, v135, -v127
	v_fma_f32 v115, v115, v41, -v49
	v_med3_f32 v61, v61, s21, v62
	v_mul_f32_e32 v59, 0x41800000, v59
	v_cvt_pk_fp8_f32 v64, v31, v9 op_sel:[0,0,1]
	v_cvt_pk_fp8_f32 v68, v8, v26
	v_med3_f32 v8, v55, s21, v62
	v_med3_f32 v9, v52, s21, v62
	v_med3_f32 v26, v80, s21, v62
	v_med3_f32 v31, v53, s21, v62
	v_mul_f32_e32 v52, 0x41800000, v81
	v_mul_f32_e32 v50, 0x41800000, v50
	v_mul_f32_e32 v53, 0x41800000, v82
	v_fma_f32 v55, v94, v79, -v126
	v_fma_f32 v48, v94, v28, -v48
	v_fma_f32 v80, v94, v30, -v127
	v_fma_f32 v49, v94, v29, -v49
	v_add_f32_e32 v79, v158, v79
	v_add_f32_e32 v28, v159, v28
	v_add_f32_e32 v30, v160, v30
	v_add_f32_e32 v29, v111, v29
	v_mov_b32_e32 v70, 0
	v_lshlrev_b32_e32 v138, 16, v36
	v_and_b32_e32 v36, 0xffff0000, v36
	v_lshlrev_b32_e32 v139, 16, v37
	v_and_b32_e32 v37, 0xffff0000, v37
	v_fma_f32 v167, v117, v136, -v128
	v_fma_f32 v168, v117, v38, -v46
	v_fma_f32 v169, v117, v137, -v129
	v_fma_f32 v117, v117, v39, -v47
	v_med3_f32 v59, v59, s21, v62
	v_mul_f32_e32 v57, 0x41800000, v57
	v_cvt_pk_fp8_f32 v65, v60, v61 op_sel:[0,0,1]
	v_cvt_pk_fp8_f32 v69, v8, v9
	v_med3_f32 v8, v52, s21, v62
	v_med3_f32 v9, v50, s21, v62
	v_med3_f32 v50, v53, s21, v62
	v_mul_f32_e32 v52, 0x41800000, v55
	v_mul_f32_e32 v48, 0x41800000, v48
	v_mul_f32_e32 v53, 0x41800000, v80
	v_fma_f32 v55, v95, v79, -v128
	v_fma_f32 v46, v95, v28, -v46
	v_fma_f32 v60, v95, v30, -v129
	v_fma_f32 v47, v95, v29, -v47
	v_add_f32_e32 v61, v161, v79
	v_add_f32_e32 v28, v162, v28
	v_add_f32_e32 v30, v163, v30
	v_add_f32_e32 v29, v113, v29
	v_mov_b32_e32 v71, 0
	v_lshlrev_b32_e32 v140, 16, v34
	v_and_b32_e32 v34, 0xffff0000, v34
	v_lshlrev_b32_e32 v141, 16, v35
	v_and_b32_e32 v35, 0xffff0000, v35
	v_fma_f32 v170, v119, v138, -v130
	v_fma_f32 v171, v119, v36, -v44
	v_fma_f32 v172, v119, v139, -v131
	v_fma_f32 v119, v119, v37, -v45
	v_med3_f32 v57, v57, s21, v62
	v_cvt_pk_fp8_f32 v66, v58, v59 op_sel:[0,0,1]
	v_cvt_pk_fp8_f32 v70, v8, v9
	v_med3_f32 v8, v52, s21, v62
	v_med3_f32 v9, v48, s21, v62
	v_med3_f32 v48, v53, s21, v62
	v_mul_f32_e32 v52, 0x41800000, v55
	v_mul_f32_e32 v46, 0x41800000, v46
	v_mul_f32_e32 v53, 0x41800000, v60
	v_fma_f32 v55, v96, v61, -v130
	v_fma_f32 v44, v96, v28, -v44
	v_fma_f32 v58, v96, v30, -v131
	v_fma_f32 v45, v96, v29, -v45
	v_add_f32_e32 v59, v164, v61
	v_add_f32_e32 v28, v165, v28
	v_add_f32_e32 v29, v115, v29
	v_mov_b32_e32 v72, 0
	v_fma_f32 v173, v121, v140, -v132
	v_fma_f32 v174, v121, v34, -v42
	v_fma_f32 v175, v121, v141, -v133
	v_fma_f32 v121, v121, v35, -v43
	v_cvt_pk_fp8_f32 v67, v56, v57 op_sel:[0,0,1]
	v_cvt_pk_fp8_f32 v71, v8, v9
	v_med3_f32 v8, v52, s21, v62
	v_med3_f32 v9, v46, s21, v62
	v_med3_f32 v46, v53, s21, v62
	v_mul_f32_e32 v52, 0x41800000, v55
	v_mul_f32_e32 v44, 0x41800000, v44
	v_mul_f32_e32 v53, 0x41800000, v58
	v_mul_f32_e32 v45, 0x41800000, v45
	v_fma_f32 v55, v97, v59, -v132
	v_fma_f32 v42, v97, v28, -v42
	v_fma_f32 v43, v97, v29, -v43
	v_add_f32_e32 v57, v167, v59
	v_add_f32_e32 v28, v168, v28
	v_add_f32_e32 v29, v117, v29
	v_mov_b32_e32 v73, 0
	global_store_dword v[24:25], v63, off offset:1024
	global_store_dword v[24:25], v64, off offset:3072
	v_cvt_pk_fp8_f32 v68, v27, v54 op_sel:[0,0,1]
	v_cvt_pk_fp8_f32 v72, v8, v9
	v_med3_f32 v8, v52, s21, v62
	v_med3_f32 v9, v44, s21, v62
	v_med3_f32 v24, v53, s21, v62
	v_med3_f32 v25, v45, s21, v62
	v_mul_f32_e32 v27, 0x41800000, v55
	v_mul_f32_e32 v42, 0x41800000, v42
	v_mul_f32_e32 v43, 0x41800000, v43
	v_fma_f32 v45, v98, v57, -v134
	v_fma_f32 v40, v98, v28, -v40
	v_fma_f32 v41, v98, v29, -v41
	v_add_f32_e32 v53, v170, v57
	v_add_f32_e32 v28, v171, v28
	v_mov_b32_e32 v74, 0
	v_cvt_pk_fp8_f32 v69, v26, v31 op_sel:[0,0,1]
	v_cvt_pk_fp8_f32 v73, v8, v9
	v_med3_f32 v8, v27, s21, v62
	v_med3_f32 v9, v42, s21, v62
	v_med3_f32 v27, v43, s21, v62
	v_mul_f32_e32 v31, 0x41800000, v45
	v_mul_f32_e32 v40, 0x41800000, v40
	v_mul_f32_e32 v41, 0x41800000, v41
	v_fma_f32 v43, v101, v53, -v136
	v_fma_f32 v38, v101, v28, -v38
	v_add_f32_e32 v45, v173, v53
	v_add_f32_e32 v28, v174, v28
	v_mov_b32_e32 v75, 0
	v_add_f32_e32 v30, v166, v30
	global_store_dword v[22:23], v65, off offset:1024
	global_store_dword v[22:23], v66, off offset:3072
	v_cvt_pk_fp8_f32 v74, v8, v9
	v_med3_f32 v8, v31, s21, v62
	v_med3_f32 v9, v40, s21, v62
	v_med3_f32 v23, v41, s21, v62
	v_mul_f32_e32 v31, 0x41800000, v43
	v_mul_f32_e32 v38, 0x41800000, v38
	v_fma_f32 v41, v104, v45, -v138
	v_fma_f32 v36, v104, v28, -v36
	v_add_f32_e32 v28, v143, v28
	v_add_f32_e32 v32, v32, v45
	v_mov_b32_e32 v76, 0
	v_fma_f32 v56, v97, v30, -v133
	v_add_f32_e32 v30, v169, v30
	v_cvt_pk_fp8_f32 v75, v8, v9
	v_med3_f32 v8, v31, s21, v62
	v_med3_f32 v9, v38, s21, v62
	v_mul_f32_e32 v38, 0x41800000, v41
	v_mul_f32_e32 v36, 0x41800000, v36
	v_fma_f32 v32, v102, v32, -v140
	v_fma_f32 v28, v102, v28, -v34
	v_mov_b32_e32 v77, 0
	v_mul_f32_e32 v44, 0x41800000, v56
	v_fma_f32 v52, v98, v30, -v135
	v_add_f32_e32 v30, v172, v30
	v_add_f32_e32 v29, v119, v29
	v_cvt_pk_fp8_f32 v76, v8, v9
	v_med3_f32 v8, v38, s21, v62
	v_med3_f32 v9, v36, s21, v62
	v_mul_f32_e32 v32, 0x41800000, v32
	v_mul_f32_e32 v28, 0x41800000, v28
	v_mov_b32_e32 v78, 0
	v_mul_f32_e32 v51, 0x41800000, v51
	v_mul_f32_e32 v49, 0x41800000, v49
	v_mul_f32_e32 v47, 0x41800000, v47
	v_med3_f32 v26, v44, s21, v62
	v_mul_f32_e32 v42, 0x41800000, v52
	v_fma_f32 v44, v101, v30, -v137
	v_fma_f32 v39, v101, v29, -v39
	v_add_f32_e32 v30, v175, v30
	v_add_f32_e32 v29, v121, v29
	v_cvt_pk_fp8_f32 v77, v8, v9
	v_med3_f32 v8, v32, s21, v62
	v_med3_f32 v9, v28, s21, v62
	v_med3_f32 v51, v51, s21, v62
	v_med3_f32 v49, v49, s21, v62
	v_med3_f32 v47, v47, s21, v62
	v_med3_f32 v22, v42, s21, v62
	v_mul_f32_e32 v40, 0x41800000, v44
	v_mul_f32_e32 v39, 0x41800000, v39
	v_fma_f32 v42, v104, v30, -v139
	v_fma_f32 v37, v104, v29, -v37
	v_add_f32_e32 v29, v142, v29
	v_add_f32_e32 v30, v33, v30
	v_cvt_pk_fp8_f32 v78, v8, v9
	v_cvt_pk_fp8_f32 v70, v50, v51 op_sel:[0,0,1]
	v_cvt_pk_fp8_f32 v71, v48, v49 op_sel:[0,0,1]
	v_med3_f32 v31, v40, s21, v62
	v_med3_f32 v33, v39, s21, v62
	v_mul_f32_e32 v39, 0x41800000, v42
	v_mul_f32_e32 v37, 0x41800000, v37
	v_fma_f32 v30, v102, v30, -v141
	v_fma_f32 v29, v102, v29, -v35
	v_cvt_pk_fp8_f32 v72, v46, v47 op_sel:[0,0,1]
	v_cvt_pk_fp8_f32 v73, v24, v25 op_sel:[0,0,1]
	v_cvt_pk_fp8_f32 v74, v26, v27 op_sel:[0,0,1]
	v_cvt_pk_fp8_f32 v75, v22, v23 op_sel:[0,0,1]
	global_store_dword v[20:21], v67, off offset:1024
	global_store_dword v[20:21], v68, off offset:3072
	v_med3_f32 v20, v39, s21, v62
	v_med3_f32 v21, v37, s21, v62
	v_mul_f32_e32 v30, 0x41800000, v30
	v_mul_f32_e32 v29, 0x41800000, v29
	v_cvt_pk_fp8_f32 v76, v31, v33 op_sel:[0,0,1]
	s_add_i32 s14, s14, 16
	v_med3_f32 v24, v30, s21, v62
	v_med3_f32 v25, v29, s21, v62
	v_cvt_pk_fp8_f32 v77, v20, v21 op_sel:[0,0,1]
	v_lshl_add_u64 v[6:7], v[6:7], 0, s[10:11]
	v_lshl_add_u64 v[4:5], v[4:5], 0, s[12:13]
	s_cmp_eq_u32 s14, 64
	v_cvt_pk_fp8_f32 v78, v24, v25 op_sel:[0,0,1]
	global_store_dword v[18:19], v69, off offset:1024
	global_store_dword v[18:19], v70, off offset:3072
	global_store_dword v[16:17], v71, off offset:1024
	global_store_dword v[16:17], v72, off offset:3072
	global_store_dword v[14:15], v73, off offset:1024
	global_store_dword v[14:15], v74, off offset:3072
	global_store_dword v[10:11], v75, off offset:1024
	global_store_dword v[10:11], v76, off offset:3072
	global_store_dword v[12:13], v77, off offset:1024
	global_store_dword v[12:13], v78, off offset:3072
	s_cbranch_scc0 .LBB0_509
	s_branch .LBB0_492
